# LDS read rebalance: B0 fragment reads hoisted from L1 to previous L4, vmcnt(8) added in L3
# speedup vs baseline: 1.0063x; 1.0063x over previous
; #define PG8_STAGE(bufoff, gbase, voff) do { const __amdgpu_buffer_rsrc_t _r = __builtin_amdgcn_make_buffer_rsrc((void*)(gbase), (short)0, 0x7fffffff, 0x00020000); _Pragma("unroll") for (int _i = 0; _i < 2; ++_i) \
;         __builtin_amdgcn_raw_ptr_buffer_load_lds(_r, (LAS unsigned*)(lds + (bufoff) + ldsw + _i * 8192), 16, (int)(voff)[_i], 0, 0, 0); } while (0)
; #define PG8_LDA(dst, b, h) do { _Pragma("unroll") for (int m = 0; m < 4; ++m) _Pragma("unroll") for (int k = 0; k < 2; ++k) dst[m][k] = *(const LAS bf16x8*)(lds + PG8_SA(b, h) + aoff + m * 2048 + k * 1024); } while (0)
; #define PG8_LDB(dst, b, h) do { _Pragma("unroll") for (int n = 0; n < 2; ++n) _Pragma("unroll") for (int k = 0; k < 2; ++k) dst[n][k] = *(const LAS bf16x8*)(lds + PG8_SB(b, h) + boff + n * 2048 + k * 1024); } while (0)
; #define PG8_MMA(ai, bj, At, Bt) do { __builtin_amdgcn_s_setprio(1); _Pragma("unroll") for (int k = 0; k < 2; ++k) _Pragma("unroll") for (int m = 0; m < 4; ++m) _Pragma("unroll") for (int n = 0; n < ((bj) == 1 ? NB1 : 2); ++n) \
;         acc[ai][bj][m][n] = __builtin_amdgcn_mfma_f32_16x16x32_bf16(Bt[n][k], At[m][k], acc[ai][bj][m][n], 0, 0, 0); __builtin_amdgcn_s_setprio(0); } while (0)
; #define PG8_WAIT_V(n) asm volatile("s_waitcnt vmcnt(" #n ")" ::: "memory")
; #define PG8_WAIT_L(n) asm volatile("s_waitcnt lgkmcnt(" #n ")" ::: "memory")
; #define PG8_BAR __builtin_amdgcn_s_barrier()
;     ...
;         for (int t = 0; t < nt; t += 2) {
;             const bool last = (t == nt - 2);
;             const char* a1 = cA + (size_t)(t + 1) * kstep;
;             const char* a2 = last ? nA : cA + (size_t)(t + 2) * kstep; const char* b2 = last ? nB : cB + (size_t)(t + 2) * kstep;
;             const char* a3 = a2 + kstep; const char* b3 = b2 + kstep;
;             PG8_LDB(B0, 0, 0); PG8_SCHED; PG8_LDA(At, 0, 0); PG8_STAGE(PG8_SA(1, 1), a1 + hstepA, voffA);
;             PG8_WAIT_L(8); PG8_BAR; PG8_WAIT_L(0); PG8_MMA(0, 0, At, B0); PG8_BAR; PG8_SCHED;
;             PG8_LDB(B1, 0, 1); PG8_STAGE(PG8_SB(0, 0), b2, voffB);
;             PG8_BAR; PG8_WAIT_L(0); PG8_MMA(0, 1, At, B1); PG8_BAR;
;             PG8_LDA(At, 0, 1); PG8_STAGE(PG8_SA(0, 0), a2, voffA);
;             PG8_BAR; PG8_WAIT_L(0); PG8_MMA(1, 0, At, B0); PG8_BAR; PG8_SCHED;
;             PG8_STAGE(PG8_SB(0, 1), b2 + hstepB, voffB);
;             PG8_WAIT_V(6); PG8_BAR; PG8_MMA(1, 1, At, B1); PG8_BAR;
.Lkrot_575:
	s_add_i32 s16, s8, 2
	s_cmp_eq_u32 s90, s8
	s_cselect_b32 s36, s42, s45
	s_cselect_b32 s23, s43, s47
	s_cselect_b32 s22, s1, s81
	s_cselect_b32 s28, s0, s51
	s_add_u32 s24, s36, 0x80
	s_addc_u32 s17, s23, 0
	s_add_u32 s8, s45, s6
	s_addc_u32 s9, s47, s7
	s_add_u32 s8, s8, 0xffffff80
	s_addc_u32 s9, s9, -1
	s_and_b32 s9, s9, 0xffff
	s_mov_b32 m0, s76
	ds_read_b128 v[144:147], v216
	ds_read_b128 v[148:151], v216 offset:1024
	ds_read_b128 v[152:155], v216 offset:2048
	ds_read_b128 v[156:159], v216 offset:3072
	ds_read_b128 v[160:163], v216 offset:4096
	ds_read_b128 v[164:167], v216 offset:5120
	ds_read_b128 v[168:171], v216 offset:6144
	ds_read_b128 v[172:175], v216 offset:7168
	buffer_load_dwordx4 v210, s[8:11], 0 offen lds
	s_mov_b32 m0, s77
	s_nop 0
	buffer_load_dwordx4 v212, s[8:11], 0 offen lds
	s_waitcnt lgkmcnt(8)
	s_barrier
	s_waitcnt lgkmcnt(0)
	s_setprio 1
	s_waitcnt lgkmcnt(7)
	v_mfma_f32_16x16x32_bf16 v[132:135], v[96:99], v[144:147], v[132:135]
	v_mfma_f32_16x16x32_bf16 v[120:123], v[136:139], v[144:147], v[120:123]
	s_waitcnt lgkmcnt(5)
	v_mfma_f32_16x16x32_bf16 v[116:119], v[96:99], v[152:155], v[116:119]
	v_mfma_f32_16x16x32_bf16 v[112:115], v[136:139], v[152:155], v[112:115]
	s_waitcnt lgkmcnt(3)
	v_mfma_f32_16x16x32_bf16 v[92:95], v[96:99], v[160:163], v[92:95]
	v_mfma_f32_16x16x32_bf16 v[88:91], v[136:139], v[160:163], v[88:91]
	s_waitcnt lgkmcnt(1)
	v_mfma_f32_16x16x32_bf16 v[76:79], v[96:99], v[168:171], v[76:79]
	v_mfma_f32_16x16x32_bf16 v[72:75], v[136:139], v[168:171], v[72:75]
	v_mfma_f32_16x16x32_bf16 v[132:135], v[100:103], v[148:151], v[132:135]
	v_mfma_f32_16x16x32_bf16 v[120:123], v[140:143], v[148:151], v[120:123]
	v_mfma_f32_16x16x32_bf16 v[116:119], v[100:103], v[156:159], v[116:119]
	v_mfma_f32_16x16x32_bf16 v[112:115], v[140:143], v[156:159], v[112:115]
	v_mfma_f32_16x16x32_bf16 v[92:95], v[100:103], v[164:167], v[92:95]
	v_mfma_f32_16x16x32_bf16 v[88:91], v[140:143], v[164:167], v[88:91]
	s_waitcnt lgkmcnt(0)
	v_mfma_f32_16x16x32_bf16 v[76:79], v[100:103], v[172:175], v[76:79]
	v_mfma_f32_16x16x32_bf16 v[72:75], v[140:143], v[172:175], v[72:75]
	s_setprio 0
	s_barrier
	s_and_b32 s29, s22, 0xffff
	s_mov_b32 s30, s10
	s_mov_b32 s31, s11
	s_mov_b32 m0, s15
	ds_read_b128 v[176:179], v217
	ds_read_b128 v[194:197], v217 offset:1024
	ds_read_b128 v[198:201], v217 offset:2048
	ds_read_b128 v[202:205], v217 offset:3072
	buffer_load_dwordx4 v211, s[28:31], 0 offen lds
	s_mov_b32 m0, s33
	s_nop 0
	buffer_load_dwordx4 v213, s[28:31], 0 offen lds
	s_barrier
	s_waitcnt lgkmcnt(0)
	s_setprio 1
	s_waitcnt lgkmcnt(3)
	v_mfma_f32_16x16x32_bf16 v[128:131], v[176:179], v[144:147], v[128:131]
	s_waitcnt lgkmcnt(1)
	v_mfma_f32_16x16x32_bf16 v[124:127], v[198:201], v[144:147], v[124:127]
	v_mfma_f32_16x16x32_bf16 v[108:111], v[176:179], v[152:155], v[108:111]
	v_mfma_f32_16x16x32_bf16 v[104:107], v[198:201], v[152:155], v[104:107]
	v_mfma_f32_16x16x32_bf16 v[84:87], v[176:179], v[160:163], v[84:87]
	v_mfma_f32_16x16x32_bf16 v[80:83], v[198:201], v[160:163], v[80:83]
	v_mfma_f32_16x16x32_bf16 v[68:71], v[176:179], v[168:171], v[68:71]
	v_mfma_f32_16x16x32_bf16 v[64:67], v[198:201], v[168:171], v[64:67]
	v_mfma_f32_16x16x32_bf16 v[128:131], v[194:197], v[148:151], v[128:131]
	s_waitcnt lgkmcnt(0)
	v_mfma_f32_16x16x32_bf16 v[124:127], v[202:205], v[148:151], v[124:127]
	v_mfma_f32_16x16x32_bf16 v[108:111], v[194:197], v[156:159], v[108:111]
	v_mfma_f32_16x16x32_bf16 v[104:107], v[202:205], v[156:159], v[104:107]
	v_mfma_f32_16x16x32_bf16 v[84:87], v[194:197], v[164:167], v[84:87]
	v_mfma_f32_16x16x32_bf16 v[80:83], v[202:205], v[164:167], v[80:83]
	v_mfma_f32_16x16x32_bf16 v[68:71], v[194:197], v[172:175], v[68:71]
	v_mfma_f32_16x16x32_bf16 v[64:67], v[202:205], v[172:175], v[64:67]
	s_setprio 0
	s_and_b32 s37, s23, 0xffff
	s_mov_b32 s38, s10
	s_mov_b32 s39, s11
	s_mov_b32 m0, s14
	s_barrier
	ds_read_b128 v[144:147], v216 offset:16384
	ds_read_b128 v[148:151], v216 offset:17408
	ds_read_b128 v[152:155], v216 offset:18432
	ds_read_b128 v[156:159], v216 offset:19456
	ds_read_b128 v[160:163], v216 offset:20480
	ds_read_b128 v[164:167], v216 offset:21504
	ds_read_b128 v[168:171], v216 offset:22528
	ds_read_b128 v[172:175], v216 offset:23552
	buffer_load_dwordx4 v210, s[36:39], 0 offen lds
	s_mov_b32 m0, s35
	s_nop 0
	buffer_load_dwordx4 v212, s[36:39], 0 offen lds
	s_waitcnt vmcnt(8)
	s_barrier
	s_waitcnt lgkmcnt(0)
	s_setprio 1
	s_waitcnt lgkmcnt(7)
	v_mfma_f32_16x16x32_bf16 v[60:63], v[96:99], v[144:147], v[60:63]
	v_mfma_f32_16x16x32_bf16 v[56:59], v[136:139], v[144:147], v[56:59]
	s_waitcnt lgkmcnt(5)
	v_mfma_f32_16x16x32_bf16 v[44:47], v[96:99], v[152:155], v[44:47]
	v_mfma_f32_16x16x32_bf16 v[40:43], v[136:139], v[152:155], v[40:43]
	s_waitcnt lgkmcnt(3)
	v_mfma_f32_16x16x32_bf16 v[28:31], v[96:99], v[160:163], v[28:31]
	v_mfma_f32_16x16x32_bf16 v[24:27], v[136:139], v[160:163], v[24:27]
	s_waitcnt lgkmcnt(1)
	v_mfma_f32_16x16x32_bf16 v[12:15], v[96:99], v[168:171], v[12:15]
	v_mfma_f32_16x16x32_bf16 v[8:11], v[136:139], v[168:171], v[8:11]
	v_mfma_f32_16x16x32_bf16 v[60:63], v[100:103], v[148:151], v[60:63]
	v_mfma_f32_16x16x32_bf16 v[56:59], v[140:143], v[148:151], v[56:59]
	v_mfma_f32_16x16x32_bf16 v[44:47], v[100:103], v[156:159], v[44:47]
	v_mfma_f32_16x16x32_bf16 v[40:43], v[140:143], v[156:159], v[40:43]
	v_mfma_f32_16x16x32_bf16 v[28:31], v[100:103], v[164:167], v[28:31]
	v_mfma_f32_16x16x32_bf16 v[24:27], v[140:143], v[164:167], v[24:27]
	s_waitcnt lgkmcnt(0)
	v_mfma_f32_16x16x32_bf16 v[12:15], v[100:103], v[172:175], v[12:15]
	v_mfma_f32_16x16x32_bf16 v[8:11], v[140:143], v[172:175], v[8:11]
	s_setprio 0
	s_barrier
; #define PG8_STAGE(bufoff, gbase, voff) do { const __amdgpu_buffer_rsrc_t _r = __builtin_amdgcn_make_buffer_rsrc((void*)(gbase), (short)0, 0x7fffffff, 0x00020000); _Pragma("unroll") for (int _i = 0; _i < 2; ++_i) \
;         __builtin_amdgcn_raw_ptr_buffer_load_lds(_r, (LAS unsigned*)(lds + (bufoff) + ldsw + _i * 8192), 16, (int)(voff)[_i], 0, 0, 0); } while (0)
; #define PG8_LDA(dst, b, h) do { _Pragma("unroll") for (int m = 0; m < 4; ++m) _Pragma("unroll") for (int k = 0; k < 2; ++k) dst[m][k] = *(const LAS bf16x8*)(lds + PG8_SA(b, h) + aoff + m * 2048 + k * 1024); } while (0)
; #define PG8_LDB(dst, b, h) do { _Pragma("unroll") for (int n = 0; n < 2; ++n) _Pragma("unroll") for (int k = 0; k < 2; ++k) dst[n][k] = *(const LAS bf16x8*)(lds + PG8_SB(b, h) + boff + n * 2048 + k * 1024); } while (0)
; #define PG8_MMA(ai, bj, At, Bt) do { __builtin_amdgcn_s_setprio(1); _Pragma("unroll") for (int k = 0; k < 2; ++k) _Pragma("unroll") for (int m = 0; m < 4; ++m) _Pragma("unroll") for (int n = 0; n < ((bj) == 1 ? NB1 : 2); ++n) \
;         acc[ai][bj][m][n] = __builtin_amdgcn_mfma_f32_16x16x32_bf16(Bt[n][k], At[m][k], acc[ai][bj][m][n], 0, 0, 0); __builtin_amdgcn_s_setprio(0); } while (0)
; #define PG8_WAIT_V(n) asm volatile("s_waitcnt vmcnt(" #n ")" ::: "memory")
; #define PG8_WAIT_L(n) asm volatile("s_waitcnt lgkmcnt(" #n ")" ::: "memory")
; #define PG8_BAR __builtin_amdgcn_s_barrier()
; #define PG8_SCHED __builtin_amdgcn_sched_barrier(0)
;     ...
;             PG8_WAIT_V(6); PG8_BAR; PG8_MMA(1, 1, At, B1); PG8_BAR;
;             PG8_LDB(B0, 1, 0); PG8_SCHED; PG8_LDA(At, 1, 0); PG8_STAGE(PG8_SA(0, 1), a2 + hstepA, voffA);
;             PG8_WAIT_L(8); PG8_BAR; PG8_WAIT_L(0); PG8_MMA(0, 0, At, B0); PG8_BAR; PG8_SCHED;
;             PG8_LDB(B1, 1, 1); PG8_STAGE(PG8_SB(1, 0), b3, voffB);
;             PG8_BAR; PG8_WAIT_L(0); PG8_MMA(0, 1, At, B1); PG8_BAR;
	ds_read_b128 v[96:99], v218
	ds_read_b128 v[100:103], v218 offset:1024
	ds_read_b128 v[136:139], v218 offset:2048
	ds_read_b128 v[140:143], v218 offset:3072
	s_add_u32 s8, s28, s18
	s_addc_u32 s82, s22, s19
	s_and_b32 s9, s82, 0xffff
	s_mov_b32 m0, s52
	s_nop 0
	buffer_load_dwordx4 v211, s[8:11], 0 offen lds
	s_mov_b32 m0, s53
	s_nop 0
	buffer_load_dwordx4 v213, s[8:11], 0 offen lds
	s_waitcnt vmcnt(6)
	s_barrier
	s_setprio 1
	v_mfma_f32_16x16x32_bf16 v[52:55], v[176:179], v[144:147], v[52:55]
	v_mfma_f32_16x16x32_bf16 v[48:51], v[198:201], v[144:147], v[48:51]
	v_mfma_f32_16x16x32_bf16 v[36:39], v[176:179], v[152:155], v[36:39]
	v_mfma_f32_16x16x32_bf16 v[32:35], v[198:201], v[152:155], v[32:35]
	v_mfma_f32_16x16x32_bf16 v[20:23], v[176:179], v[160:163], v[20:23]
	v_mfma_f32_16x16x32_bf16 v[16:19], v[198:201], v[160:163], v[16:19]
	v_mfma_f32_16x16x32_bf16 v[4:7], v[176:179], v[168:171], v[4:7]
	v_mfma_f32_16x16x32_bf16 v[0:3], v[198:201], v[168:171], v[0:3]
	v_mfma_f32_16x16x32_bf16 v[52:55], v[194:197], v[148:151], v[52:55]
	v_mfma_f32_16x16x32_bf16 v[48:51], v[202:205], v[148:151], v[48:51]
	v_mfma_f32_16x16x32_bf16 v[36:39], v[194:197], v[156:159], v[36:39]
	v_mfma_f32_16x16x32_bf16 v[32:35], v[202:205], v[156:159], v[32:35]
	v_mfma_f32_16x16x32_bf16 v[20:23], v[194:197], v[164:167], v[20:23]
	v_mfma_f32_16x16x32_bf16 v[16:19], v[202:205], v[164:167], v[16:19]
	v_mfma_f32_16x16x32_bf16 v[4:7], v[194:197], v[172:175], v[4:7]
	v_mfma_f32_16x16x32_bf16 v[0:3], v[202:205], v[172:175], v[0:3]
	s_setprio 0
	s_barrier
	s_add_u32 s36, s36, s6
	s_addc_u32 s9, s23, s7
	s_and_b32 s37, s9, 0xffff
	s_mov_b32 m0, s58
	ds_read_b128 v[144:147], v216 offset:32768
	ds_read_b128 v[148:151], v216 offset:33792
	ds_read_b128 v[152:155], v216 offset:34816
	ds_read_b128 v[156:159], v216 offset:35840
	ds_read_b128 v[160:163], v216 offset:36864
	ds_read_b128 v[164:167], v216 offset:37888
	ds_read_b128 v[168:171], v216 offset:38912
	ds_read_b128 v[172:175], v216 offset:39936
	buffer_load_dwordx4 v210, s[36:39], 0 offen lds
	s_mov_b32 m0, s59
	s_nop 0
	buffer_load_dwordx4 v212, s[36:39], 0 offen lds
	s_waitcnt lgkmcnt(8)
	s_barrier
	s_waitcnt lgkmcnt(0)
	s_setprio 1
	s_waitcnt lgkmcnt(7)
	v_mfma_f32_16x16x32_bf16 v[132:135], v[96:99], v[144:147], v[132:135]
	v_mfma_f32_16x16x32_bf16 v[120:123], v[136:139], v[144:147], v[120:123]
	s_waitcnt lgkmcnt(5)
	v_mfma_f32_16x16x32_bf16 v[116:119], v[96:99], v[152:155], v[116:119]
	v_mfma_f32_16x16x32_bf16 v[112:115], v[136:139], v[152:155], v[112:115]
	s_waitcnt lgkmcnt(3)
	v_mfma_f32_16x16x32_bf16 v[92:95], v[96:99], v[160:163], v[92:95]
	v_mfma_f32_16x16x32_bf16 v[88:91], v[136:139], v[160:163], v[88:91]
	s_waitcnt lgkmcnt(1)
	v_mfma_f32_16x16x32_bf16 v[76:79], v[96:99], v[168:171], v[76:79]
	v_mfma_f32_16x16x32_bf16 v[72:75], v[136:139], v[168:171], v[72:75]
	v_mfma_f32_16x16x32_bf16 v[132:135], v[100:103], v[148:151], v[132:135]
	v_mfma_f32_16x16x32_bf16 v[120:123], v[140:143], v[148:151], v[120:123]
	v_mfma_f32_16x16x32_bf16 v[116:119], v[100:103], v[156:159], v[116:119]
	v_mfma_f32_16x16x32_bf16 v[112:115], v[140:143], v[156:159], v[112:115]
	v_mfma_f32_16x16x32_bf16 v[92:95], v[100:103], v[164:167], v[92:95]
	v_mfma_f32_16x16x32_bf16 v[88:91], v[140:143], v[164:167], v[88:91]
	s_waitcnt lgkmcnt(0)
	v_mfma_f32_16x16x32_bf16 v[76:79], v[100:103], v[172:175], v[76:79]
	v_mfma_f32_16x16x32_bf16 v[72:75], v[140:143], v[172:175], v[72:75]
	s_setprio 0
	s_barrier
	s_add_u32 s28, s28, 0x80
	s_addc_u32 s9, s22, 0
	s_and_b32 s29, s9, 0xffff
	s_mov_b32 m0, s48
	ds_read_b128 v[176:179], v219
	ds_read_b128 v[194:197], v219 offset:1024
	ds_read_b128 v[198:201], v219 offset:2048
	ds_read_b128 v[202:205], v219 offset:3072
	buffer_load_dwordx4 v211, s[28:31], 0 offen lds
	s_mov_b32 m0, s49
	s_nop 0
	buffer_load_dwordx4 v213, s[28:31], 0 offen lds
	s_barrier
; #define PG8_STAGE(bufoff, gbase, voff) do { const __amdgpu_buffer_rsrc_t _r = __builtin_amdgcn_make_buffer_rsrc((void*)(gbase), (short)0, 0x7fffffff, 0x00020000); _Pragma("unroll") for (int _i = 0; _i < 2; ++_i) \
;         __builtin_amdgcn_raw_ptr_buffer_load_lds(_r, (LAS unsigned*)(lds + (bufoff) + ldsw + _i * 8192), 16, (int)(voff)[_i], 0, 0, 0); } while (0)
; #define PG8_LDA(dst, b, h) do { _Pragma("unroll") for (int m = 0; m < 4; ++m) _Pragma("unroll") for (int k = 0; k < 2; ++k) dst[m][k] = *(const LAS bf16x8*)(lds + PG8_SA(b, h) + aoff + m * 2048 + k * 1024); } while (0)
; #define PG8_MMA(ai, bj, At, Bt) do { __builtin_amdgcn_s_setprio(1); _Pragma("unroll") for (int k = 0; k < 2; ++k) _Pragma("unroll") for (int m = 0; m < 4; ++m) _Pragma("unroll") for (int n = 0; n < ((bj) == 1 ? NB1 : 2); ++n) \
;         acc[ai][bj][m][n] = __builtin_amdgcn_mfma_f32_16x16x32_bf16(Bt[n][k], At[m][k], acc[ai][bj][m][n], 0, 0, 0); __builtin_amdgcn_s_setprio(0); } while (0)
; #define PG8_WAIT_V(n) asm volatile("s_waitcnt vmcnt(" #n ")" ::: "memory")
; #define PG8_WAIT_L(n) asm volatile("s_waitcnt lgkmcnt(" #n ")" ::: "memory")
; #define PG8_BAR __builtin_amdgcn_s_barrier()
; #define PG8_SCHED __builtin_amdgcn_sched_barrier(0)
;     ...
;             PG8_BAR; PG8_WAIT_L(0); PG8_MMA(0, 1, At, B1); PG8_BAR;
;             PG8_LDA(At, 1, 1); PG8_STAGE(PG8_SA(1, 0), a3, voffA);
;             PG8_BAR; PG8_WAIT_L(0); PG8_MMA(1, 0, At, B0); PG8_BAR; PG8_SCHED;
;             PG8_STAGE(PG8_SB(1, 1), b3 + hstepB, voffB);
;             PG8_WAIT_V(6); PG8_BAR; PG8_MMA(1, 1, At, B1); PG8_BAR;
;         }
	s_waitcnt lgkmcnt(0)
	s_setprio 1
	s_waitcnt lgkmcnt(3)
	v_mfma_f32_16x16x32_bf16 v[128:131], v[176:179], v[144:147], v[128:131]
	s_waitcnt lgkmcnt(1)
	v_mfma_f32_16x16x32_bf16 v[124:127], v[198:201], v[144:147], v[124:127]
	v_mfma_f32_16x16x32_bf16 v[108:111], v[176:179], v[152:155], v[108:111]
	v_mfma_f32_16x16x32_bf16 v[104:107], v[198:201], v[152:155], v[104:107]
	v_mfma_f32_16x16x32_bf16 v[84:87], v[176:179], v[160:163], v[84:87]
	v_mfma_f32_16x16x32_bf16 v[80:83], v[198:201], v[160:163], v[80:83]
	v_mfma_f32_16x16x32_bf16 v[68:71], v[176:179], v[168:171], v[68:71]
	v_mfma_f32_16x16x32_bf16 v[64:67], v[198:201], v[168:171], v[64:67]
	v_mfma_f32_16x16x32_bf16 v[128:131], v[194:197], v[148:151], v[128:131]
	s_waitcnt lgkmcnt(0)
	v_mfma_f32_16x16x32_bf16 v[124:127], v[202:205], v[148:151], v[124:127]
	v_mfma_f32_16x16x32_bf16 v[108:111], v[194:197], v[156:159], v[108:111]
	v_mfma_f32_16x16x32_bf16 v[104:107], v[202:205], v[156:159], v[104:107]
	v_mfma_f32_16x16x32_bf16 v[84:87], v[194:197], v[164:167], v[84:87]
	v_mfma_f32_16x16x32_bf16 v[80:83], v[202:205], v[164:167], v[80:83]
	v_mfma_f32_16x16x32_bf16 v[68:71], v[194:197], v[172:175], v[68:71]
	v_mfma_f32_16x16x32_bf16 v[64:67], v[202:205], v[172:175], v[64:67]
	s_setprio 0
	s_and_b32 s25, s17, 0xffff
	s_mov_b32 s26, s10
	s_mov_b32 s27, s11
	s_mov_b32 m0, s83
	s_barrier
	ds_read_b128 v[144:147], v216 offset:49152
	ds_read_b128 v[148:151], v216 offset:50176
	ds_read_b128 v[152:155], v216 offset:51200
	ds_read_b128 v[156:159], v216 offset:52224
	ds_read_b128 v[160:163], v216 offset:53248
	ds_read_b128 v[164:167], v216 offset:54272
	ds_read_b128 v[168:171], v216 offset:55296
	ds_read_b128 v[172:175], v216 offset:56320
	buffer_load_dwordx4 v210, s[24:27], 0 offen lds
	s_mov_b32 m0, s84
	s_nop 0
	buffer_load_dwordx4 v212, s[24:27], 0 offen lds
	s_waitcnt vmcnt(8)
	s_barrier
	s_waitcnt lgkmcnt(0)
	s_setprio 1
	s_waitcnt lgkmcnt(7)
	v_mfma_f32_16x16x32_bf16 v[60:63], v[96:99], v[144:147], v[60:63]
	v_mfma_f32_16x16x32_bf16 v[56:59], v[136:139], v[144:147], v[56:59]
	s_waitcnt lgkmcnt(5)
	v_mfma_f32_16x16x32_bf16 v[44:47], v[96:99], v[152:155], v[44:47]
	v_mfma_f32_16x16x32_bf16 v[40:43], v[136:139], v[152:155], v[40:43]
	s_waitcnt lgkmcnt(3)
	v_mfma_f32_16x16x32_bf16 v[28:31], v[96:99], v[160:163], v[28:31]
	v_mfma_f32_16x16x32_bf16 v[24:27], v[136:139], v[160:163], v[24:27]
	s_waitcnt lgkmcnt(1)
	v_mfma_f32_16x16x32_bf16 v[12:15], v[96:99], v[168:171], v[12:15]
	v_mfma_f32_16x16x32_bf16 v[8:11], v[136:139], v[168:171], v[8:11]
	v_mfma_f32_16x16x32_bf16 v[60:63], v[100:103], v[148:151], v[60:63]
	v_mfma_f32_16x16x32_bf16 v[56:59], v[140:143], v[148:151], v[56:59]
	v_mfma_f32_16x16x32_bf16 v[44:47], v[100:103], v[156:159], v[44:47]
	v_mfma_f32_16x16x32_bf16 v[40:43], v[140:143], v[156:159], v[40:43]
	v_mfma_f32_16x16x32_bf16 v[28:31], v[100:103], v[164:167], v[28:31]
	v_mfma_f32_16x16x32_bf16 v[24:27], v[140:143], v[164:167], v[24:27]
	s_waitcnt lgkmcnt(0)
	v_mfma_f32_16x16x32_bf16 v[12:15], v[100:103], v[172:175], v[12:15]
	v_mfma_f32_16x16x32_bf16 v[8:11], v[140:143], v[172:175], v[8:11]
	s_setprio 0
	s_barrier
	ds_read_b128 v[96:99], v215
	ds_read_b128 v[100:103], v215 offset:1024
	ds_read_b128 v[136:139], v215 offset:2048
	ds_read_b128 v[140:143], v215 offset:3072
	s_add_u32 s8, s8, 0x80
	s_addc_u32 s9, s82, 0
	s_and_b32 s9, s9, 0xffff
	s_mov_b32 m0, s85
	s_nop 0
	buffer_load_dwordx4 v211, s[8:11], 0 offen lds
	s_mov_b32 m0, s86
	s_nop 0
	buffer_load_dwordx4 v213, s[8:11], 0 offen lds
	s_waitcnt vmcnt(6)
	s_barrier
	s_setprio 1
	v_mfma_f32_16x16x32_bf16 v[52:55], v[176:179], v[144:147], v[52:55]
	v_mfma_f32_16x16x32_bf16 v[48:51], v[198:201], v[144:147], v[48:51]
	v_mfma_f32_16x16x32_bf16 v[36:39], v[176:179], v[152:155], v[36:39]
	v_mfma_f32_16x16x32_bf16 v[32:35], v[198:201], v[152:155], v[32:35]
	v_mfma_f32_16x16x32_bf16 v[20:23], v[176:179], v[160:163], v[20:23]
	v_mfma_f32_16x16x32_bf16 v[16:19], v[198:201], v[160:163], v[16:19]
	v_mfma_f32_16x16x32_bf16 v[4:7], v[176:179], v[168:171], v[4:7]
	v_mfma_f32_16x16x32_bf16 v[0:3], v[198:201], v[168:171], v[0:3]
	v_mfma_f32_16x16x32_bf16 v[52:55], v[194:197], v[148:151], v[52:55]
	v_mfma_f32_16x16x32_bf16 v[48:51], v[202:205], v[148:151], v[48:51]
	v_mfma_f32_16x16x32_bf16 v[36:39], v[194:197], v[156:159], v[36:39]
	v_mfma_f32_16x16x32_bf16 v[32:35], v[202:205], v[156:159], v[32:35]
	v_mfma_f32_16x16x32_bf16 v[20:23], v[194:197], v[164:167], v[20:23]
	v_mfma_f32_16x16x32_bf16 v[16:19], v[202:205], v[164:167], v[16:19]
	v_mfma_f32_16x16x32_bf16 v[4:7], v[194:197], v[172:175], v[4:7]
	v_mfma_f32_16x16x32_bf16 v[0:3], v[202:205], v[172:175], v[0:3]
	s_setprio 0
	s_add_u32 s45, s45, 0x100
	s_addc_u32 s47, s47, 0
	s_add_u32 s51, s51, 0x100
	s_addc_u32 s81, s81, 0
	s_cmp_ge_i32 s16, s89
	s_mov_b32 s8, s16
	s_barrier
	s_cbranch_scc0 .Lkrot_575
	s_waitcnt lgkmcnt(0)
	s_branch .LBB0_568

; #define PG8_STAGE(bufoff, gbase, voff) do { const __amdgpu_buffer_rsrc_t _r = __builtin_amdgcn_make_buffer_rsrc((void*)(gbase), (short)0, 0x7fffffff, 0x00020000); _Pragma("unroll") for (int _i = 0; _i < 2; ++_i) \
;         __builtin_amdgcn_raw_ptr_buffer_load_lds(_r, (LAS unsigned*)(lds + (bufoff) + ldsw + _i * 8192), 16, (int)(voff)[_i], 0, 0, 0); } while (0)
; #define PG8_LDA(dst, b, h) do { _Pragma("unroll") for (int m = 0; m < 4; ++m) _Pragma("unroll") for (int k = 0; k < 2; ++k) dst[m][k] = *(const LAS bf16x8*)(lds + PG8_SA(b, h) + aoff + m * 2048 + k * 1024); } while (0)
; #define PG8_LDB(dst, b, h) do { _Pragma("unroll") for (int n = 0; n < 2; ++n) _Pragma("unroll") for (int k = 0; k < 2; ++k) dst[n][k] = *(const LAS bf16x8*)(lds + PG8_SB(b, h) + boff + n * 2048 + k * 1024); } while (0)
; #define PG8_MMA(ai, bj, At, Bt) do { __builtin_amdgcn_s_setprio(1); _Pragma("unroll") for (int k = 0; k < 2; ++k) _Pragma("unroll") for (int m = 0; m < 4; ++m) _Pragma("unroll") for (int n = 0; n < ((bj) == 1 ? NB1 : 2); ++n) \
;         acc[ai][bj][m][n] = __builtin_amdgcn_mfma_f32_16x16x32_bf16(Bt[n][k], At[m][k], acc[ai][bj][m][n], 0, 0, 0); __builtin_amdgcn_s_setprio(0); } while (0)
; #define PG8_WAIT_V(n) asm volatile("s_waitcnt vmcnt(" #n ")" ::: "memory")
; #define PG8_WAIT_L(n) asm volatile("s_waitcnt lgkmcnt(" #n ")" ::: "memory")
; #define PG8_BAR __builtin_amdgcn_s_barrier()
;     ...
;         for (int t = 0; t < nt; t += 2) {
;             const bool last = (t == nt - 2);
;             const char* a1 = cA + (size_t)(t + 1) * kstep;
;             const char* a2 = last ? nA : cA + (size_t)(t + 2) * kstep; const char* b2 = last ? nB : cB + (size_t)(t + 2) * kstep;
;             const char* a3 = a2 + kstep; const char* b3 = b2 + kstep;
;             PG8_LDB(B0, 0, 0); PG8_SCHED; PG8_LDA(At, 0, 0); PG8_STAGE(PG8_SA(1, 1), a1 + hstepA, voffA);
;             PG8_WAIT_L(8); PG8_BAR; PG8_WAIT_L(0); PG8_MMA(0, 0, At, B0); PG8_BAR; PG8_SCHED;
;             PG8_LDB(B1, 0, 1); PG8_STAGE(PG8_SB(0, 0), b2, voffB);
;             PG8_BAR; PG8_WAIT_L(0); PG8_MMA(0, 1, At, B1); PG8_BAR;
;             PG8_LDA(At, 0, 1); PG8_STAGE(PG8_SA(0, 0), a2, voffA);
;             PG8_BAR; PG8_WAIT_L(0); PG8_MMA(1, 0, At, B0); PG8_BAR; PG8_SCHED;
;             PG8_STAGE(PG8_SB(0, 1), b2 + hstepB, voffB);
;             PG8_WAIT_V(6); PG8_BAR; PG8_MMA(1, 1, At, B1); PG8_BAR;
.Lkrot_627:
	s_add_i32 s16, s8, 2
	s_cmp_eq_u32 s82, s8
	s_cselect_b32 s36, s1, s89
	s_cselect_b32 s23, s0, s90
	s_cselect_b32 s22, s47, s92
	s_cselect_b32 s28, s51, s91
	s_add_u32 s24, s36, 0x80
	s_addc_u32 s17, s23, 0
	s_add_u32 s8, s89, s18
	s_addc_u32 s9, s90, s19
	s_add_u32 s8, s8, 0xffffff80
	s_addc_u32 s9, s9, -1
	s_and_b32 s9, s9, 0xffff
	s_mov_b32 m0, s83
	ds_read_b128 v[144:147], v213
	ds_read_b128 v[148:151], v213 offset:1024
	ds_read_b128 v[152:155], v213 offset:2048
	ds_read_b128 v[156:159], v213 offset:3072
	ds_read_b128 v[160:163], v213 offset:4096
	ds_read_b128 v[164:167], v213 offset:5120
	ds_read_b128 v[168:171], v213 offset:6144
	ds_read_b128 v[172:175], v213 offset:7168
	buffer_load_dwordx4 v206, s[8:11], 0 offen lds
	s_mov_b32 m0, s84
	s_nop 0
	buffer_load_dwordx4 v208, s[8:11], 0 offen lds
	s_waitcnt lgkmcnt(8)
	s_barrier
	s_waitcnt lgkmcnt(0)
	s_setprio 1
	s_waitcnt lgkmcnt(7)
	v_mfma_f32_16x16x32_bf16 v[112:115], v[128:131], v[144:147], v[112:115]
	v_mfma_f32_16x16x32_bf16 v[116:119], v[136:139], v[144:147], v[116:119]
	s_waitcnt lgkmcnt(5)
	v_mfma_f32_16x16x32_bf16 v[100:103], v[128:131], v[152:155], v[100:103]
	v_mfma_f32_16x16x32_bf16 v[96:99], v[136:139], v[152:155], v[96:99]
	s_waitcnt lgkmcnt(3)
	v_mfma_f32_16x16x32_bf16 v[84:87], v[128:131], v[160:163], v[84:87]
	v_mfma_f32_16x16x32_bf16 v[80:83], v[136:139], v[160:163], v[80:83]
	s_waitcnt lgkmcnt(1)
	v_mfma_f32_16x16x32_bf16 v[68:71], v[128:131], v[168:171], v[68:71]
	v_mfma_f32_16x16x32_bf16 v[64:67], v[136:139], v[168:171], v[64:67]
	v_mfma_f32_16x16x32_bf16 v[112:115], v[132:135], v[148:151], v[112:115]
	v_mfma_f32_16x16x32_bf16 v[116:119], v[140:143], v[148:151], v[116:119]
	v_mfma_f32_16x16x32_bf16 v[100:103], v[132:135], v[156:159], v[100:103]
	v_mfma_f32_16x16x32_bf16 v[96:99], v[140:143], v[156:159], v[96:99]
	v_mfma_f32_16x16x32_bf16 v[84:87], v[132:135], v[164:167], v[84:87]
	v_mfma_f32_16x16x32_bf16 v[80:83], v[140:143], v[164:167], v[80:83]
	s_waitcnt lgkmcnt(0)
	v_mfma_f32_16x16x32_bf16 v[68:71], v[132:135], v[172:175], v[68:71]
	v_mfma_f32_16x16x32_bf16 v[64:67], v[140:143], v[172:175], v[64:67]
	s_setprio 0
	s_barrier
	s_and_b32 s29, s22, 0xffff
	s_mov_b32 s30, s10
	s_mov_b32 s31, s11
	s_mov_b32 m0, s15
	ds_read_b128 v[176:179], v214
	ds_read_b128 v[180:183], v214 offset:1024
	ds_read_b128 v[188:191], v214 offset:2048
	ds_read_b128 v[192:195], v214 offset:3072
	buffer_load_dwordx4 v207, s[28:31], 0 offen lds
	s_mov_b32 m0, s33
	s_nop 0
	buffer_load_dwordx4 v209, s[28:31], 0 offen lds
	s_barrier
	s_waitcnt lgkmcnt(0)
	s_setprio 1
	s_waitcnt lgkmcnt(3)
	v_mfma_f32_16x16x32_bf16 v[124:127], v[176:179], v[144:147], v[124:127]
	s_waitcnt lgkmcnt(1)
	v_mfma_f32_16x16x32_bf16 v[120:123], v[188:191], v[144:147], v[120:123]
	v_mfma_f32_16x16x32_bf16 v[108:111], v[176:179], v[152:155], v[108:111]
	v_mfma_f32_16x16x32_bf16 v[104:107], v[188:191], v[152:155], v[104:107]
	v_mfma_f32_16x16x32_bf16 v[92:95], v[176:179], v[160:163], v[92:95]
	v_mfma_f32_16x16x32_bf16 v[88:91], v[188:191], v[160:163], v[88:91]
	v_mfma_f32_16x16x32_bf16 v[76:79], v[176:179], v[168:171], v[76:79]
	v_mfma_f32_16x16x32_bf16 v[72:75], v[188:191], v[168:171], v[72:75]
	v_mfma_f32_16x16x32_bf16 v[124:127], v[180:183], v[148:151], v[124:127]
	s_waitcnt lgkmcnt(0)
	v_mfma_f32_16x16x32_bf16 v[120:123], v[192:195], v[148:151], v[120:123]
	v_mfma_f32_16x16x32_bf16 v[108:111], v[180:183], v[156:159], v[108:111]
	v_mfma_f32_16x16x32_bf16 v[104:107], v[192:195], v[156:159], v[104:107]
	v_mfma_f32_16x16x32_bf16 v[92:95], v[180:183], v[164:167], v[92:95]
	v_mfma_f32_16x16x32_bf16 v[88:91], v[192:195], v[164:167], v[88:91]
	v_mfma_f32_16x16x32_bf16 v[76:79], v[180:183], v[172:175], v[76:79]
	v_mfma_f32_16x16x32_bf16 v[72:75], v[192:195], v[172:175], v[72:75]
	s_setprio 0
	s_and_b32 s37, s23, 0xffff
	s_mov_b32 s38, s10
	s_mov_b32 s39, s11
	s_mov_b32 m0, s14
	s_barrier
	ds_read_b128 v[144:147], v213 offset:16384
	ds_read_b128 v[148:151], v213 offset:17408
	ds_read_b128 v[152:155], v213 offset:18432
	ds_read_b128 v[156:159], v213 offset:19456
	ds_read_b128 v[160:163], v213 offset:20480
	ds_read_b128 v[164:167], v213 offset:21504
	ds_read_b128 v[168:171], v213 offset:22528
	ds_read_b128 v[172:175], v213 offset:23552
	buffer_load_dwordx4 v206, s[36:39], 0 offen lds
	s_mov_b32 m0, s35
	s_nop 0
	buffer_load_dwordx4 v208, s[36:39], 0 offen lds
	s_waitcnt vmcnt(8)
	s_barrier
	s_waitcnt lgkmcnt(0)
	s_setprio 1
	s_waitcnt lgkmcnt(7)
	v_mfma_f32_16x16x32_bf16 v[52:55], v[128:131], v[144:147], v[52:55]
	v_mfma_f32_16x16x32_bf16 v[48:51], v[136:139], v[144:147], v[48:51]
	s_waitcnt lgkmcnt(5)
	v_mfma_f32_16x16x32_bf16 v[36:39], v[128:131], v[152:155], v[36:39]
	v_mfma_f32_16x16x32_bf16 v[32:35], v[136:139], v[152:155], v[32:35]
	s_waitcnt lgkmcnt(3)
	v_mfma_f32_16x16x32_bf16 v[20:23], v[128:131], v[160:163], v[20:23]
	v_mfma_f32_16x16x32_bf16 v[16:19], v[136:139], v[160:163], v[16:19]
	s_waitcnt lgkmcnt(1)
	v_mfma_f32_16x16x32_bf16 v[4:7], v[128:131], v[168:171], v[4:7]
	v_mfma_f32_16x16x32_bf16 v[0:3], v[136:139], v[168:171], v[0:3]
	v_mfma_f32_16x16x32_bf16 v[52:55], v[132:135], v[148:151], v[52:55]
	v_mfma_f32_16x16x32_bf16 v[48:51], v[140:143], v[148:151], v[48:51]
	v_mfma_f32_16x16x32_bf16 v[36:39], v[132:135], v[156:159], v[36:39]
	v_mfma_f32_16x16x32_bf16 v[32:35], v[140:143], v[156:159], v[32:35]
	v_mfma_f32_16x16x32_bf16 v[20:23], v[132:135], v[164:167], v[20:23]
	v_mfma_f32_16x16x32_bf16 v[16:19], v[140:143], v[164:167], v[16:19]
	s_waitcnt lgkmcnt(0)
	v_mfma_f32_16x16x32_bf16 v[4:7], v[132:135], v[172:175], v[4:7]
	v_mfma_f32_16x16x32_bf16 v[0:3], v[140:143], v[172:175], v[0:3]
	s_setprio 0
	s_barrier
; #define PG8_STAGE(bufoff, gbase, voff) do { const __amdgpu_buffer_rsrc_t _r = __builtin_amdgcn_make_buffer_rsrc((void*)(gbase), (short)0, 0x7fffffff, 0x00020000); _Pragma("unroll") for (int _i = 0; _i < 2; ++_i) \
;         __builtin_amdgcn_raw_ptr_buffer_load_lds(_r, (LAS unsigned*)(lds + (bufoff) + ldsw + _i * 8192), 16, (int)(voff)[_i], 0, 0, 0); } while (0)
; #define PG8_LDA(dst, b, h) do { _Pragma("unroll") for (int m = 0; m < 4; ++m) _Pragma("unroll") for (int k = 0; k < 2; ++k) dst[m][k] = *(const LAS bf16x8*)(lds + PG8_SA(b, h) + aoff + m * 2048 + k * 1024); } while (0)
; #define PG8_LDB(dst, b, h) do { _Pragma("unroll") for (int n = 0; n < 2; ++n) _Pragma("unroll") for (int k = 0; k < 2; ++k) dst[n][k] = *(const LAS bf16x8*)(lds + PG8_SB(b, h) + boff + n * 2048 + k * 1024); } while (0)
; #define PG8_MMA(ai, bj, At, Bt) do { __builtin_amdgcn_s_setprio(1); _Pragma("unroll") for (int k = 0; k < 2; ++k) _Pragma("unroll") for (int m = 0; m < 4; ++m) _Pragma("unroll") for (int n = 0; n < ((bj) == 1 ? NB1 : 2); ++n) \
;         acc[ai][bj][m][n] = __builtin_amdgcn_mfma_f32_16x16x32_bf16(Bt[n][k], At[m][k], acc[ai][bj][m][n], 0, 0, 0); __builtin_amdgcn_s_setprio(0); } while (0)
; #define PG8_WAIT_V(n) asm volatile("s_waitcnt vmcnt(" #n ")" ::: "memory")
; #define PG8_WAIT_L(n) asm volatile("s_waitcnt lgkmcnt(" #n ")" ::: "memory")
; #define PG8_BAR __builtin_amdgcn_s_barrier()
; #define PG8_SCHED __builtin_amdgcn_sched_barrier(0)
;     ...
;             PG8_WAIT_V(6); PG8_BAR; PG8_MMA(1, 1, At, B1); PG8_BAR;
;             PG8_LDB(B0, 1, 0); PG8_SCHED; PG8_LDA(At, 1, 0); PG8_STAGE(PG8_SA(0, 1), a2 + hstepA, voffA);
;             PG8_WAIT_L(8); PG8_BAR; PG8_WAIT_L(0); PG8_MMA(0, 0, At, B0); PG8_BAR; PG8_SCHED;
;             PG8_LDB(B1, 1, 1); PG8_STAGE(PG8_SB(1, 0), b3, voffB);
;             PG8_BAR; PG8_WAIT_L(0); PG8_MMA(0, 1, At, B1); PG8_BAR;
	ds_read_b128 v[128:131], v215
	ds_read_b128 v[132:135], v215 offset:1024
	ds_read_b128 v[136:139], v215 offset:2048
	ds_read_b128 v[140:143], v215 offset:3072
	s_add_u32 s8, s28, s42
	s_addc_u32 s93, s22, s43
	s_and_b32 s9, s93, 0xffff
	s_mov_b32 m0, s65
	s_nop 0
	buffer_load_dwordx4 v207, s[8:11], 0 offen lds
	s_mov_b32 m0, s67
	s_nop 0
	buffer_load_dwordx4 v209, s[8:11], 0 offen lds
	s_waitcnt vmcnt(6)
	s_barrier
	s_setprio 1
	v_mfma_f32_16x16x32_bf16 v[60:63], v[176:179], v[144:147], v[60:63]
	v_mfma_f32_16x16x32_bf16 v[56:59], v[188:191], v[144:147], v[56:59]
	v_mfma_f32_16x16x32_bf16 v[44:47], v[176:179], v[152:155], v[44:47]
	v_mfma_f32_16x16x32_bf16 v[40:43], v[188:191], v[152:155], v[40:43]
	v_mfma_f32_16x16x32_bf16 v[28:31], v[176:179], v[160:163], v[28:31]
	v_mfma_f32_16x16x32_bf16 v[24:27], v[188:191], v[160:163], v[24:27]
	v_mfma_f32_16x16x32_bf16 v[12:15], v[176:179], v[168:171], v[12:15]
	v_mfma_f32_16x16x32_bf16 v[8:11], v[188:191], v[168:171], v[8:11]
	v_mfma_f32_16x16x32_bf16 v[60:63], v[180:183], v[148:151], v[60:63]
	v_mfma_f32_16x16x32_bf16 v[56:59], v[192:195], v[148:151], v[56:59]
	v_mfma_f32_16x16x32_bf16 v[44:47], v[180:183], v[156:159], v[44:47]
	v_mfma_f32_16x16x32_bf16 v[40:43], v[192:195], v[156:159], v[40:43]
	v_mfma_f32_16x16x32_bf16 v[28:31], v[180:183], v[164:167], v[28:31]
	v_mfma_f32_16x16x32_bf16 v[24:27], v[192:195], v[164:167], v[24:27]
	v_mfma_f32_16x16x32_bf16 v[12:15], v[180:183], v[172:175], v[12:15]
	v_mfma_f32_16x16x32_bf16 v[8:11], v[192:195], v[172:175], v[8:11]
	s_setprio 0
	s_barrier
	s_add_u32 s36, s36, s18
	s_addc_u32 s9, s23, s19
	s_and_b32 s37, s9, 0xffff
	s_mov_b32 m0, s70
	ds_read_b128 v[144:147], v213 offset:32768
	ds_read_b128 v[148:151], v213 offset:33792
	ds_read_b128 v[152:155], v213 offset:34816
	ds_read_b128 v[156:159], v213 offset:35840
	ds_read_b128 v[160:163], v213 offset:36864
	ds_read_b128 v[164:167], v213 offset:37888
	ds_read_b128 v[168:171], v213 offset:38912
	ds_read_b128 v[172:175], v213 offset:39936
	buffer_load_dwordx4 v206, s[36:39], 0 offen lds
	s_mov_b32 m0, s71
	s_nop 0
	buffer_load_dwordx4 v208, s[36:39], 0 offen lds
	s_waitcnt lgkmcnt(8)
	s_barrier
	s_waitcnt lgkmcnt(0)
	s_setprio 1
	s_waitcnt lgkmcnt(7)
	v_mfma_f32_16x16x32_bf16 v[112:115], v[128:131], v[144:147], v[112:115]
	v_mfma_f32_16x16x32_bf16 v[116:119], v[136:139], v[144:147], v[116:119]
	s_waitcnt lgkmcnt(5)
	v_mfma_f32_16x16x32_bf16 v[100:103], v[128:131], v[152:155], v[100:103]
	v_mfma_f32_16x16x32_bf16 v[96:99], v[136:139], v[152:155], v[96:99]
	s_waitcnt lgkmcnt(3)
	v_mfma_f32_16x16x32_bf16 v[84:87], v[128:131], v[160:163], v[84:87]
	v_mfma_f32_16x16x32_bf16 v[80:83], v[136:139], v[160:163], v[80:83]
	s_waitcnt lgkmcnt(1)
	v_mfma_f32_16x16x32_bf16 v[68:71], v[128:131], v[168:171], v[68:71]
	v_mfma_f32_16x16x32_bf16 v[64:67], v[136:139], v[168:171], v[64:67]
	v_mfma_f32_16x16x32_bf16 v[112:115], v[132:135], v[148:151], v[112:115]
	v_mfma_f32_16x16x32_bf16 v[116:119], v[140:143], v[148:151], v[116:119]
	v_mfma_f32_16x16x32_bf16 v[100:103], v[132:135], v[156:159], v[100:103]
	v_mfma_f32_16x16x32_bf16 v[96:99], v[140:143], v[156:159], v[96:99]
	v_mfma_f32_16x16x32_bf16 v[84:87], v[132:135], v[164:167], v[84:87]
	v_mfma_f32_16x16x32_bf16 v[80:83], v[140:143], v[164:167], v[80:83]
	s_waitcnt lgkmcnt(0)
	v_mfma_f32_16x16x32_bf16 v[68:71], v[132:135], v[172:175], v[68:71]
	v_mfma_f32_16x16x32_bf16 v[64:67], v[140:143], v[172:175], v[64:67]
	s_setprio 0
	s_barrier
	s_add_u32 s28, s28, 0x80
	s_addc_u32 s9, s22, 0
	s_and_b32 s29, s9, 0xffff
	s_mov_b32 m0, s74
	ds_read_b128 v[176:179], v216
	ds_read_b128 v[180:183], v216 offset:1024
	ds_read_b128 v[188:191], v216 offset:2048
	ds_read_b128 v[192:195], v216 offset:3072
	buffer_load_dwordx4 v207, s[28:31], 0 offen lds
	s_mov_b32 m0, s75
	s_nop 0
	buffer_load_dwordx4 v209, s[28:31], 0 offen lds
	s_barrier
; #define PG8_STAGE(bufoff, gbase, voff) do { const __amdgpu_buffer_rsrc_t _r = __builtin_amdgcn_make_buffer_rsrc((void*)(gbase), (short)0, 0x7fffffff, 0x00020000); _Pragma("unroll") for (int _i = 0; _i < 2; ++_i) \
;         __builtin_amdgcn_raw_ptr_buffer_load_lds(_r, (LAS unsigned*)(lds + (bufoff) + ldsw + _i * 8192), 16, (int)(voff)[_i], 0, 0, 0); } while (0)
; #define PG8_LDA(dst, b, h) do { _Pragma("unroll") for (int m = 0; m < 4; ++m) _Pragma("unroll") for (int k = 0; k < 2; ++k) dst[m][k] = *(const LAS bf16x8*)(lds + PG8_SA(b, h) + aoff + m * 2048 + k * 1024); } while (0)
; #define PG8_MMA(ai, bj, At, Bt) do { __builtin_amdgcn_s_setprio(1); _Pragma("unroll") for (int k = 0; k < 2; ++k) _Pragma("unroll") for (int m = 0; m < 4; ++m) _Pragma("unroll") for (int n = 0; n < ((bj) == 1 ? NB1 : 2); ++n) \
;         acc[ai][bj][m][n] = __builtin_amdgcn_mfma_f32_16x16x32_bf16(Bt[n][k], At[m][k], acc[ai][bj][m][n], 0, 0, 0); __builtin_amdgcn_s_setprio(0); } while (0)
; #define PG8_WAIT_V(n) asm volatile("s_waitcnt vmcnt(" #n ")" ::: "memory")
; #define PG8_WAIT_L(n) asm volatile("s_waitcnt lgkmcnt(" #n ")" ::: "memory")
; #define PG8_BAR __builtin_amdgcn_s_barrier()
; #define PG8_SCHED __builtin_amdgcn_sched_barrier(0)
;     ...
;             PG8_BAR; PG8_WAIT_L(0); PG8_MMA(0, 1, At, B1); PG8_BAR;
;             PG8_LDA(At, 1, 1); PG8_STAGE(PG8_SA(1, 0), a3, voffA);
;             PG8_BAR; PG8_WAIT_L(0); PG8_MMA(1, 0, At, B0); PG8_BAR; PG8_SCHED;
;             PG8_STAGE(PG8_SB(1, 1), b3 + hstepB, voffB);
;             PG8_WAIT_V(6); PG8_BAR; PG8_MMA(1, 1, At, B1); PG8_BAR;
;         }
	s_waitcnt lgkmcnt(0)
	s_setprio 1
	s_waitcnt lgkmcnt(3)
	v_mfma_f32_16x16x32_bf16 v[124:127], v[176:179], v[144:147], v[124:127]
	s_waitcnt lgkmcnt(1)
	v_mfma_f32_16x16x32_bf16 v[120:123], v[188:191], v[144:147], v[120:123]
	v_mfma_f32_16x16x32_bf16 v[108:111], v[176:179], v[152:155], v[108:111]
	v_mfma_f32_16x16x32_bf16 v[104:107], v[188:191], v[152:155], v[104:107]
	v_mfma_f32_16x16x32_bf16 v[92:95], v[176:179], v[160:163], v[92:95]
	v_mfma_f32_16x16x32_bf16 v[88:91], v[188:191], v[160:163], v[88:91]
	v_mfma_f32_16x16x32_bf16 v[76:79], v[176:179], v[168:171], v[76:79]
	v_mfma_f32_16x16x32_bf16 v[72:75], v[188:191], v[168:171], v[72:75]
	v_mfma_f32_16x16x32_bf16 v[124:127], v[180:183], v[148:151], v[124:127]
	s_waitcnt lgkmcnt(0)
	v_mfma_f32_16x16x32_bf16 v[120:123], v[192:195], v[148:151], v[120:123]
	v_mfma_f32_16x16x32_bf16 v[108:111], v[180:183], v[156:159], v[108:111]
	v_mfma_f32_16x16x32_bf16 v[104:107], v[192:195], v[156:159], v[104:107]
	v_mfma_f32_16x16x32_bf16 v[92:95], v[180:183], v[164:167], v[92:95]
	v_mfma_f32_16x16x32_bf16 v[88:91], v[192:195], v[164:167], v[88:91]
	v_mfma_f32_16x16x32_bf16 v[76:79], v[180:183], v[172:175], v[76:79]
	v_mfma_f32_16x16x32_bf16 v[72:75], v[192:195], v[172:175], v[72:75]
	s_setprio 0
	s_and_b32 s25, s17, 0xffff
	s_mov_b32 s26, s10
	s_mov_b32 s27, s11
	s_mov_b32 m0, s76
	s_barrier
	ds_read_b128 v[144:147], v213 offset:49152
	ds_read_b128 v[148:151], v213 offset:50176
	ds_read_b128 v[152:155], v213 offset:51200
	ds_read_b128 v[156:159], v213 offset:52224
	ds_read_b128 v[160:163], v213 offset:53248
	ds_read_b128 v[164:167], v213 offset:54272
	ds_read_b128 v[168:171], v213 offset:55296
	ds_read_b128 v[172:175], v213 offset:56320
	buffer_load_dwordx4 v206, s[24:27], 0 offen lds
	s_mov_b32 m0, s77
	s_nop 0
	buffer_load_dwordx4 v208, s[24:27], 0 offen lds
	s_waitcnt vmcnt(8)
	s_barrier
	s_waitcnt lgkmcnt(0)
	s_setprio 1
	s_waitcnt lgkmcnt(7)
	v_mfma_f32_16x16x32_bf16 v[52:55], v[128:131], v[144:147], v[52:55]
	v_mfma_f32_16x16x32_bf16 v[48:51], v[136:139], v[144:147], v[48:51]
	s_waitcnt lgkmcnt(5)
	v_mfma_f32_16x16x32_bf16 v[36:39], v[128:131], v[152:155], v[36:39]
	v_mfma_f32_16x16x32_bf16 v[32:35], v[136:139], v[152:155], v[32:35]
	s_waitcnt lgkmcnt(3)
	v_mfma_f32_16x16x32_bf16 v[20:23], v[128:131], v[160:163], v[20:23]
	v_mfma_f32_16x16x32_bf16 v[16:19], v[136:139], v[160:163], v[16:19]
	s_waitcnt lgkmcnt(1)
	v_mfma_f32_16x16x32_bf16 v[4:7], v[128:131], v[168:171], v[4:7]
	v_mfma_f32_16x16x32_bf16 v[0:3], v[136:139], v[168:171], v[0:3]
	v_mfma_f32_16x16x32_bf16 v[52:55], v[132:135], v[148:151], v[52:55]
	v_mfma_f32_16x16x32_bf16 v[48:51], v[140:143], v[148:151], v[48:51]
	v_mfma_f32_16x16x32_bf16 v[36:39], v[132:135], v[156:159], v[36:39]
	v_mfma_f32_16x16x32_bf16 v[32:35], v[140:143], v[156:159], v[32:35]
	v_mfma_f32_16x16x32_bf16 v[20:23], v[132:135], v[164:167], v[20:23]
	v_mfma_f32_16x16x32_bf16 v[16:19], v[140:143], v[164:167], v[16:19]
	s_waitcnt lgkmcnt(0)
	v_mfma_f32_16x16x32_bf16 v[4:7], v[132:135], v[172:175], v[4:7]
	v_mfma_f32_16x16x32_bf16 v[0:3], v[140:143], v[172:175], v[0:3]
	s_setprio 0
	s_barrier
	ds_read_b128 v[128:131], v212
	ds_read_b128 v[132:135], v212 offset:1024
	ds_read_b128 v[136:139], v212 offset:2048
	ds_read_b128 v[140:143], v212 offset:3072
	s_add_u32 s8, s8, 0x80
	s_addc_u32 s9, s93, 0
	s_and_b32 s9, s9, 0xffff
	s_mov_b32 m0, s78
	s_nop 0
	buffer_load_dwordx4 v207, s[8:11], 0 offen lds
	s_mov_b32 m0, s79
	s_nop 0
	buffer_load_dwordx4 v209, s[8:11], 0 offen lds
	s_waitcnt vmcnt(6)
	s_barrier
	s_setprio 1
	v_mfma_f32_16x16x32_bf16 v[60:63], v[176:179], v[144:147], v[60:63]
	v_mfma_f32_16x16x32_bf16 v[56:59], v[188:191], v[144:147], v[56:59]
	v_mfma_f32_16x16x32_bf16 v[44:47], v[176:179], v[152:155], v[44:47]
	v_mfma_f32_16x16x32_bf16 v[40:43], v[188:191], v[152:155], v[40:43]
	v_mfma_f32_16x16x32_bf16 v[28:31], v[176:179], v[160:163], v[28:31]
	v_mfma_f32_16x16x32_bf16 v[24:27], v[188:191], v[160:163], v[24:27]
	v_mfma_f32_16x16x32_bf16 v[12:15], v[176:179], v[168:171], v[12:15]
	v_mfma_f32_16x16x32_bf16 v[8:11], v[188:191], v[168:171], v[8:11]
	v_mfma_f32_16x16x32_bf16 v[60:63], v[180:183], v[148:151], v[60:63]
	v_mfma_f32_16x16x32_bf16 v[56:59], v[192:195], v[148:151], v[56:59]
	v_mfma_f32_16x16x32_bf16 v[44:47], v[180:183], v[156:159], v[44:47]
	v_mfma_f32_16x16x32_bf16 v[40:43], v[192:195], v[156:159], v[40:43]
	v_mfma_f32_16x16x32_bf16 v[28:31], v[180:183], v[164:167], v[28:31]
	v_mfma_f32_16x16x32_bf16 v[24:27], v[192:195], v[164:167], v[24:27]
	v_mfma_f32_16x16x32_bf16 v[12:15], v[180:183], v[172:175], v[12:15]
	v_mfma_f32_16x16x32_bf16 v[8:11], v[192:195], v[172:175], v[8:11]
	s_setprio 0
	s_add_u32 s89, s89, 0x100
	s_addc_u32 s90, s90, 0
	s_add_u32 s91, s91, 0x100
	s_addc_u32 s92, s92, 0
	s_cmp_ge_i32 s16, s73
	s_mov_b32 s8, s16
	s_barrier
	s_cbranch_scc0 .Lkrot_627
	s_waitcnt lgkmcnt(0)
	s_mov_b64 s[36:37], s[44:45]

; #define PG8_STAGE(bufoff, gbase, voff) do { const __amdgpu_buffer_rsrc_t _r = __builtin_amdgcn_make_buffer_rsrc((void*)(gbase), (short)0, 0x7fffffff, 0x00020000); _Pragma("unroll") for (int _i = 0; _i < 2; ++_i) \
;         __builtin_amdgcn_raw_ptr_buffer_load_lds(_r, (LAS unsigned*)(lds + (bufoff) + ldsw + _i * 8192), 16, (int)(voff)[_i], 0, 0, 0); } while (0)
; #define PG8_LDA(dst, b, h) do { _Pragma("unroll") for (int m = 0; m < 4; ++m) _Pragma("unroll") for (int k = 0; k < 2; ++k) dst[m][k] = *(const LAS bf16x8*)(lds + PG8_SA(b, h) + aoff + m * 2048 + k * 1024); } while (0)
; #define PG8_LDB(dst, b, h) do { _Pragma("unroll") for (int n = 0; n < 2; ++n) _Pragma("unroll") for (int k = 0; k < 2; ++k) dst[n][k] = *(const LAS bf16x8*)(lds + PG8_SB(b, h) + boff + n * 2048 + k * 1024); } while (0)
; #define PG8_MMA(ai, bj, At, Bt) do { __builtin_amdgcn_s_setprio(1); _Pragma("unroll") for (int k = 0; k < 2; ++k) _Pragma("unroll") for (int m = 0; m < 4; ++m) _Pragma("unroll") for (int n = 0; n < ((bj) == 1 ? NB1 : 2); ++n) \
;         acc[ai][bj][m][n] = __builtin_amdgcn_mfma_f32_16x16x32_bf16(Bt[n][k], At[m][k], acc[ai][bj][m][n], 0, 0, 0); __builtin_amdgcn_s_setprio(0); } while (0)
; #define PG8_WAIT_V(n) asm volatile("s_waitcnt vmcnt(" #n ")" ::: "memory")
; #define PG8_WAIT_L(n) asm volatile("s_waitcnt lgkmcnt(" #n ")" ::: "memory")
; #define PG8_BAR __builtin_amdgcn_s_barrier()
;     ...
;         for (int t = 0; t < nt; t += 2) {
;             const bool last = (t == nt - 2);
;             const char* a1 = cA + (size_t)(t + 1) * kstep;
;             const char* a2 = last ? nA : cA + (size_t)(t + 2) * kstep; const char* b2 = last ? nB : cB + (size_t)(t + 2) * kstep;
;             const char* a3 = a2 + kstep; const char* b3 = b2 + kstep;
;             PG8_LDB(B0, 0, 0); PG8_SCHED; PG8_LDA(At, 0, 0); PG8_STAGE(PG8_SA(1, 1), a1 + hstepA, voffA);
;             PG8_WAIT_L(8); PG8_BAR; PG8_WAIT_L(0); PG8_MMA(0, 0, At, B0); PG8_BAR; PG8_SCHED;
;             PG8_LDB(B1, 0, 1); PG8_STAGE(PG8_SB(0, 0), b2, voffB);
;             PG8_BAR; PG8_WAIT_L(0); PG8_MMA(0, 1, At, B1); PG8_BAR;
;             PG8_LDA(At, 0, 1); PG8_STAGE(PG8_SA(0, 0), a2, voffA);
;             PG8_BAR; PG8_WAIT_L(0); PG8_MMA(1, 0, At, B0); PG8_BAR; PG8_SCHED;
;             PG8_STAGE(PG8_SB(0, 1), b2 + hstepB, voffB);
;             PG8_WAIT_V(6); PG8_BAR; PG8_MMA(1, 1, At, B1); PG8_BAR;
.Lkrot_690:
	s_add_i32 s22, s16, 2
	s_cmp_eq_u32 s91, s16
	s_cselect_b32 s36, s59, vcc_lo
	s_cselect_b32 s26, s53, vcc_hi
	s_cselect_b32 s25, s96, s46
	s_cselect_b32 s28, s97, s3
	s_add_u32 s24, s36, 0x80
	s_addc_u32 s23, s26, 0
	s_add_u32 s16, vcc_lo, s0
	s_addc_u32 s17, vcc_hi, s1
	s_add_u32 s16, s16, 0xffffff80
	s_addc_u32 s17, s17, -1
	s_and_b32 s17, s17, 0xffff
	s_mov_b32 m0, s92
	ds_read_b128 v[132:135], v194
	ds_read_b128 v[136:139], v194 offset:1024
	ds_read_b128 v[140:143], v194 offset:2048
	ds_read_b128 v[174:177], v194 offset:3072
	ds_read_b128 v[178:181], v194 offset:4096
	ds_read_b128 v[182:185], v194 offset:5120
	ds_read_b128 v[202:205], v194 offset:6144
	ds_read_b128 v[206:209], v194 offset:7168
	buffer_load_dwordx4 v186, s[16:19], 0 offen lds
	s_mov_b32 m0, s93
	s_nop 0
	buffer_load_dwordx4 v188, s[16:19], 0 offen lds
	s_waitcnt lgkmcnt(8)
	s_barrier
	s_waitcnt lgkmcnt(0)
	s_setprio 1
	s_waitcnt lgkmcnt(7)
	v_mfma_f32_16x16x32_bf16 v[152:155], v[76:79], v[132:135], v[152:155]
	v_mfma_f32_16x16x32_bf16 v[144:147], v[92:95], v[132:135], v[144:147]
	s_waitcnt lgkmcnt(5)
	v_mfma_f32_16x16x32_bf16 v[124:127], v[76:79], v[140:143], v[124:127]
	v_mfma_f32_16x16x32_bf16 v[120:123], v[92:95], v[140:143], v[120:123]
	s_waitcnt lgkmcnt(3)
	v_mfma_f32_16x16x32_bf16 v[108:111], v[76:79], v[178:181], v[108:111]
	v_mfma_f32_16x16x32_bf16 v[104:107], v[92:95], v[178:181], v[104:107]
	s_waitcnt lgkmcnt(1)
	v_mfma_f32_16x16x32_bf16 v[84:87], v[76:79], v[202:205], v[84:87]
	v_mfma_f32_16x16x32_bf16 v[80:83], v[92:95], v[202:205], v[80:83]
	v_mfma_f32_16x16x32_bf16 v[152:155], v[88:91], v[136:139], v[152:155]
	v_mfma_f32_16x16x32_bf16 v[144:147], v[128:131], v[136:139], v[144:147]
	v_mfma_f32_16x16x32_bf16 v[124:127], v[88:91], v[174:177], v[124:127]
	v_mfma_f32_16x16x32_bf16 v[120:123], v[128:131], v[174:177], v[120:123]
	v_mfma_f32_16x16x32_bf16 v[108:111], v[88:91], v[182:185], v[108:111]
	v_mfma_f32_16x16x32_bf16 v[104:107], v[128:131], v[182:185], v[104:107]
	s_waitcnt lgkmcnt(0)
	v_mfma_f32_16x16x32_bf16 v[84:87], v[88:91], v[206:209], v[84:87]
	v_mfma_f32_16x16x32_bf16 v[80:83], v[128:131], v[206:209], v[80:83]
	s_setprio 0
	s_barrier
	s_and_b32 s29, s25, 0xffff
	s_mov_b32 s30, s18
	s_mov_b32 s31, s19
	s_mov_b32 m0, s73
	ds_read_b128 v[210:213], v195
	ds_read_b128 v[214:217], v195 offset:1024
	ds_read_b128 v[218:221], v195 offset:2048
	ds_read_b128 v[222:225], v195 offset:3072
	buffer_load_dwordx4 v187, s[28:31], 0 offen lds
	s_mov_b32 m0, s78
	s_nop 0
	buffer_load_dwordx4 v189, s[28:31], 0 offen lds
	s_barrier
	s_waitcnt lgkmcnt(0)
	s_setprio 1
	s_waitcnt lgkmcnt(3)
	v_mfma_f32_16x16x32_bf16 v[116:119], v[210:213], v[140:143], v[116:119]
	s_waitcnt lgkmcnt(1)
	v_mfma_f32_16x16x32_bf16 v[112:115], v[218:221], v[140:143], v[112:115]
	v_mfma_f32_16x16x32_bf16 v[100:103], v[210:213], v[178:181], v[100:103]
	v_mfma_f32_16x16x32_bf16 v[96:99], v[218:221], v[178:181], v[96:99]
	v_mfma_f32_16x16x32_bf16 v[68:71], v[210:213], v[202:205], v[68:71]
	v_mfma_f32_16x16x32_bf16 v[64:67], v[218:221], v[202:205], v[64:67]
	v_mfma_f32_16x16x32_bf16 v[156:159], v[210:213], v[132:135], v[156:159]
	v_mfma_f32_16x16x32_bf16 v[132:135], v[218:221], v[132:135], v[148:151]
	v_mfma_f32_16x16x32_bf16 v[116:119], v[214:217], v[174:177], v[116:119]
	s_waitcnt lgkmcnt(0)
	v_mfma_f32_16x16x32_bf16 v[112:115], v[222:225], v[174:177], v[112:115]
	v_mfma_f32_16x16x32_bf16 v[100:103], v[214:217], v[182:185], v[100:103]
	v_mfma_f32_16x16x32_bf16 v[96:99], v[222:225], v[182:185], v[96:99]
	v_mfma_f32_16x16x32_bf16 v[68:71], v[214:217], v[206:209], v[68:71]
	v_mfma_f32_16x16x32_bf16 v[64:67], v[222:225], v[206:209], v[64:67]
	v_mfma_f32_16x16x32_bf16 v[140:143], v[214:217], v[136:139], v[156:159]
	v_mfma_f32_16x16x32_bf16 v[132:135], v[222:225], v[136:139], v[132:135]
	s_setprio 0
	s_and_b32 s37, s26, 0xffff
	s_mov_b32 s38, s18
	s_mov_b32 s39, s19
	s_mov_b32 m0, s71
	s_barrier
	ds_read_b128 v[136:139], v194 offset:16384
	ds_read_b128 v[148:151], v194 offset:17408
	ds_read_b128 v[156:159], v194 offset:18432
	ds_read_b128 v[174:177], v194 offset:19456
	ds_read_b128 v[178:181], v194 offset:20480
	ds_read_b128 v[182:185], v194 offset:21504
	ds_read_b128 v[202:205], v194 offset:22528
	ds_read_b128 v[206:209], v194 offset:23552
	buffer_load_dwordx4 v186, s[36:39], 0 offen lds
	s_mov_b32 m0, s79
	s_nop 0
	buffer_load_dwordx4 v188, s[36:39], 0 offen lds
	s_waitcnt vmcnt(8)
	s_barrier
	s_waitcnt lgkmcnt(0)
	s_setprio 1
	s_waitcnt lgkmcnt(7)
	v_mfma_f32_16x16x32_bf16 v[60:63], v[76:79], v[136:139], v[60:63]
	v_mfma_f32_16x16x32_bf16 v[52:55], v[92:95], v[136:139], v[52:55]
	s_waitcnt lgkmcnt(5)
	v_mfma_f32_16x16x32_bf16 v[44:47], v[76:79], v[156:159], v[44:47]
	v_mfma_f32_16x16x32_bf16 v[40:43], v[92:95], v[156:159], v[40:43]
	s_waitcnt lgkmcnt(3)
	v_mfma_f32_16x16x32_bf16 v[28:31], v[76:79], v[178:181], v[28:31]
	v_mfma_f32_16x16x32_bf16 v[24:27], v[92:95], v[178:181], v[24:27]
	s_waitcnt lgkmcnt(1)
	v_mfma_f32_16x16x32_bf16 v[12:15], v[76:79], v[202:205], v[12:15]
	v_mfma_f32_16x16x32_bf16 v[8:11], v[92:95], v[202:205], v[8:11]
	v_mfma_f32_16x16x32_bf16 v[60:63], v[88:91], v[148:151], v[60:63]
	v_mfma_f32_16x16x32_bf16 v[52:55], v[128:131], v[148:151], v[52:55]
	v_mfma_f32_16x16x32_bf16 v[44:47], v[88:91], v[174:177], v[44:47]
	v_mfma_f32_16x16x32_bf16 v[40:43], v[128:131], v[174:177], v[40:43]
	v_mfma_f32_16x16x32_bf16 v[28:31], v[88:91], v[182:185], v[28:31]
	v_mfma_f32_16x16x32_bf16 v[24:27], v[128:131], v[182:185], v[24:27]
	s_waitcnt lgkmcnt(0)
	v_mfma_f32_16x16x32_bf16 v[12:15], v[88:91], v[206:209], v[12:15]
	v_mfma_f32_16x16x32_bf16 v[8:11], v[128:131], v[206:209], v[8:11]
	s_setprio 0
	s_barrier
; #define PG8_STAGE(bufoff, gbase, voff) do { const __amdgpu_buffer_rsrc_t _r = __builtin_amdgcn_make_buffer_rsrc((void*)(gbase), (short)0, 0x7fffffff, 0x00020000); _Pragma("unroll") for (int _i = 0; _i < 2; ++_i) \
;         __builtin_amdgcn_raw_ptr_buffer_load_lds(_r, (LAS unsigned*)(lds + (bufoff) + ldsw + _i * 8192), 16, (int)(voff)[_i], 0, 0, 0); } while (0)
; #define PG8_LDA(dst, b, h) do { _Pragma("unroll") for (int m = 0; m < 4; ++m) _Pragma("unroll") for (int k = 0; k < 2; ++k) dst[m][k] = *(const LAS bf16x8*)(lds + PG8_SA(b, h) + aoff + m * 2048 + k * 1024); } while (0)
; #define PG8_LDB(dst, b, h) do { _Pragma("unroll") for (int n = 0; n < 2; ++n) _Pragma("unroll") for (int k = 0; k < 2; ++k) dst[n][k] = *(const LAS bf16x8*)(lds + PG8_SB(b, h) + boff + n * 2048 + k * 1024); } while (0)
; #define PG8_MMA(ai, bj, At, Bt) do { __builtin_amdgcn_s_setprio(1); _Pragma("unroll") for (int k = 0; k < 2; ++k) _Pragma("unroll") for (int m = 0; m < 4; ++m) _Pragma("unroll") for (int n = 0; n < ((bj) == 1 ? NB1 : 2); ++n) \
;         acc[ai][bj][m][n] = __builtin_amdgcn_mfma_f32_16x16x32_bf16(Bt[n][k], At[m][k], acc[ai][bj][m][n], 0, 0, 0); __builtin_amdgcn_s_setprio(0); } while (0)
; #define PG8_WAIT_V(n) asm volatile("s_waitcnt vmcnt(" #n ")" ::: "memory")
; #define PG8_WAIT_L(n) asm volatile("s_waitcnt lgkmcnt(" #n ")" ::: "memory")
; #define PG8_BAR __builtin_amdgcn_s_barrier()
; #define PG8_SCHED __builtin_amdgcn_sched_barrier(0)
;     ...
;             PG8_WAIT_V(6); PG8_BAR; PG8_MMA(1, 1, At, B1); PG8_BAR;
;             PG8_LDB(B0, 1, 0); PG8_SCHED; PG8_LDA(At, 1, 0); PG8_STAGE(PG8_SA(0, 1), a2 + hstepA, voffA);
;             PG8_WAIT_L(8); PG8_BAR; PG8_WAIT_L(0); PG8_MMA(0, 0, At, B0); PG8_BAR; PG8_SCHED;
;             PG8_LDB(B1, 1, 1); PG8_STAGE(PG8_SB(1, 0), b3, voffB);
;             PG8_BAR; PG8_WAIT_L(0); PG8_MMA(0, 1, At, B1); PG8_BAR;
	ds_read_b128 v[76:79], v196
	ds_read_b128 v[88:91], v196 offset:1024
	ds_read_b128 v[92:95], v196 offset:2048
	ds_read_b128 v[128:131], v196 offset:3072
	s_add_u32 s16, s28, s44
	s_addc_u32 s74, s25, s45
	s_and_b32 s17, s74, 0xffff
	s_mov_b32 m0, s80
	s_nop 0
	buffer_load_dwordx4 v187, s[16:19], 0 offen lds
	s_mov_b32 m0, s81
	s_nop 0
	buffer_load_dwordx4 v189, s[16:19], 0 offen lds
	s_waitcnt vmcnt(6)
	s_barrier
	s_setprio 1
	v_mfma_f32_16x16x32_bf16 v[56:59], v[210:213], v[136:139], v[56:59]
	v_mfma_f32_16x16x32_bf16 v[48:51], v[218:221], v[136:139], v[48:51]
	v_mfma_f32_16x16x32_bf16 v[36:39], v[210:213], v[156:159], v[36:39]
	v_mfma_f32_16x16x32_bf16 v[32:35], v[218:221], v[156:159], v[32:35]
	v_mfma_f32_16x16x32_bf16 v[20:23], v[210:213], v[178:181], v[20:23]
	v_mfma_f32_16x16x32_bf16 v[16:19], v[218:221], v[178:181], v[16:19]
	v_mfma_f32_16x16x32_bf16 v[4:7], v[210:213], v[202:205], v[4:7]
	v_mfma_f32_16x16x32_bf16 v[0:3], v[218:221], v[202:205], v[0:3]
	v_mfma_f32_16x16x32_bf16 v[56:59], v[214:217], v[148:151], v[56:59]
	v_mfma_f32_16x16x32_bf16 v[48:51], v[222:225], v[148:151], v[48:51]
	v_mfma_f32_16x16x32_bf16 v[36:39], v[214:217], v[174:177], v[36:39]
	v_mfma_f32_16x16x32_bf16 v[32:35], v[222:225], v[174:177], v[32:35]
	v_mfma_f32_16x16x32_bf16 v[20:23], v[214:217], v[182:185], v[20:23]
	v_mfma_f32_16x16x32_bf16 v[16:19], v[222:225], v[182:185], v[16:19]
	v_mfma_f32_16x16x32_bf16 v[4:7], v[214:217], v[206:209], v[4:7]
	v_mfma_f32_16x16x32_bf16 v[0:3], v[222:225], v[206:209], v[0:3]
	s_setprio 0
	s_barrier
	s_add_u32 s36, s36, s0
	s_addc_u32 s17, s26, s1
	s_and_b32 s37, s17, 0xffff
	s_mov_b32 m0, s82
	ds_read_b128 v[136:139], v194 offset:32768
	ds_read_b128 v[148:151], v194 offset:33792
	ds_read_b128 v[156:159], v194 offset:34816
	ds_read_b128 v[174:177], v194 offset:35840
	ds_read_b128 v[178:181], v194 offset:36864
	ds_read_b128 v[182:185], v194 offset:37888
	ds_read_b128 v[202:205], v194 offset:38912
	ds_read_b128 v[206:209], v194 offset:39936
	buffer_load_dwordx4 v186, s[36:39], 0 offen lds
	s_mov_b32 m0, s83
	s_nop 0
	buffer_load_dwordx4 v188, s[36:39], 0 offen lds
	s_waitcnt lgkmcnt(8)
	s_barrier
	s_waitcnt lgkmcnt(0)
	s_setprio 1
	s_waitcnt lgkmcnt(7)
	v_mfma_f32_16x16x32_bf16 v[152:155], v[76:79], v[136:139], v[152:155]
	v_mfma_f32_16x16x32_bf16 v[144:147], v[92:95], v[136:139], v[144:147]
	s_waitcnt lgkmcnt(5)
	v_mfma_f32_16x16x32_bf16 v[124:127], v[76:79], v[156:159], v[124:127]
	v_mfma_f32_16x16x32_bf16 v[120:123], v[92:95], v[156:159], v[120:123]
	s_waitcnt lgkmcnt(3)
	v_mfma_f32_16x16x32_bf16 v[108:111], v[76:79], v[178:181], v[108:111]
	v_mfma_f32_16x16x32_bf16 v[104:107], v[92:95], v[178:181], v[104:107]
	s_waitcnt lgkmcnt(1)
	v_mfma_f32_16x16x32_bf16 v[84:87], v[76:79], v[202:205], v[84:87]
	v_mfma_f32_16x16x32_bf16 v[80:83], v[92:95], v[202:205], v[80:83]
	v_mfma_f32_16x16x32_bf16 v[152:155], v[88:91], v[148:151], v[152:155]
	v_mfma_f32_16x16x32_bf16 v[144:147], v[128:131], v[148:151], v[144:147]
	v_mfma_f32_16x16x32_bf16 v[124:127], v[88:91], v[174:177], v[124:127]
	v_mfma_f32_16x16x32_bf16 v[120:123], v[128:131], v[174:177], v[120:123]
	v_mfma_f32_16x16x32_bf16 v[108:111], v[88:91], v[182:185], v[108:111]
	v_mfma_f32_16x16x32_bf16 v[104:107], v[128:131], v[182:185], v[104:107]
	s_waitcnt lgkmcnt(0)
	v_mfma_f32_16x16x32_bf16 v[84:87], v[88:91], v[206:209], v[84:87]
	v_mfma_f32_16x16x32_bf16 v[80:83], v[128:131], v[206:209], v[80:83]
	s_setprio 0
	s_barrier
	s_add_u32 s28, s28, 0x80
	s_addc_u32 s17, s25, 0
	s_and_b32 s29, s17, 0xffff
	s_mov_b32 m0, s85
	ds_read_b128 v[210:213], v197
	ds_read_b128 v[214:217], v197 offset:1024
	ds_read_b128 v[218:221], v197 offset:2048
	ds_read_b128 v[222:225], v197 offset:3072
	buffer_load_dwordx4 v187, s[28:31], 0 offen lds
	s_mov_b32 m0, s86
	s_nop 0
	buffer_load_dwordx4 v189, s[28:31], 0 offen lds
	s_barrier
; #define PG8_STAGE(bufoff, gbase, voff) do { const __amdgpu_buffer_rsrc_t _r = __builtin_amdgcn_make_buffer_rsrc((void*)(gbase), (short)0, 0x7fffffff, 0x00020000); _Pragma("unroll") for (int _i = 0; _i < 2; ++_i) \
;         __builtin_amdgcn_raw_ptr_buffer_load_lds(_r, (LAS unsigned*)(lds + (bufoff) + ldsw + _i * 8192), 16, (int)(voff)[_i], 0, 0, 0); } while (0)
; #define PG8_LDA(dst, b, h) do { _Pragma("unroll") for (int m = 0; m < 4; ++m) _Pragma("unroll") for (int k = 0; k < 2; ++k) dst[m][k] = *(const LAS bf16x8*)(lds + PG8_SA(b, h) + aoff + m * 2048 + k * 1024); } while (0)
; #define PG8_MMA(ai, bj, At, Bt) do { __builtin_amdgcn_s_setprio(1); _Pragma("unroll") for (int k = 0; k < 2; ++k) _Pragma("unroll") for (int m = 0; m < 4; ++m) _Pragma("unroll") for (int n = 0; n < ((bj) == 1 ? NB1 : 2); ++n) \
;         acc[ai][bj][m][n] = __builtin_amdgcn_mfma_f32_16x16x32_bf16(Bt[n][k], At[m][k], acc[ai][bj][m][n], 0, 0, 0); __builtin_amdgcn_s_setprio(0); } while (0)
; #define PG8_WAIT_V(n) asm volatile("s_waitcnt vmcnt(" #n ")" ::: "memory")
; #define PG8_WAIT_L(n) asm volatile("s_waitcnt lgkmcnt(" #n ")" ::: "memory")
; #define PG8_BAR __builtin_amdgcn_s_barrier()
; #define PG8_SCHED __builtin_amdgcn_sched_barrier(0)
;     ...
;             PG8_BAR; PG8_WAIT_L(0); PG8_MMA(0, 1, At, B1); PG8_BAR;
;             PG8_LDA(At, 1, 1); PG8_STAGE(PG8_SA(1, 0), a3, voffA);
;             PG8_BAR; PG8_WAIT_L(0); PG8_MMA(1, 0, At, B0); PG8_BAR; PG8_SCHED;
;             PG8_STAGE(PG8_SB(1, 1), b3 + hstepB, voffB);
;             PG8_WAIT_V(6); PG8_BAR; PG8_MMA(1, 1, At, B1); PG8_BAR;
;         }
	s_waitcnt lgkmcnt(0)
	s_setprio 1
	s_waitcnt lgkmcnt(3)
	v_mfma_f32_16x16x32_bf16 v[140:143], v[210:213], v[136:139], v[140:143]
	s_waitcnt lgkmcnt(1)
	v_mfma_f32_16x16x32_bf16 v[132:135], v[218:221], v[136:139], v[132:135]
	v_mfma_f32_16x16x32_bf16 v[116:119], v[210:213], v[156:159], v[116:119]
	v_mfma_f32_16x16x32_bf16 v[112:115], v[218:221], v[156:159], v[112:115]
	v_mfma_f32_16x16x32_bf16 v[100:103], v[210:213], v[178:181], v[100:103]
	v_mfma_f32_16x16x32_bf16 v[96:99], v[218:221], v[178:181], v[96:99]
	v_mfma_f32_16x16x32_bf16 v[68:71], v[210:213], v[202:205], v[68:71]
	v_mfma_f32_16x16x32_bf16 v[64:67], v[218:221], v[202:205], v[64:67]
	v_mfma_f32_16x16x32_bf16 v[156:159], v[214:217], v[148:151], v[140:143]
	s_waitcnt lgkmcnt(0)
	v_mfma_f32_16x16x32_bf16 v[148:151], v[222:225], v[148:151], v[132:135]
	v_mfma_f32_16x16x32_bf16 v[116:119], v[214:217], v[174:177], v[116:119]
	v_mfma_f32_16x16x32_bf16 v[112:115], v[222:225], v[174:177], v[112:115]
	v_mfma_f32_16x16x32_bf16 v[100:103], v[214:217], v[182:185], v[100:103]
	v_mfma_f32_16x16x32_bf16 v[96:99], v[222:225], v[182:185], v[96:99]
	v_mfma_f32_16x16x32_bf16 v[68:71], v[214:217], v[206:209], v[68:71]
	v_mfma_f32_16x16x32_bf16 v[64:67], v[222:225], v[206:209], v[64:67]
	s_setprio 0
	s_and_b32 s25, s23, 0xffff
	s_mov_b32 s26, s18
	s_mov_b32 s27, s19
	s_mov_b32 m0, s87
	s_barrier
	ds_read_b128 v[132:135], v194 offset:49152
	ds_read_b128 v[136:139], v194 offset:50176
	ds_read_b128 v[140:143], v194 offset:51200
	ds_read_b128 v[174:177], v194 offset:52224
	ds_read_b128 v[178:181], v194 offset:53248
	ds_read_b128 v[182:185], v194 offset:54272
	ds_read_b128 v[202:205], v194 offset:55296
	ds_read_b128 v[206:209], v194 offset:56320
	buffer_load_dwordx4 v186, s[24:27], 0 offen lds
	s_mov_b32 m0, s88
	s_nop 0
	buffer_load_dwordx4 v188, s[24:27], 0 offen lds
	s_waitcnt vmcnt(8)
	s_barrier
	s_waitcnt lgkmcnt(0)
	s_setprio 1
	s_waitcnt lgkmcnt(7)
	v_mfma_f32_16x16x32_bf16 v[60:63], v[76:79], v[132:135], v[60:63]
	v_mfma_f32_16x16x32_bf16 v[52:55], v[92:95], v[132:135], v[52:55]
	s_waitcnt lgkmcnt(5)
	v_mfma_f32_16x16x32_bf16 v[44:47], v[76:79], v[140:143], v[44:47]
	v_mfma_f32_16x16x32_bf16 v[40:43], v[92:95], v[140:143], v[40:43]
	s_waitcnt lgkmcnt(3)
	v_mfma_f32_16x16x32_bf16 v[28:31], v[76:79], v[178:181], v[28:31]
	v_mfma_f32_16x16x32_bf16 v[24:27], v[92:95], v[178:181], v[24:27]
	s_waitcnt lgkmcnt(1)
	v_mfma_f32_16x16x32_bf16 v[12:15], v[76:79], v[202:205], v[12:15]
	v_mfma_f32_16x16x32_bf16 v[8:11], v[92:95], v[202:205], v[8:11]
	v_mfma_f32_16x16x32_bf16 v[60:63], v[88:91], v[136:139], v[60:63]
	v_mfma_f32_16x16x32_bf16 v[52:55], v[128:131], v[136:139], v[52:55]
	v_mfma_f32_16x16x32_bf16 v[44:47], v[88:91], v[174:177], v[44:47]
	v_mfma_f32_16x16x32_bf16 v[40:43], v[128:131], v[174:177], v[40:43]
	v_mfma_f32_16x16x32_bf16 v[28:31], v[88:91], v[182:185], v[28:31]
	v_mfma_f32_16x16x32_bf16 v[24:27], v[128:131], v[182:185], v[24:27]
	s_waitcnt lgkmcnt(0)
	v_mfma_f32_16x16x32_bf16 v[12:15], v[88:91], v[206:209], v[12:15]
	v_mfma_f32_16x16x32_bf16 v[8:11], v[128:131], v[206:209], v[8:11]
	s_setprio 0
	s_barrier
	ds_read_b128 v[76:79], v193
	ds_read_b128 v[88:91], v193 offset:1024
	ds_read_b128 v[92:95], v193 offset:2048
	ds_read_b128 v[128:131], v193 offset:3072
	s_add_u32 s16, s16, 0x80
	s_addc_u32 s17, s74, 0
	s_and_b32 s17, s17, 0xffff
	s_mov_b32 m0, s89
	s_nop 0
	buffer_load_dwordx4 v187, s[16:19], 0 offen lds
	s_mov_b32 m0, s90
	s_nop 0
	buffer_load_dwordx4 v189, s[16:19], 0 offen lds
	s_waitcnt vmcnt(6)
	s_barrier
	s_setprio 1
	v_mfma_f32_16x16x32_bf16 v[56:59], v[210:213], v[132:135], v[56:59]
	v_mfma_f32_16x16x32_bf16 v[48:51], v[218:221], v[132:135], v[48:51]
	v_mfma_f32_16x16x32_bf16 v[36:39], v[210:213], v[140:143], v[36:39]
	v_mfma_f32_16x16x32_bf16 v[32:35], v[218:221], v[140:143], v[32:35]
	v_mfma_f32_16x16x32_bf16 v[20:23], v[210:213], v[178:181], v[20:23]
	v_mfma_f32_16x16x32_bf16 v[16:19], v[218:221], v[178:181], v[16:19]
	v_mfma_f32_16x16x32_bf16 v[4:7], v[210:213], v[202:205], v[4:7]
	v_mfma_f32_16x16x32_bf16 v[0:3], v[218:221], v[202:205], v[0:3]
	v_mfma_f32_16x16x32_bf16 v[56:59], v[214:217], v[136:139], v[56:59]
	v_mfma_f32_16x16x32_bf16 v[48:51], v[222:225], v[136:139], v[48:51]
	v_mfma_f32_16x16x32_bf16 v[36:39], v[214:217], v[174:177], v[36:39]
	v_mfma_f32_16x16x32_bf16 v[32:35], v[222:225], v[174:177], v[32:35]
	v_mfma_f32_16x16x32_bf16 v[20:23], v[214:217], v[182:185], v[20:23]
	v_mfma_f32_16x16x32_bf16 v[16:19], v[222:225], v[182:185], v[16:19]
	v_mfma_f32_16x16x32_bf16 v[4:7], v[214:217], v[206:209], v[4:7]
	v_mfma_f32_16x16x32_bf16 v[0:3], v[222:225], v[206:209], v[0:3]
	s_setprio 0
	s_add_u32 vcc_lo, vcc_lo, 0x100
	s_addc_u32 vcc_hi, vcc_hi, 0
	s_add_u32 s3, s3, 0x100
	s_addc_u32 s46, s46, 0
	s_cmp_ge_i32 s22, s84
	s_mov_b32 s16, s22
	s_barrier
	s_cbranch_scc0 .Lkrot_690
	s_waitcnt lgkmcnt(0)
	v_readlane_b32 s96, v252, 38
	v_readlane_b32 s97, v252, 39

; #define PG8_STAGE(bufoff, gbase, voff) do { const __amdgpu_buffer_rsrc_t _r = __builtin_amdgcn_make_buffer_rsrc((void*)(gbase), (short)0, 0x7fffffff, 0x00020000); _Pragma("unroll") for (int _i = 0; _i < 2; ++_i) \
;         __builtin_amdgcn_raw_ptr_buffer_load_lds(_r, (LAS unsigned*)(lds + (bufoff) + ldsw + _i * 8192), 16, (int)(voff)[_i], 0, 0, 0); } while (0)
; #define PG8_LDA(dst, b, h) do { _Pragma("unroll") for (int m = 0; m < 4; ++m) _Pragma("unroll") for (int k = 0; k < 2; ++k) dst[m][k] = *(const LAS bf16x8*)(lds + PG8_SA(b, h) + aoff + m * 2048 + k * 1024); } while (0)
; #define PG8_LDB(dst, b, h) do { _Pragma("unroll") for (int n = 0; n < 2; ++n) _Pragma("unroll") for (int k = 0; k < 2; ++k) dst[n][k] = *(const LAS bf16x8*)(lds + PG8_SB(b, h) + boff + n * 2048 + k * 1024); } while (0)
; #define PG8_MMA(ai, bj, At, Bt) do { __builtin_amdgcn_s_setprio(1); _Pragma("unroll") for (int k = 0; k < 2; ++k) _Pragma("unroll") for (int m = 0; m < 4; ++m) _Pragma("unroll") for (int n = 0; n < ((bj) == 1 ? NB1 : 2); ++n) \
;         acc[ai][bj][m][n] = __builtin_amdgcn_mfma_f32_16x16x32_bf16(Bt[n][k], At[m][k], acc[ai][bj][m][n], 0, 0, 0); __builtin_amdgcn_s_setprio(0); } while (0)
; #define PG8_WAIT_V(n) asm volatile("s_waitcnt vmcnt(" #n ")" ::: "memory")
; #define PG8_WAIT_L(n) asm volatile("s_waitcnt lgkmcnt(" #n ")" ::: "memory")
; #define PG8_BAR __builtin_amdgcn_s_barrier()
;     ...
;         for (int t = 0; t < nt; t += 2) {
;             const bool last = (t == nt - 2);
;             const char* a1 = cA + (size_t)(t + 1) * kstep;
;             const char* a2 = last ? nA : cA + (size_t)(t + 2) * kstep; const char* b2 = last ? nB : cB + (size_t)(t + 2) * kstep;
;             const char* a3 = a2 + kstep; const char* b3 = b2 + kstep;
;             PG8_LDB(B0, 0, 0); PG8_SCHED; PG8_LDA(At, 0, 0); PG8_STAGE(PG8_SA(1, 1), a1 + hstepA, voffA);
;             PG8_WAIT_L(8); PG8_BAR; PG8_WAIT_L(0); PG8_MMA(0, 0, At, B0); PG8_BAR; PG8_SCHED;
;             PG8_LDB(B1, 0, 1); PG8_STAGE(PG8_SB(0, 0), b2, voffB);
;             PG8_BAR; PG8_WAIT_L(0); PG8_MMA(0, 1, At, B1); PG8_BAR;
;             PG8_LDA(At, 0, 1); PG8_STAGE(PG8_SA(0, 0), a2, voffA);
;             PG8_BAR; PG8_WAIT_L(0); PG8_MMA(1, 0, At, B0); PG8_BAR; PG8_SCHED;
;             PG8_STAGE(PG8_SB(0, 1), b2 + hstepB, voffB);
;             PG8_WAIT_V(6); PG8_BAR; PG8_MMA(1, 1, At, B1); PG8_BAR;
.Lkrot_772:
	s_add_i32 s22, s8, 2
	s_cmp_eq_u32 s81, s8
	s_cselect_b32 s28, s0, s89
	s_cselect_b32 s19, s1, s90
	s_cselect_b32 s18, s51, s92
	s_cselect_b32 s24, s50, s91
	s_add_u32 s16, s28, 0x80
	s_addc_u32 s17, s19, 0
	s_add_u32 s8, s89, s36
	s_addc_u32 s9, s90, s37
	s_add_u32 s8, s8, 0xffffff80
	s_addc_u32 s9, s9, -1
	s_and_b32 s9, s9, 0xffff
	s_mov_b32 m0, s82
	ds_read_b128 v[144:147], v228
	ds_read_b128 v[148:151], v228 offset:1024
	ds_read_b128 v[152:155], v228 offset:2048
	ds_read_b128 v[156:159], v228 offset:3072
	ds_read_b128 v[160:163], v228 offset:4096
	ds_read_b128 v[164:167], v228 offset:5120
	ds_read_b128 v[168:171], v228 offset:6144
	ds_read_b128 v[172:175], v228 offset:7168
	buffer_load_dwordx4 v222, s[8:11], 0 offen lds
	s_mov_b32 m0, s83
	s_nop 0
	buffer_load_dwordx4 v224, s[8:11], 0 offen lds
	s_waitcnt lgkmcnt(8)
	s_barrier
	s_waitcnt lgkmcnt(0)
	s_setprio 1
	s_waitcnt lgkmcnt(7)
	v_mfma_f32_16x16x32_bf16 v[120:123], v[128:131], v[144:147], v[120:123]
	v_mfma_f32_16x16x32_bf16 v[124:127], v[136:139], v[144:147], v[124:127]
	s_waitcnt lgkmcnt(5)
	v_mfma_f32_16x16x32_bf16 v[108:111], v[128:131], v[152:155], v[108:111]
	v_mfma_f32_16x16x32_bf16 v[104:107], v[136:139], v[152:155], v[104:107]
	s_waitcnt lgkmcnt(3)
	v_mfma_f32_16x16x32_bf16 v[92:95], v[128:131], v[160:163], v[92:95]
	v_mfma_f32_16x16x32_bf16 v[88:91], v[136:139], v[160:163], v[88:91]
	s_waitcnt lgkmcnt(1)
	v_mfma_f32_16x16x32_bf16 v[76:79], v[128:131], v[168:171], v[76:79]
	v_mfma_f32_16x16x32_bf16 v[72:75], v[136:139], v[168:171], v[72:75]
	v_mfma_f32_16x16x32_bf16 v[120:123], v[132:135], v[148:151], v[120:123]
	v_mfma_f32_16x16x32_bf16 v[124:127], v[140:143], v[148:151], v[124:127]
	v_mfma_f32_16x16x32_bf16 v[108:111], v[132:135], v[156:159], v[108:111]
	v_mfma_f32_16x16x32_bf16 v[104:107], v[140:143], v[156:159], v[104:107]
	v_mfma_f32_16x16x32_bf16 v[92:95], v[132:135], v[164:167], v[92:95]
	v_mfma_f32_16x16x32_bf16 v[88:91], v[140:143], v[164:167], v[88:91]
	s_waitcnt lgkmcnt(0)
	v_mfma_f32_16x16x32_bf16 v[76:79], v[132:135], v[172:175], v[76:79]
	v_mfma_f32_16x16x32_bf16 v[72:75], v[140:143], v[172:175], v[72:75]
	s_setprio 0
	s_barrier
	s_and_b32 s25, s18, 0xffff
	s_mov_b32 s26, s10
	s_mov_b32 s27, s11
	s_mov_b32 m0, s64
	ds_read_b128 v[176:179], v229
	ds_read_b128 v[180:183], v229 offset:1024
	ds_read_b128 v[192:195], v229 offset:2048
	ds_read_b128 v[196:199], v229 offset:3072
	buffer_load_dwordx4 v223, s[24:27], 0 offen lds
	s_mov_b32 m0, s65
	s_nop 0
	buffer_load_dwordx4 v225, s[24:27], 0 offen lds
	s_barrier
	s_waitcnt lgkmcnt(0)
	s_setprio 1
	s_waitcnt lgkmcnt(3)
	v_mfma_f32_16x16x32_bf16 v[116:119], v[176:179], v[144:147], v[116:119]
	s_waitcnt lgkmcnt(1)
	v_mfma_f32_16x16x32_bf16 v[112:115], v[192:195], v[144:147], v[112:115]
	v_mfma_f32_16x16x32_bf16 v[100:103], v[176:179], v[152:155], v[100:103]
	v_mfma_f32_16x16x32_bf16 v[96:99], v[192:195], v[152:155], v[96:99]
	v_mfma_f32_16x16x32_bf16 v[84:87], v[176:179], v[160:163], v[84:87]
	v_mfma_f32_16x16x32_bf16 v[80:83], v[192:195], v[160:163], v[80:83]
	v_mfma_f32_16x16x32_bf16 v[68:71], v[176:179], v[168:171], v[68:71]
	v_mfma_f32_16x16x32_bf16 v[64:67], v[192:195], v[168:171], v[64:67]
	v_mfma_f32_16x16x32_bf16 v[116:119], v[180:183], v[148:151], v[116:119]
	s_waitcnt lgkmcnt(0)
	v_mfma_f32_16x16x32_bf16 v[112:115], v[196:199], v[148:151], v[112:115]
	v_mfma_f32_16x16x32_bf16 v[100:103], v[180:183], v[156:159], v[100:103]
	v_mfma_f32_16x16x32_bf16 v[96:99], v[196:199], v[156:159], v[96:99]
	v_mfma_f32_16x16x32_bf16 v[84:87], v[180:183], v[164:167], v[84:87]
	v_mfma_f32_16x16x32_bf16 v[80:83], v[196:199], v[164:167], v[80:83]
	v_mfma_f32_16x16x32_bf16 v[68:71], v[180:183], v[172:175], v[68:71]
	v_mfma_f32_16x16x32_bf16 v[64:67], v[196:199], v[172:175], v[64:67]
	s_setprio 0
	s_and_b32 s29, s19, 0xffff
	s_mov_b32 s30, s10
	s_mov_b32 s31, s11
	s_mov_b32 m0, s59
	s_barrier
	ds_read_b128 v[144:147], v228 offset:16384
	ds_read_b128 v[148:151], v228 offset:17408
	ds_read_b128 v[152:155], v228 offset:18432
	ds_read_b128 v[156:159], v228 offset:19456
	ds_read_b128 v[160:163], v228 offset:20480
	ds_read_b128 v[164:167], v228 offset:21504
	ds_read_b128 v[168:171], v228 offset:22528
	ds_read_b128 v[172:175], v228 offset:23552
	buffer_load_dwordx4 v222, s[28:31], 0 offen lds
	s_mov_b32 m0, s67
	s_nop 0
	buffer_load_dwordx4 v224, s[28:31], 0 offen lds
	s_waitcnt vmcnt(8)
	s_barrier
	s_waitcnt lgkmcnt(0)
	s_setprio 1
	s_waitcnt lgkmcnt(7)
	v_mfma_f32_16x16x32_bf16 v[60:63], v[128:131], v[144:147], v[60:63]
	v_mfma_f32_16x16x32_bf16 v[56:59], v[136:139], v[144:147], v[56:59]
	s_waitcnt lgkmcnt(5)
	v_mfma_f32_16x16x32_bf16 v[44:47], v[128:131], v[152:155], v[44:47]
	v_mfma_f32_16x16x32_bf16 v[40:43], v[136:139], v[152:155], v[40:43]
	s_waitcnt lgkmcnt(3)
	v_mfma_f32_16x16x32_bf16 v[28:31], v[128:131], v[160:163], v[28:31]
	v_mfma_f32_16x16x32_bf16 v[24:27], v[136:139], v[160:163], v[24:27]
	s_waitcnt lgkmcnt(1)
	v_mfma_f32_16x16x32_bf16 v[12:15], v[128:131], v[168:171], v[12:15]
	v_mfma_f32_16x16x32_bf16 v[8:11], v[136:139], v[168:171], v[8:11]
	v_mfma_f32_16x16x32_bf16 v[60:63], v[132:135], v[148:151], v[60:63]
	v_mfma_f32_16x16x32_bf16 v[56:59], v[140:143], v[148:151], v[56:59]
	v_mfma_f32_16x16x32_bf16 v[44:47], v[132:135], v[156:159], v[44:47]
	v_mfma_f32_16x16x32_bf16 v[40:43], v[140:143], v[156:159], v[40:43]
	v_mfma_f32_16x16x32_bf16 v[28:31], v[132:135], v[164:167], v[28:31]
	v_mfma_f32_16x16x32_bf16 v[24:27], v[140:143], v[164:167], v[24:27]
	s_waitcnt lgkmcnt(0)
	v_mfma_f32_16x16x32_bf16 v[12:15], v[132:135], v[172:175], v[12:15]
	v_mfma_f32_16x16x32_bf16 v[8:11], v[140:143], v[172:175], v[8:11]
	s_setprio 0
	s_barrier
; #define PG8_STAGE(bufoff, gbase, voff) do { const __amdgpu_buffer_rsrc_t _r = __builtin_amdgcn_make_buffer_rsrc((void*)(gbase), (short)0, 0x7fffffff, 0x00020000); _Pragma("unroll") for (int _i = 0; _i < 2; ++_i) \
;         __builtin_amdgcn_raw_ptr_buffer_load_lds(_r, (LAS unsigned*)(lds + (bufoff) + ldsw + _i * 8192), 16, (int)(voff)[_i], 0, 0, 0); } while (0)
; #define PG8_LDA(dst, b, h) do { _Pragma("unroll") for (int m = 0; m < 4; ++m) _Pragma("unroll") for (int k = 0; k < 2; ++k) dst[m][k] = *(const LAS bf16x8*)(lds + PG8_SA(b, h) + aoff + m * 2048 + k * 1024); } while (0)
; #define PG8_LDB(dst, b, h) do { _Pragma("unroll") for (int n = 0; n < 2; ++n) _Pragma("unroll") for (int k = 0; k < 2; ++k) dst[n][k] = *(const LAS bf16x8*)(lds + PG8_SB(b, h) + boff + n * 2048 + k * 1024); } while (0)
; #define PG8_MMA(ai, bj, At, Bt) do { __builtin_amdgcn_s_setprio(1); _Pragma("unroll") for (int k = 0; k < 2; ++k) _Pragma("unroll") for (int m = 0; m < 4; ++m) _Pragma("unroll") for (int n = 0; n < ((bj) == 1 ? NB1 : 2); ++n) \
;         acc[ai][bj][m][n] = __builtin_amdgcn_mfma_f32_16x16x32_bf16(Bt[n][k], At[m][k], acc[ai][bj][m][n], 0, 0, 0); __builtin_amdgcn_s_setprio(0); } while (0)
; #define PG8_WAIT_V(n) asm volatile("s_waitcnt vmcnt(" #n ")" ::: "memory")
; #define PG8_WAIT_L(n) asm volatile("s_waitcnt lgkmcnt(" #n ")" ::: "memory")
; #define PG8_BAR __builtin_amdgcn_s_barrier()
; #define PG8_SCHED __builtin_amdgcn_sched_barrier(0)
;     ...
;             PG8_WAIT_V(6); PG8_BAR; PG8_MMA(1, 1, At, B1); PG8_BAR;
;             PG8_LDB(B0, 1, 0); PG8_SCHED; PG8_LDA(At, 1, 0); PG8_STAGE(PG8_SA(0, 1), a2 + hstepA, voffA);
;             PG8_WAIT_L(8); PG8_BAR; PG8_WAIT_L(0); PG8_MMA(0, 0, At, B0); PG8_BAR; PG8_SCHED;
;             PG8_LDB(B1, 1, 1); PG8_STAGE(PG8_SB(1, 0), b3, voffB);
;             PG8_BAR; PG8_WAIT_L(0); PG8_MMA(0, 1, At, B1); PG8_BAR;
	ds_read_b128 v[128:131], v230
	ds_read_b128 v[132:135], v230 offset:1024
	ds_read_b128 v[136:139], v230 offset:2048
	ds_read_b128 v[140:143], v230 offset:3072
	s_add_u32 s8, s24, s38
	s_addc_u32 s23, s18, s39
	s_and_b32 s9, s23, 0xffff
	s_mov_b32 m0, s70
	s_nop 0
	buffer_load_dwordx4 v223, s[8:11], 0 offen lds
	s_mov_b32 m0, s71
	s_nop 0
	buffer_load_dwordx4 v225, s[8:11], 0 offen lds
	s_waitcnt vmcnt(6)
	s_barrier
	s_setprio 1
	v_mfma_f32_16x16x32_bf16 v[52:55], v[176:179], v[144:147], v[52:55]
	v_mfma_f32_16x16x32_bf16 v[48:51], v[192:195], v[144:147], v[48:51]
	v_mfma_f32_16x16x32_bf16 v[36:39], v[176:179], v[152:155], v[36:39]
	v_mfma_f32_16x16x32_bf16 v[32:35], v[192:195], v[152:155], v[32:35]
	v_mfma_f32_16x16x32_bf16 v[20:23], v[176:179], v[160:163], v[20:23]
	v_mfma_f32_16x16x32_bf16 v[16:19], v[192:195], v[160:163], v[16:19]
	v_mfma_f32_16x16x32_bf16 v[4:7], v[176:179], v[168:171], v[4:7]
	v_mfma_f32_16x16x32_bf16 v[0:3], v[192:195], v[168:171], v[0:3]
	v_mfma_f32_16x16x32_bf16 v[52:55], v[180:183], v[148:151], v[52:55]
	v_mfma_f32_16x16x32_bf16 v[48:51], v[196:199], v[148:151], v[48:51]
	v_mfma_f32_16x16x32_bf16 v[36:39], v[180:183], v[156:159], v[36:39]
	v_mfma_f32_16x16x32_bf16 v[32:35], v[196:199], v[156:159], v[32:35]
	v_mfma_f32_16x16x32_bf16 v[20:23], v[180:183], v[164:167], v[20:23]
	v_mfma_f32_16x16x32_bf16 v[16:19], v[196:199], v[164:167], v[16:19]
	v_mfma_f32_16x16x32_bf16 v[4:7], v[180:183], v[172:175], v[4:7]
	v_mfma_f32_16x16x32_bf16 v[0:3], v[196:199], v[172:175], v[0:3]
	s_setprio 0
	s_barrier
	s_add_u32 s28, s28, s36
	s_addc_u32 s9, s19, s37
	s_and_b32 s29, s9, 0xffff
	s_mov_b32 m0, s72
	ds_read_b128 v[144:147], v228 offset:32768
	ds_read_b128 v[148:151], v228 offset:33792
	ds_read_b128 v[152:155], v228 offset:34816
	ds_read_b128 v[156:159], v228 offset:35840
	ds_read_b128 v[160:163], v228 offset:36864
	ds_read_b128 v[164:167], v228 offset:37888
	ds_read_b128 v[168:171], v228 offset:38912
	ds_read_b128 v[172:175], v228 offset:39936
	buffer_load_dwordx4 v222, s[28:31], 0 offen lds
	s_mov_b32 m0, s73
	s_nop 0
	buffer_load_dwordx4 v224, s[28:31], 0 offen lds
	s_waitcnt lgkmcnt(8)
	s_barrier
	s_waitcnt lgkmcnt(0)
	s_setprio 1
	s_waitcnt lgkmcnt(7)
	v_mfma_f32_16x16x32_bf16 v[120:123], v[128:131], v[144:147], v[120:123]
	v_mfma_f32_16x16x32_bf16 v[124:127], v[136:139], v[144:147], v[124:127]
	s_waitcnt lgkmcnt(5)
	v_mfma_f32_16x16x32_bf16 v[108:111], v[128:131], v[152:155], v[108:111]
	v_mfma_f32_16x16x32_bf16 v[104:107], v[136:139], v[152:155], v[104:107]
	s_waitcnt lgkmcnt(3)
	v_mfma_f32_16x16x32_bf16 v[92:95], v[128:131], v[160:163], v[92:95]
	v_mfma_f32_16x16x32_bf16 v[88:91], v[136:139], v[160:163], v[88:91]
	s_waitcnt lgkmcnt(1)
	v_mfma_f32_16x16x32_bf16 v[76:79], v[128:131], v[168:171], v[76:79]
	v_mfma_f32_16x16x32_bf16 v[72:75], v[136:139], v[168:171], v[72:75]
	v_mfma_f32_16x16x32_bf16 v[120:123], v[132:135], v[148:151], v[120:123]
	v_mfma_f32_16x16x32_bf16 v[124:127], v[140:143], v[148:151], v[124:127]
	v_mfma_f32_16x16x32_bf16 v[108:111], v[132:135], v[156:159], v[108:111]
	v_mfma_f32_16x16x32_bf16 v[104:107], v[140:143], v[156:159], v[104:107]
	v_mfma_f32_16x16x32_bf16 v[92:95], v[132:135], v[164:167], v[92:95]
	v_mfma_f32_16x16x32_bf16 v[88:91], v[140:143], v[164:167], v[88:91]
	s_waitcnt lgkmcnt(0)
	v_mfma_f32_16x16x32_bf16 v[76:79], v[132:135], v[172:175], v[76:79]
	v_mfma_f32_16x16x32_bf16 v[72:75], v[140:143], v[172:175], v[72:75]
	s_setprio 0
	s_barrier
	s_add_u32 s24, s24, 0x80
	s_addc_u32 s9, s18, 0
	s_and_b32 s25, s9, 0xffff
	s_mov_b32 m0, s75
	ds_read_b128 v[176:179], v231
	ds_read_b128 v[180:183], v231 offset:1024
	ds_read_b128 v[192:195], v231 offset:2048
	ds_read_b128 v[196:199], v231 offset:3072
	buffer_load_dwordx4 v223, s[24:27], 0 offen lds
	s_mov_b32 m0, s76
	s_nop 0
	buffer_load_dwordx4 v225, s[24:27], 0 offen lds
	s_barrier
; #define PG8_STAGE(bufoff, gbase, voff) do { const __amdgpu_buffer_rsrc_t _r = __builtin_amdgcn_make_buffer_rsrc((void*)(gbase), (short)0, 0x7fffffff, 0x00020000); _Pragma("unroll") for (int _i = 0; _i < 2; ++_i) \
;         __builtin_amdgcn_raw_ptr_buffer_load_lds(_r, (LAS unsigned*)(lds + (bufoff) + ldsw + _i * 8192), 16, (int)(voff)[_i], 0, 0, 0); } while (0)
; #define PG8_LDA(dst, b, h) do { _Pragma("unroll") for (int m = 0; m < 4; ++m) _Pragma("unroll") for (int k = 0; k < 2; ++k) dst[m][k] = *(const LAS bf16x8*)(lds + PG8_SA(b, h) + aoff + m * 2048 + k * 1024); } while (0)
; #define PG8_MMA(ai, bj, At, Bt) do { __builtin_amdgcn_s_setprio(1); _Pragma("unroll") for (int k = 0; k < 2; ++k) _Pragma("unroll") for (int m = 0; m < 4; ++m) _Pragma("unroll") for (int n = 0; n < ((bj) == 1 ? NB1 : 2); ++n) \
;         acc[ai][bj][m][n] = __builtin_amdgcn_mfma_f32_16x16x32_bf16(Bt[n][k], At[m][k], acc[ai][bj][m][n], 0, 0, 0); __builtin_amdgcn_s_setprio(0); } while (0)
; #define PG8_WAIT_V(n) asm volatile("s_waitcnt vmcnt(" #n ")" ::: "memory")
; #define PG8_WAIT_L(n) asm volatile("s_waitcnt lgkmcnt(" #n ")" ::: "memory")
; #define PG8_BAR __builtin_amdgcn_s_barrier()
; #define PG8_SCHED __builtin_amdgcn_sched_barrier(0)
;     ...
;             PG8_BAR; PG8_WAIT_L(0); PG8_MMA(0, 1, At, B1); PG8_BAR;
;             PG8_LDA(At, 1, 1); PG8_STAGE(PG8_SA(1, 0), a3, voffA);
;             PG8_BAR; PG8_WAIT_L(0); PG8_MMA(1, 0, At, B0); PG8_BAR; PG8_SCHED;
;             PG8_STAGE(PG8_SB(1, 1), b3 + hstepB, voffB);
;             PG8_WAIT_V(6); PG8_BAR; PG8_MMA(1, 1, At, B1); PG8_BAR;
;         }
	s_waitcnt lgkmcnt(0)
	s_setprio 1
	s_waitcnt lgkmcnt(3)
	v_mfma_f32_16x16x32_bf16 v[116:119], v[176:179], v[144:147], v[116:119]
	s_waitcnt lgkmcnt(1)
	v_mfma_f32_16x16x32_bf16 v[112:115], v[192:195], v[144:147], v[112:115]
	v_mfma_f32_16x16x32_bf16 v[100:103], v[176:179], v[152:155], v[100:103]
	v_mfma_f32_16x16x32_bf16 v[96:99], v[192:195], v[152:155], v[96:99]
	v_mfma_f32_16x16x32_bf16 v[84:87], v[176:179], v[160:163], v[84:87]
	v_mfma_f32_16x16x32_bf16 v[80:83], v[192:195], v[160:163], v[80:83]
	v_mfma_f32_16x16x32_bf16 v[68:71], v[176:179], v[168:171], v[68:71]
	v_mfma_f32_16x16x32_bf16 v[64:67], v[192:195], v[168:171], v[64:67]
	v_mfma_f32_16x16x32_bf16 v[116:119], v[180:183], v[148:151], v[116:119]
	s_waitcnt lgkmcnt(0)
	v_mfma_f32_16x16x32_bf16 v[112:115], v[196:199], v[148:151], v[112:115]
	v_mfma_f32_16x16x32_bf16 v[100:103], v[180:183], v[156:159], v[100:103]
	v_mfma_f32_16x16x32_bf16 v[96:99], v[196:199], v[156:159], v[96:99]
	v_mfma_f32_16x16x32_bf16 v[84:87], v[180:183], v[164:167], v[84:87]
	v_mfma_f32_16x16x32_bf16 v[80:83], v[196:199], v[164:167], v[80:83]
	v_mfma_f32_16x16x32_bf16 v[68:71], v[180:183], v[172:175], v[68:71]
	v_mfma_f32_16x16x32_bf16 v[64:67], v[196:199], v[172:175], v[64:67]
	s_setprio 0
	s_and_b32 s17, s17, 0xffff
	s_mov_b32 s18, s10
	s_mov_b32 s19, s11
	s_mov_b32 m0, s77
	s_barrier
	ds_read_b128 v[144:147], v228 offset:49152
	ds_read_b128 v[148:151], v228 offset:50176
	ds_read_b128 v[152:155], v228 offset:51200
	ds_read_b128 v[156:159], v228 offset:52224
	ds_read_b128 v[160:163], v228 offset:53248
	ds_read_b128 v[164:167], v228 offset:54272
	ds_read_b128 v[168:171], v228 offset:55296
	ds_read_b128 v[172:175], v228 offset:56320
	buffer_load_dwordx4 v222, s[16:19], 0 offen lds
	s_mov_b32 m0, s78
	s_nop 0
	buffer_load_dwordx4 v224, s[16:19], 0 offen lds
	s_waitcnt vmcnt(8)
	s_barrier
	s_waitcnt lgkmcnt(0)
	s_setprio 1
	s_waitcnt lgkmcnt(7)
	v_mfma_f32_16x16x32_bf16 v[60:63], v[128:131], v[144:147], v[60:63]
	v_mfma_f32_16x16x32_bf16 v[56:59], v[136:139], v[144:147], v[56:59]
	s_waitcnt lgkmcnt(5)
	v_mfma_f32_16x16x32_bf16 v[44:47], v[128:131], v[152:155], v[44:47]
	v_mfma_f32_16x16x32_bf16 v[40:43], v[136:139], v[152:155], v[40:43]
	s_waitcnt lgkmcnt(3)
	v_mfma_f32_16x16x32_bf16 v[28:31], v[128:131], v[160:163], v[28:31]
	v_mfma_f32_16x16x32_bf16 v[24:27], v[136:139], v[160:163], v[24:27]
	s_waitcnt lgkmcnt(1)
	v_mfma_f32_16x16x32_bf16 v[12:15], v[128:131], v[168:171], v[12:15]
	v_mfma_f32_16x16x32_bf16 v[8:11], v[136:139], v[168:171], v[8:11]
	v_mfma_f32_16x16x32_bf16 v[60:63], v[132:135], v[148:151], v[60:63]
	v_mfma_f32_16x16x32_bf16 v[56:59], v[140:143], v[148:151], v[56:59]
	v_mfma_f32_16x16x32_bf16 v[44:47], v[132:135], v[156:159], v[44:47]
	v_mfma_f32_16x16x32_bf16 v[40:43], v[140:143], v[156:159], v[40:43]
	v_mfma_f32_16x16x32_bf16 v[28:31], v[132:135], v[164:167], v[28:31]
	v_mfma_f32_16x16x32_bf16 v[24:27], v[140:143], v[164:167], v[24:27]
	s_waitcnt lgkmcnt(0)
	v_mfma_f32_16x16x32_bf16 v[12:15], v[132:135], v[172:175], v[12:15]
	v_mfma_f32_16x16x32_bf16 v[8:11], v[140:143], v[172:175], v[8:11]
	s_setprio 0
	s_barrier
	ds_read_b128 v[128:131], v227
	ds_read_b128 v[132:135], v227 offset:1024
	ds_read_b128 v[136:139], v227 offset:2048
	ds_read_b128 v[140:143], v227 offset:3072
	s_add_u32 s8, s8, 0x80
	s_addc_u32 s9, s23, 0
	s_and_b32 s9, s9, 0xffff
	s_mov_b32 m0, s79
	s_nop 0
	buffer_load_dwordx4 v223, s[8:11], 0 offen lds
	s_mov_b32 m0, s80
	s_nop 0
	buffer_load_dwordx4 v225, s[8:11], 0 offen lds
	s_waitcnt vmcnt(6)
	s_barrier
	s_setprio 1
	v_mfma_f32_16x16x32_bf16 v[52:55], v[176:179], v[144:147], v[52:55]
	v_mfma_f32_16x16x32_bf16 v[48:51], v[192:195], v[144:147], v[48:51]
	v_mfma_f32_16x16x32_bf16 v[36:39], v[176:179], v[152:155], v[36:39]
	v_mfma_f32_16x16x32_bf16 v[32:35], v[192:195], v[152:155], v[32:35]
	v_mfma_f32_16x16x32_bf16 v[20:23], v[176:179], v[160:163], v[20:23]
	v_mfma_f32_16x16x32_bf16 v[16:19], v[192:195], v[160:163], v[16:19]
	v_mfma_f32_16x16x32_bf16 v[4:7], v[176:179], v[168:171], v[4:7]
	v_mfma_f32_16x16x32_bf16 v[0:3], v[192:195], v[168:171], v[0:3]
	v_mfma_f32_16x16x32_bf16 v[52:55], v[180:183], v[148:151], v[52:55]
	v_mfma_f32_16x16x32_bf16 v[48:51], v[196:199], v[148:151], v[48:51]
	v_mfma_f32_16x16x32_bf16 v[36:39], v[180:183], v[156:159], v[36:39]
	v_mfma_f32_16x16x32_bf16 v[32:35], v[196:199], v[156:159], v[32:35]
	v_mfma_f32_16x16x32_bf16 v[20:23], v[180:183], v[164:167], v[20:23]
	v_mfma_f32_16x16x32_bf16 v[16:19], v[196:199], v[164:167], v[16:19]
	v_mfma_f32_16x16x32_bf16 v[4:7], v[180:183], v[172:175], v[4:7]
	v_mfma_f32_16x16x32_bf16 v[0:3], v[196:199], v[172:175], v[0:3]
	s_setprio 0
	s_add_u32 s89, s89, 0x100
	s_addc_u32 s90, s90, 0
	s_add_u32 s91, s91, 0x100
	s_addc_u32 s92, s92, 0
	s_cmp_ge_i32 s22, s74
	s_mov_b32 s8, s22
	s_barrier
	s_cbranch_scc0 .Lkrot_772
	s_waitcnt lgkmcnt(0)

; #define PG8_STAGE(bufoff, gbase, voff) do { const __amdgpu_buffer_rsrc_t _r = __builtin_amdgcn_make_buffer_rsrc((void*)(gbase), (short)0, 0x7fffffff, 0x00020000); _Pragma("unroll") for (int _i = 0; _i < 2; ++_i) \
;         __builtin_amdgcn_raw_ptr_buffer_load_lds(_r, (LAS unsigned*)(lds + (bufoff) + ldsw + _i * 8192), 16, (int)(voff)[_i], 0, 0, 0); } while (0)
; #define PG8_LDA(dst, b, h) do { _Pragma("unroll") for (int m = 0; m < 4; ++m) _Pragma("unroll") for (int k = 0; k < 2; ++k) dst[m][k] = *(const LAS bf16x8*)(lds + PG8_SA(b, h) + aoff + m * 2048 + k * 1024); } while (0)
; #define PG8_LDB(dst, b, h) do { _Pragma("unroll") for (int n = 0; n < 2; ++n) _Pragma("unroll") for (int k = 0; k < 2; ++k) dst[n][k] = *(const LAS bf16x8*)(lds + PG8_SB(b, h) + boff + n * 2048 + k * 1024); } while (0)
; #define PG8_MMA(ai, bj, At, Bt) do { __builtin_amdgcn_s_setprio(1); _Pragma("unroll") for (int k = 0; k < 2; ++k) _Pragma("unroll") for (int m = 0; m < 4; ++m) _Pragma("unroll") for (int n = 0; n < ((bj) == 1 ? NB1 : 2); ++n) \
;         acc[ai][bj][m][n] = __builtin_amdgcn_mfma_f32_16x16x32_bf16(Bt[n][k], At[m][k], acc[ai][bj][m][n], 0, 0, 0); __builtin_amdgcn_s_setprio(0); } while (0)
; #define PG8_WAIT_V(n) asm volatile("s_waitcnt vmcnt(" #n ")" ::: "memory")
; #define PG8_WAIT_L(n) asm volatile("s_waitcnt lgkmcnt(" #n ")" ::: "memory")
; #define PG8_BAR __builtin_amdgcn_s_barrier()
;     ...
;         for (int t = 0; t < nt; t += 2) {
;             const bool last = (t == nt - 2);
;             const char* a1 = cA + (size_t)(t + 1) * kstep;
;             const char* a2 = last ? nA : cA + (size_t)(t + 2) * kstep; const char* b2 = last ? nB : cB + (size_t)(t + 2) * kstep;
;             const char* a3 = a2 + kstep; const char* b3 = b2 + kstep;
;             PG8_LDB(B0, 0, 0); PG8_SCHED; PG8_LDA(At, 0, 0); PG8_STAGE(PG8_SA(1, 1), a1 + hstepA, voffA);
;             PG8_WAIT_L(8); PG8_BAR; PG8_WAIT_L(0); PG8_MMA(0, 0, At, B0); PG8_BAR; PG8_SCHED;
;             PG8_LDB(B1, 0, 1); PG8_STAGE(PG8_SB(0, 0), b2, voffB);
;             PG8_BAR; PG8_WAIT_L(0); PG8_MMA(0, 1, At, B1); PG8_BAR;
;             PG8_LDA(At, 0, 1); PG8_STAGE(PG8_SA(0, 0), a2, voffA);
;             PG8_BAR; PG8_WAIT_L(0); PG8_MMA(1, 0, At, B0); PG8_BAR; PG8_SCHED;
;             PG8_STAGE(PG8_SB(0, 1), b2 + hstepB, voffB);
;             PG8_WAIT_V(6); PG8_BAR; PG8_MMA(1, 1, At, B1); PG8_BAR;
.Lkrot_844:
	s_add_i32 vcc_lo, s16, 2
	s_cmp_eq_u32 s87, s16
	s_cselect_b32 s36, s23, s94
	s_cselect_b32 s26, s22, s95
	s_cselect_b32 s27, s53, s97
	s_cselect_b32 s28, s59, s96
	s_add_u32 s24, s36, 0x80
	s_addc_u32 s25, s26, 0
	s_add_u32 s16, s94, s0
	s_addc_u32 s17, s95, s1
	s_add_u32 s16, s16, 0xffffff80
	s_addc_u32 s17, s17, -1
	s_and_b32 s17, s17, 0xffff
	s_mov_b32 m0, s88
	ds_read_b128 v[130:133], v142
	ds_read_b128 v[150:153], v142 offset:1024
	ds_read_b128 v[154:157], v142 offset:2048
	ds_read_b128 v[158:161], v142 offset:3072
	ds_read_b128 v[162:165], v142 offset:4096
	ds_read_b128 v[166:169], v142 offset:5120
	ds_read_b128 v[170:173], v142 offset:6144
	ds_read_b128 v[174:177], v142 offset:7168
	buffer_load_dwordx4 v134, s[16:19], 0 offen lds
	s_mov_b32 m0, s89
	s_nop 0
	buffer_load_dwordx4 v136, s[16:19], 0 offen lds
	s_waitcnt lgkmcnt(8)
	s_barrier
	s_waitcnt lgkmcnt(0)
	s_setprio 1
	s_waitcnt lgkmcnt(7)
	v_mfma_f32_16x16x32_bf16 v[88:91], v[100:103], v[130:133], v[88:91]
	v_mfma_f32_16x16x32_bf16 v[96:99], v[122:125], v[130:133], v[96:99]
	s_waitcnt lgkmcnt(5)
	v_mfma_f32_16x16x32_bf16 v[76:79], v[100:103], v[154:157], v[76:79]
	v_mfma_f32_16x16x32_bf16 v[84:87], v[122:125], v[154:157], v[84:87]
	s_waitcnt lgkmcnt(3)
	v_mfma_f32_16x16x32_bf16 v[64:67], v[100:103], v[162:165], v[64:67]
	v_mfma_f32_16x16x32_bf16 v[72:75], v[122:125], v[162:165], v[72:75]
	s_waitcnt lgkmcnt(1)
	v_mfma_f32_16x16x32_bf16 v[52:55], v[100:103], v[170:173], v[52:55]
	v_mfma_f32_16x16x32_bf16 v[60:63], v[122:125], v[170:173], v[60:63]
	v_mfma_f32_16x16x32_bf16 v[88:91], v[104:107], v[150:153], v[88:91]
	v_mfma_f32_16x16x32_bf16 v[96:99], v[126:129], v[150:153], v[96:99]
	v_mfma_f32_16x16x32_bf16 v[76:79], v[104:107], v[158:161], v[76:79]
	v_mfma_f32_16x16x32_bf16 v[84:87], v[126:129], v[158:161], v[84:87]
	v_mfma_f32_16x16x32_bf16 v[64:67], v[104:107], v[166:169], v[64:67]
	v_mfma_f32_16x16x32_bf16 v[72:75], v[126:129], v[166:169], v[72:75]
	s_waitcnt lgkmcnt(0)
	v_mfma_f32_16x16x32_bf16 v[52:55], v[104:107], v[174:177], v[52:55]
	v_mfma_f32_16x16x32_bf16 v[60:63], v[126:129], v[174:177], v[60:63]
	s_setprio 0
	s_barrier
	s_and_b32 s29, s27, 0xffff
	s_mov_b32 s30, s18
	s_mov_b32 s31, s19
	s_mov_b32 m0, s73
	ds_read_b128 v[178:181], v143
	ds_read_b128 v[182:185], v143 offset:1024
	buffer_load_dwordx4 v135, s[28:31], 0 offen lds
	s_mov_b32 m0, s74
	s_nop 0
	buffer_load_dwordx4 v137, s[28:31], 0 offen lds
	s_barrier
	s_waitcnt lgkmcnt(0)
	s_setprio 1
	s_waitcnt lgkmcnt(1)
	v_mfma_f32_16x16x32_bf16 v[92:95], v[178:181], v[130:133], v[92:95]
	v_mfma_f32_16x16x32_bf16 v[80:83], v[178:181], v[154:157], v[80:83]
	v_mfma_f32_16x16x32_bf16 v[68:71], v[178:181], v[162:165], v[68:71]
	v_mfma_f32_16x16x32_bf16 v[56:59], v[178:181], v[170:173], v[56:59]
	s_waitcnt lgkmcnt(0)
	v_mfma_f32_16x16x32_bf16 v[92:95], v[182:185], v[150:153], v[92:95]
	v_mfma_f32_16x16x32_bf16 v[80:83], v[182:185], v[158:161], v[80:83]
	v_mfma_f32_16x16x32_bf16 v[68:71], v[182:185], v[166:169], v[68:71]
	v_mfma_f32_16x16x32_bf16 v[56:59], v[182:185], v[174:177], v[56:59]
	s_setprio 0
	s_and_b32 s37, s26, 0xffff
	s_mov_b32 s38, s18
	s_mov_b32 s39, s19
	s_mov_b32 m0, s71
	s_barrier
	ds_read_b128 v[130:133], v142 offset:16384
	ds_read_b128 v[150:153], v142 offset:17408
	ds_read_b128 v[154:157], v142 offset:18432
	ds_read_b128 v[158:161], v142 offset:19456
	ds_read_b128 v[162:165], v142 offset:20480
	ds_read_b128 v[166:169], v142 offset:21504
	ds_read_b128 v[170:173], v142 offset:22528
	ds_read_b128 v[174:177], v142 offset:23552
	buffer_load_dwordx4 v134, s[36:39], 0 offen lds
	s_mov_b32 m0, s75
	s_nop 0
	buffer_load_dwordx4 v136, s[36:39], 0 offen lds
	s_waitcnt vmcnt(8)
	s_barrier
	s_waitcnt lgkmcnt(0)
	s_setprio 1
	s_waitcnt lgkmcnt(7)
	v_mfma_f32_16x16x32_bf16 v[44:47], v[100:103], v[130:133], v[44:47]
	v_mfma_f32_16x16x32_bf16 v[48:51], v[122:125], v[130:133], v[48:51]
	s_waitcnt lgkmcnt(5)
	v_mfma_f32_16x16x32_bf16 v[28:31], v[100:103], v[154:157], v[28:31]
	v_mfma_f32_16x16x32_bf16 v[36:39], v[122:125], v[154:157], v[36:39]
	s_waitcnt lgkmcnt(3)
	v_mfma_f32_16x16x32_bf16 v[12:15], v[100:103], v[162:165], v[12:15]
	v_mfma_f32_16x16x32_bf16 v[20:23], v[122:125], v[162:165], v[20:23]
	s_waitcnt lgkmcnt(1)
	v_mfma_f32_16x16x32_bf16 v[0:3], v[100:103], v[170:173], v[0:3]
	v_mfma_f32_16x16x32_bf16 v[8:11], v[122:125], v[170:173], v[8:11]
	v_mfma_f32_16x16x32_bf16 v[44:47], v[104:107], v[150:153], v[44:47]
	v_mfma_f32_16x16x32_bf16 v[48:51], v[126:129], v[150:153], v[48:51]
	v_mfma_f32_16x16x32_bf16 v[28:31], v[104:107], v[158:161], v[28:31]
	v_mfma_f32_16x16x32_bf16 v[36:39], v[126:129], v[158:161], v[36:39]
	v_mfma_f32_16x16x32_bf16 v[12:15], v[104:107], v[166:169], v[12:15]
	v_mfma_f32_16x16x32_bf16 v[20:23], v[126:129], v[166:169], v[20:23]
	s_waitcnt lgkmcnt(0)
	v_mfma_f32_16x16x32_bf16 v[0:3], v[104:107], v[174:177], v[0:3]
	v_mfma_f32_16x16x32_bf16 v[8:11], v[126:129], v[174:177], v[8:11]
	s_setprio 0
	s_barrier
	ds_read_b128 v[100:103], v144
	ds_read_b128 v[104:107], v144 offset:1024
	ds_read_b128 v[122:125], v144 offset:2048
	ds_read_b128 v[126:129], v144 offset:3072
	s_add_u32 s16, s28, s44
	s_addc_u32 vcc_hi, s27, s45
	s_and_b32 s17, vcc_hi, 0xffff
	s_mov_b32 m0, s76
	s_nop 0
	buffer_load_dwordx4 v135, s[16:19], 0 offen lds
	s_mov_b32 m0, s77
	s_nop 0
	buffer_load_dwordx4 v137, s[16:19], 0 offen lds
	s_waitcnt vmcnt(6)
	s_barrier
; #define PG8_STAGE(bufoff, gbase, voff) do { const __amdgpu_buffer_rsrc_t _r = __builtin_amdgcn_make_buffer_rsrc((void*)(gbase), (short)0, 0x7fffffff, 0x00020000); _Pragma("unroll") for (int _i = 0; _i < 2; ++_i) \
;         __builtin_amdgcn_raw_ptr_buffer_load_lds(_r, (LAS unsigned*)(lds + (bufoff) + ldsw + _i * 8192), 16, (int)(voff)[_i], 0, 0, 0); } while (0)
; #define PG8_LDA(dst, b, h) do { _Pragma("unroll") for (int m = 0; m < 4; ++m) _Pragma("unroll") for (int k = 0; k < 2; ++k) dst[m][k] = *(const LAS bf16x8*)(lds + PG8_SA(b, h) + aoff + m * 2048 + k * 1024); } while (0)
; #define PG8_LDB(dst, b, h) do { _Pragma("unroll") for (int n = 0; n < 2; ++n) _Pragma("unroll") for (int k = 0; k < 2; ++k) dst[n][k] = *(const LAS bf16x8*)(lds + PG8_SB(b, h) + boff + n * 2048 + k * 1024); } while (0)
; #define PG8_MMA(ai, bj, At, Bt) do { __builtin_amdgcn_s_setprio(1); _Pragma("unroll") for (int k = 0; k < 2; ++k) _Pragma("unroll") for (int m = 0; m < 4; ++m) _Pragma("unroll") for (int n = 0; n < ((bj) == 1 ? NB1 : 2); ++n) \
;         acc[ai][bj][m][n] = __builtin_amdgcn_mfma_f32_16x16x32_bf16(Bt[n][k], At[m][k], acc[ai][bj][m][n], 0, 0, 0); __builtin_amdgcn_s_setprio(0); } while (0)
; #define PG8_WAIT_V(n) asm volatile("s_waitcnt vmcnt(" #n ")" ::: "memory")
; #define PG8_WAIT_L(n) asm volatile("s_waitcnt lgkmcnt(" #n ")" ::: "memory")
; #define PG8_BAR __builtin_amdgcn_s_barrier()
; #define PG8_SCHED __builtin_amdgcn_sched_barrier(0)
;     ...
;             PG8_WAIT_V(6); PG8_BAR; PG8_MMA(1, 1, At, B1); PG8_BAR;
;             PG8_LDB(B0, 1, 0); PG8_SCHED; PG8_LDA(At, 1, 0); PG8_STAGE(PG8_SA(0, 1), a2 + hstepA, voffA);
;             PG8_WAIT_L(8); PG8_BAR; PG8_WAIT_L(0); PG8_MMA(0, 0, At, B0); PG8_BAR; PG8_SCHED;
;             PG8_LDB(B1, 1, 1); PG8_STAGE(PG8_SB(1, 0), b3, voffB);
;             PG8_BAR; PG8_WAIT_L(0); PG8_MMA(0, 1, At, B1); PG8_BAR;
;             PG8_LDA(At, 1, 1); PG8_STAGE(PG8_SA(1, 0), a3, voffA);
;             PG8_BAR; PG8_WAIT_L(0); PG8_MMA(1, 0, At, B0); PG8_BAR; PG8_SCHED;
;             PG8_STAGE(PG8_SB(1, 1), b3 + hstepB, voffB);
;             PG8_WAIT_V(6); PG8_BAR; PG8_MMA(1, 1, At, B1); PG8_BAR;
;         }
	s_setprio 1
	v_mfma_f32_16x16x32_bf16 v[40:43], v[178:181], v[130:133], v[40:43]
	v_mfma_f32_16x16x32_bf16 v[32:35], v[178:181], v[154:157], v[32:35]
	v_mfma_f32_16x16x32_bf16 v[16:19], v[178:181], v[162:165], v[16:19]
	v_mfma_f32_16x16x32_bf16 v[4:7], v[178:181], v[170:173], v[4:7]
	v_mfma_f32_16x16x32_bf16 v[40:43], v[182:185], v[150:153], v[40:43]
	v_mfma_f32_16x16x32_bf16 v[32:35], v[182:185], v[158:161], v[32:35]
	v_mfma_f32_16x16x32_bf16 v[16:19], v[182:185], v[166:169], v[16:19]
	v_mfma_f32_16x16x32_bf16 v[4:7], v[182:185], v[174:177], v[4:7]
	s_setprio 0
	s_barrier
	s_add_u32 s36, s36, s0
	s_addc_u32 s17, s26, s1
	s_and_b32 s37, s17, 0xffff
	s_mov_b32 m0, s78
	ds_read_b128 v[130:133], v142 offset:32768
	ds_read_b128 v[150:153], v142 offset:33792
	ds_read_b128 v[154:157], v142 offset:34816
	ds_read_b128 v[158:161], v142 offset:35840
	ds_read_b128 v[162:165], v142 offset:36864
	ds_read_b128 v[166:169], v142 offset:37888
	ds_read_b128 v[170:173], v142 offset:38912
	ds_read_b128 v[174:177], v142 offset:39936
	buffer_load_dwordx4 v134, s[36:39], 0 offen lds
	s_mov_b32 m0, s79
	s_nop 0
	buffer_load_dwordx4 v136, s[36:39], 0 offen lds
	s_waitcnt lgkmcnt(8)
	s_barrier
	s_waitcnt lgkmcnt(0)
	s_setprio 1
	s_waitcnt lgkmcnt(7)
	v_mfma_f32_16x16x32_bf16 v[88:91], v[100:103], v[130:133], v[88:91]
	v_mfma_f32_16x16x32_bf16 v[96:99], v[122:125], v[130:133], v[96:99]
	s_waitcnt lgkmcnt(5)
	v_mfma_f32_16x16x32_bf16 v[76:79], v[100:103], v[154:157], v[76:79]
	v_mfma_f32_16x16x32_bf16 v[84:87], v[122:125], v[154:157], v[84:87]
	s_waitcnt lgkmcnt(3)
	v_mfma_f32_16x16x32_bf16 v[64:67], v[100:103], v[162:165], v[64:67]
	v_mfma_f32_16x16x32_bf16 v[72:75], v[122:125], v[162:165], v[72:75]
	s_waitcnt lgkmcnt(1)
	v_mfma_f32_16x16x32_bf16 v[52:55], v[100:103], v[170:173], v[52:55]
	v_mfma_f32_16x16x32_bf16 v[60:63], v[122:125], v[170:173], v[60:63]
	v_mfma_f32_16x16x32_bf16 v[88:91], v[104:107], v[150:153], v[88:91]
	v_mfma_f32_16x16x32_bf16 v[96:99], v[126:129], v[150:153], v[96:99]
	v_mfma_f32_16x16x32_bf16 v[76:79], v[104:107], v[158:161], v[76:79]
	v_mfma_f32_16x16x32_bf16 v[84:87], v[126:129], v[158:161], v[84:87]
	v_mfma_f32_16x16x32_bf16 v[64:67], v[104:107], v[166:169], v[64:67]
	v_mfma_f32_16x16x32_bf16 v[72:75], v[126:129], v[166:169], v[72:75]
	s_waitcnt lgkmcnt(0)
	v_mfma_f32_16x16x32_bf16 v[52:55], v[104:107], v[174:177], v[52:55]
	v_mfma_f32_16x16x32_bf16 v[60:63], v[126:129], v[174:177], v[60:63]
	s_setprio 0
	s_barrier
	s_add_u32 s28, s28, 0x80
	s_addc_u32 s17, s27, 0
	s_and_b32 s29, s17, 0xffff
	s_mov_b32 m0, s81
	ds_read_b128 v[178:181], v145
	ds_read_b128 v[182:185], v145 offset:1024
	buffer_load_dwordx4 v135, s[28:31], 0 offen lds
	s_mov_b32 m0, s82
	s_nop 0
	buffer_load_dwordx4 v137, s[28:31], 0 offen lds
	s_barrier
	s_waitcnt lgkmcnt(0)
	s_setprio 1
	s_waitcnt lgkmcnt(1)
	v_mfma_f32_16x16x32_bf16 v[92:95], v[178:181], v[130:133], v[92:95]
	v_mfma_f32_16x16x32_bf16 v[80:83], v[178:181], v[154:157], v[80:83]
	v_mfma_f32_16x16x32_bf16 v[68:71], v[178:181], v[162:165], v[68:71]
	v_mfma_f32_16x16x32_bf16 v[56:59], v[178:181], v[170:173], v[56:59]
	s_waitcnt lgkmcnt(0)
	v_mfma_f32_16x16x32_bf16 v[92:95], v[182:185], v[150:153], v[92:95]
	v_mfma_f32_16x16x32_bf16 v[80:83], v[182:185], v[158:161], v[80:83]
	v_mfma_f32_16x16x32_bf16 v[68:71], v[182:185], v[166:169], v[68:71]
	v_mfma_f32_16x16x32_bf16 v[56:59], v[182:185], v[174:177], v[56:59]
	s_setprio 0
	s_and_b32 s25, s25, 0xffff
	s_mov_b32 s26, s18
	s_mov_b32 s27, s19
	s_mov_b32 m0, s83
	s_barrier
	ds_read_b128 v[130:133], v142 offset:49152
	ds_read_b128 v[150:153], v142 offset:50176
	ds_read_b128 v[154:157], v142 offset:51200
	ds_read_b128 v[158:161], v142 offset:52224
	ds_read_b128 v[162:165], v142 offset:53248
	ds_read_b128 v[166:169], v142 offset:54272
	ds_read_b128 v[170:173], v142 offset:55296
	ds_read_b128 v[174:177], v142 offset:56320
	buffer_load_dwordx4 v134, s[24:27], 0 offen lds
	s_mov_b32 m0, s84
	s_nop 0
	buffer_load_dwordx4 v136, s[24:27], 0 offen lds
	s_waitcnt vmcnt(8)
	s_barrier
	s_waitcnt lgkmcnt(0)
	s_setprio 1
	s_waitcnt lgkmcnt(7)
	v_mfma_f32_16x16x32_bf16 v[44:47], v[100:103], v[130:133], v[44:47]
	v_mfma_f32_16x16x32_bf16 v[48:51], v[122:125], v[130:133], v[48:51]
	s_waitcnt lgkmcnt(5)
	v_mfma_f32_16x16x32_bf16 v[28:31], v[100:103], v[154:157], v[28:31]
	v_mfma_f32_16x16x32_bf16 v[36:39], v[122:125], v[154:157], v[36:39]
	s_waitcnt lgkmcnt(3)
	v_mfma_f32_16x16x32_bf16 v[12:15], v[100:103], v[162:165], v[12:15]
	v_mfma_f32_16x16x32_bf16 v[20:23], v[122:125], v[162:165], v[20:23]
	s_waitcnt lgkmcnt(1)
	v_mfma_f32_16x16x32_bf16 v[0:3], v[100:103], v[170:173], v[0:3]
	v_mfma_f32_16x16x32_bf16 v[8:11], v[122:125], v[170:173], v[8:11]
	v_mfma_f32_16x16x32_bf16 v[44:47], v[104:107], v[150:153], v[44:47]
	v_mfma_f32_16x16x32_bf16 v[48:51], v[126:129], v[150:153], v[48:51]
	v_mfma_f32_16x16x32_bf16 v[28:31], v[104:107], v[158:161], v[28:31]
	v_mfma_f32_16x16x32_bf16 v[36:39], v[126:129], v[158:161], v[36:39]
	v_mfma_f32_16x16x32_bf16 v[12:15], v[104:107], v[166:169], v[12:15]
	v_mfma_f32_16x16x32_bf16 v[20:23], v[126:129], v[166:169], v[20:23]
	s_waitcnt lgkmcnt(0)
	v_mfma_f32_16x16x32_bf16 v[0:3], v[104:107], v[174:177], v[0:3]
	v_mfma_f32_16x16x32_bf16 v[8:11], v[126:129], v[174:177], v[8:11]
	s_setprio 0
	s_barrier
	ds_read_b128 v[100:103], v141
	ds_read_b128 v[104:107], v141 offset:1024
	ds_read_b128 v[122:125], v141 offset:2048
	ds_read_b128 v[126:129], v141 offset:3072
	s_add_u32 s16, s16, 0x80
	s_addc_u32 s17, vcc_hi, 0
	s_and_b32 s17, s17, 0xffff
	s_mov_b32 m0, s85
	s_nop 0
	buffer_load_dwordx4 v135, s[16:19], 0 offen lds
	s_mov_b32 m0, s86
	s_nop 0
	buffer_load_dwordx4 v137, s[16:19], 0 offen lds
	s_waitcnt vmcnt(6)
	s_barrier
	s_setprio 1
	v_mfma_f32_16x16x32_bf16 v[40:43], v[178:181], v[130:133], v[40:43]
	v_mfma_f32_16x16x32_bf16 v[32:35], v[178:181], v[154:157], v[32:35]
	v_mfma_f32_16x16x32_bf16 v[16:19], v[178:181], v[162:165], v[16:19]
	v_mfma_f32_16x16x32_bf16 v[4:7], v[178:181], v[170:173], v[4:7]
	v_mfma_f32_16x16x32_bf16 v[40:43], v[182:185], v[150:153], v[40:43]
	v_mfma_f32_16x16x32_bf16 v[32:35], v[182:185], v[158:161], v[32:35]
	v_mfma_f32_16x16x32_bf16 v[16:19], v[182:185], v[166:169], v[16:19]
	v_mfma_f32_16x16x32_bf16 v[4:7], v[182:185], v[174:177], v[4:7]
	s_setprio 0
	s_add_u32 s94, s94, 0x100
	s_addc_u32 s95, s95, 0
	s_add_u32 s96, s96, 0x100
	s_addc_u32 s97, s97, 0
	s_cmp_ge_i32 vcc_lo, s80
	s_mov_b32 s16, vcc_lo
	s_barrier
	s_cbranch_scc0 .Lkrot_844
	s_waitcnt lgkmcnt(0)
	v_readlane_b32 s96, v252, 38
	v_readlane_b32 s97, v252, 39

; #define PG8_STAGE(bufoff, gbase, voff) do { const __amdgpu_buffer_rsrc_t _r = __builtin_amdgcn_make_buffer_rsrc((void*)(gbase), (short)0, 0x7fffffff, 0x00020000); _Pragma("unroll") for (int _i = 0; _i < 2; ++_i) \
;         __builtin_amdgcn_raw_ptr_buffer_load_lds(_r, (LAS unsigned*)(lds + (bufoff) + ldsw + _i * 8192), 16, (int)(voff)[_i], 0, 0, 0); } while (0)
; #define PG8_LDA(dst, b, h) do { _Pragma("unroll") for (int m = 0; m < 4; ++m) _Pragma("unroll") for (int k = 0; k < 2; ++k) dst[m][k] = *(const LAS bf16x8*)(lds + PG8_SA(b, h) + aoff + m * 2048 + k * 1024); } while (0)
; #define PG8_LDB(dst, b, h) do { _Pragma("unroll") for (int n = 0; n < 2; ++n) _Pragma("unroll") for (int k = 0; k < 2; ++k) dst[n][k] = *(const LAS bf16x8*)(lds + PG8_SB(b, h) + boff + n * 2048 + k * 1024); } while (0)
; #define PG8_MMA(ai, bj, At, Bt) do { __builtin_amdgcn_s_setprio(1); _Pragma("unroll") for (int k = 0; k < 2; ++k) _Pragma("unroll") for (int m = 0; m < 4; ++m) _Pragma("unroll") for (int n = 0; n < ((bj) == 1 ? NB1 : 2); ++n) \
;         acc[ai][bj][m][n] = __builtin_amdgcn_mfma_f32_16x16x32_bf16(Bt[n][k], At[m][k], acc[ai][bj][m][n], 0, 0, 0); __builtin_amdgcn_s_setprio(0); } while (0)
; #define PG8_WAIT_V(n) asm volatile("s_waitcnt vmcnt(" #n ")" ::: "memory")
; #define PG8_WAIT_L(n) asm volatile("s_waitcnt lgkmcnt(" #n ")" ::: "memory")
; #define PG8_BAR __builtin_amdgcn_s_barrier()
;     ...
;         for (int t = 0; t < nt; t += 2) {
;             const bool last = (t == nt - 2);
;             const char* a1 = cA + (size_t)(t + 1) * kstep;
;             const char* a2 = last ? nA : cA + (size_t)(t + 2) * kstep; const char* b2 = last ? nB : cB + (size_t)(t + 2) * kstep;
;             const char* a3 = a2 + kstep; const char* b3 = b2 + kstep;
;             PG8_LDB(B0, 0, 0); PG8_SCHED; PG8_LDA(At, 0, 0); PG8_STAGE(PG8_SA(1, 1), a1 + hstepA, voffA);
;             PG8_WAIT_L(8); PG8_BAR; PG8_WAIT_L(0); PG8_MMA(0, 0, At, B0); PG8_BAR; PG8_SCHED;
;             PG8_LDB(B1, 0, 1); PG8_STAGE(PG8_SB(0, 0), b2, voffB);
;             PG8_BAR; PG8_WAIT_L(0); PG8_MMA(0, 1, At, B1); PG8_BAR;
;             PG8_LDA(At, 0, 1); PG8_STAGE(PG8_SA(0, 0), a2, voffA);
;             PG8_BAR; PG8_WAIT_L(0); PG8_MMA(1, 0, At, B0); PG8_BAR; PG8_SCHED;
;             PG8_STAGE(PG8_SB(0, 1), b2 + hstepB, voffB);
;             PG8_WAIT_V(6); PG8_BAR; PG8_MMA(1, 1, At, B1); PG8_BAR;
.Lkrot_922:
	s_add_i32 s22, s8, 2
	s_cmp_eq_u32 s87, s8
	s_cselect_b32 s28, s1, s91
	s_cselect_b32 s19, s0, s92
	s_cselect_b32 s18, s49, s94
	s_cselect_b32 s24, s51, s93
	s_add_u32 s16, s28, 0x80
	s_addc_u32 s17, s19, 0
	s_add_u32 s8, s91, s36
	s_addc_u32 s9, s92, s37
	s_add_u32 s8, s8, 0xffffff80
	s_addc_u32 s9, s9, -1
	s_and_b32 s9, s9, 0xffff
	s_mov_b32 m0, s88
	ds_read_b128 v[144:147], v228
	ds_read_b128 v[148:151], v228 offset:1024
	ds_read_b128 v[152:155], v228 offset:2048
	ds_read_b128 v[156:159], v228 offset:3072
	ds_read_b128 v[160:163], v228 offset:4096
	ds_read_b128 v[164:167], v228 offset:5120
	ds_read_b128 v[168:171], v228 offset:6144
	ds_read_b128 v[172:175], v228 offset:7168
	buffer_load_dwordx4 v222, s[8:11], 0 offen lds
	s_mov_b32 m0, s89
	s_nop 0
	buffer_load_dwordx4 v224, s[8:11], 0 offen lds
	s_waitcnt lgkmcnt(8)
	s_barrier
	s_waitcnt lgkmcnt(0)
	s_setprio 1
	s_waitcnt lgkmcnt(7)
	v_mfma_f32_16x16x32_bf16 v[120:123], v[128:131], v[144:147], v[120:123]
	v_mfma_f32_16x16x32_bf16 v[124:127], v[136:139], v[144:147], v[124:127]
	s_waitcnt lgkmcnt(5)
	v_mfma_f32_16x16x32_bf16 v[108:111], v[128:131], v[152:155], v[108:111]
	v_mfma_f32_16x16x32_bf16 v[104:107], v[136:139], v[152:155], v[104:107]
	s_waitcnt lgkmcnt(3)
	v_mfma_f32_16x16x32_bf16 v[92:95], v[128:131], v[160:163], v[92:95]
	v_mfma_f32_16x16x32_bf16 v[88:91], v[136:139], v[160:163], v[88:91]
	s_waitcnt lgkmcnt(1)
	v_mfma_f32_16x16x32_bf16 v[76:79], v[128:131], v[168:171], v[76:79]
	v_mfma_f32_16x16x32_bf16 v[72:75], v[136:139], v[168:171], v[72:75]
	v_mfma_f32_16x16x32_bf16 v[120:123], v[132:135], v[148:151], v[120:123]
	v_mfma_f32_16x16x32_bf16 v[124:127], v[140:143], v[148:151], v[124:127]
	v_mfma_f32_16x16x32_bf16 v[108:111], v[132:135], v[156:159], v[108:111]
	v_mfma_f32_16x16x32_bf16 v[104:107], v[140:143], v[156:159], v[104:107]
	v_mfma_f32_16x16x32_bf16 v[92:95], v[132:135], v[164:167], v[92:95]
	v_mfma_f32_16x16x32_bf16 v[88:91], v[140:143], v[164:167], v[88:91]
	s_waitcnt lgkmcnt(0)
	v_mfma_f32_16x16x32_bf16 v[76:79], v[132:135], v[172:175], v[76:79]
	v_mfma_f32_16x16x32_bf16 v[72:75], v[140:143], v[172:175], v[72:75]
	s_setprio 0
	s_barrier
	s_and_b32 s25, s18, 0xffff
	s_mov_b32 s26, s10
	s_mov_b32 s27, s11
	s_mov_b32 m0, s67
	ds_read_b128 v[176:179], v229
	ds_read_b128 v[180:183], v229 offset:1024
	ds_read_b128 v[192:195], v229 offset:2048
	ds_read_b128 v[196:199], v229 offset:3072
	buffer_load_dwordx4 v223, s[24:27], 0 offen lds
	s_mov_b32 m0, s74
	s_nop 0
	buffer_load_dwordx4 v225, s[24:27], 0 offen lds
	s_barrier
	s_waitcnt lgkmcnt(0)
	s_setprio 1
	s_waitcnt lgkmcnt(3)
	v_mfma_f32_16x16x32_bf16 v[116:119], v[176:179], v[144:147], v[116:119]
	s_waitcnt lgkmcnt(1)
	v_mfma_f32_16x16x32_bf16 v[112:115], v[192:195], v[144:147], v[112:115]
	v_mfma_f32_16x16x32_bf16 v[100:103], v[176:179], v[152:155], v[100:103]
	v_mfma_f32_16x16x32_bf16 v[96:99], v[192:195], v[152:155], v[96:99]
	v_mfma_f32_16x16x32_bf16 v[84:87], v[176:179], v[160:163], v[84:87]
	v_mfma_f32_16x16x32_bf16 v[80:83], v[192:195], v[160:163], v[80:83]
	v_mfma_f32_16x16x32_bf16 v[68:71], v[176:179], v[168:171], v[68:71]
	v_mfma_f32_16x16x32_bf16 v[64:67], v[192:195], v[168:171], v[64:67]
	v_mfma_f32_16x16x32_bf16 v[116:119], v[180:183], v[148:151], v[116:119]
	s_waitcnt lgkmcnt(0)
	v_mfma_f32_16x16x32_bf16 v[112:115], v[196:199], v[148:151], v[112:115]
	v_mfma_f32_16x16x32_bf16 v[100:103], v[180:183], v[156:159], v[100:103]
	v_mfma_f32_16x16x32_bf16 v[96:99], v[196:199], v[156:159], v[96:99]
	v_mfma_f32_16x16x32_bf16 v[84:87], v[180:183], v[164:167], v[84:87]
	v_mfma_f32_16x16x32_bf16 v[80:83], v[196:199], v[164:167], v[80:83]
	v_mfma_f32_16x16x32_bf16 v[68:71], v[180:183], v[172:175], v[68:71]
	v_mfma_f32_16x16x32_bf16 v[64:67], v[196:199], v[172:175], v[64:67]
	s_setprio 0
	s_and_b32 s29, s19, 0xffff
	s_mov_b32 s30, s10
	s_mov_b32 s31, s11
	s_mov_b32 m0, s65
	s_barrier
	ds_read_b128 v[144:147], v228 offset:16384
	ds_read_b128 v[148:151], v228 offset:17408
	ds_read_b128 v[152:155], v228 offset:18432
	ds_read_b128 v[156:159], v228 offset:19456
	ds_read_b128 v[160:163], v228 offset:20480
	ds_read_b128 v[164:167], v228 offset:21504
	ds_read_b128 v[168:171], v228 offset:22528
	ds_read_b128 v[172:175], v228 offset:23552
	buffer_load_dwordx4 v222, s[28:31], 0 offen lds
	s_mov_b32 m0, s75
	s_nop 0
	buffer_load_dwordx4 v224, s[28:31], 0 offen lds
	s_waitcnt vmcnt(8)
	s_barrier
	s_waitcnt lgkmcnt(0)
	s_setprio 1
	s_waitcnt lgkmcnt(7)
	v_mfma_f32_16x16x32_bf16 v[60:63], v[128:131], v[144:147], v[60:63]
	v_mfma_f32_16x16x32_bf16 v[56:59], v[136:139], v[144:147], v[56:59]
	s_waitcnt lgkmcnt(5)
	v_mfma_f32_16x16x32_bf16 v[44:47], v[128:131], v[152:155], v[44:47]
	v_mfma_f32_16x16x32_bf16 v[40:43], v[136:139], v[152:155], v[40:43]
	s_waitcnt lgkmcnt(3)
	v_mfma_f32_16x16x32_bf16 v[28:31], v[128:131], v[160:163], v[28:31]
	v_mfma_f32_16x16x32_bf16 v[24:27], v[136:139], v[160:163], v[24:27]
	s_waitcnt lgkmcnt(1)
	v_mfma_f32_16x16x32_bf16 v[12:15], v[128:131], v[168:171], v[12:15]
	v_mfma_f32_16x16x32_bf16 v[8:11], v[136:139], v[168:171], v[8:11]
	v_mfma_f32_16x16x32_bf16 v[60:63], v[132:135], v[148:151], v[60:63]
	v_mfma_f32_16x16x32_bf16 v[56:59], v[140:143], v[148:151], v[56:59]
	v_mfma_f32_16x16x32_bf16 v[44:47], v[132:135], v[156:159], v[44:47]
	v_mfma_f32_16x16x32_bf16 v[40:43], v[140:143], v[156:159], v[40:43]
	v_mfma_f32_16x16x32_bf16 v[28:31], v[132:135], v[164:167], v[28:31]
	v_mfma_f32_16x16x32_bf16 v[24:27], v[140:143], v[164:167], v[24:27]
	s_waitcnt lgkmcnt(0)
	v_mfma_f32_16x16x32_bf16 v[12:15], v[132:135], v[172:175], v[12:15]
	v_mfma_f32_16x16x32_bf16 v[8:11], v[140:143], v[172:175], v[8:11]
	s_setprio 0
	s_barrier
; #define PG8_STAGE(bufoff, gbase, voff) do { const __amdgpu_buffer_rsrc_t _r = __builtin_amdgcn_make_buffer_rsrc((void*)(gbase), (short)0, 0x7fffffff, 0x00020000); _Pragma("unroll") for (int _i = 0; _i < 2; ++_i) \
;         __builtin_amdgcn_raw_ptr_buffer_load_lds(_r, (LAS unsigned*)(lds + (bufoff) + ldsw + _i * 8192), 16, (int)(voff)[_i], 0, 0, 0); } while (0)
; #define PG8_LDA(dst, b, h) do { _Pragma("unroll") for (int m = 0; m < 4; ++m) _Pragma("unroll") for (int k = 0; k < 2; ++k) dst[m][k] = *(const LAS bf16x8*)(lds + PG8_SA(b, h) + aoff + m * 2048 + k * 1024); } while (0)
; #define PG8_LDB(dst, b, h) do { _Pragma("unroll") for (int n = 0; n < 2; ++n) _Pragma("unroll") for (int k = 0; k < 2; ++k) dst[n][k] = *(const LAS bf16x8*)(lds + PG8_SB(b, h) + boff + n * 2048 + k * 1024); } while (0)
; #define PG8_MMA(ai, bj, At, Bt) do { __builtin_amdgcn_s_setprio(1); _Pragma("unroll") for (int k = 0; k < 2; ++k) _Pragma("unroll") for (int m = 0; m < 4; ++m) _Pragma("unroll") for (int n = 0; n < ((bj) == 1 ? NB1 : 2); ++n) \
;         acc[ai][bj][m][n] = __builtin_amdgcn_mfma_f32_16x16x32_bf16(Bt[n][k], At[m][k], acc[ai][bj][m][n], 0, 0, 0); __builtin_amdgcn_s_setprio(0); } while (0)
; #define PG8_WAIT_V(n) asm volatile("s_waitcnt vmcnt(" #n ")" ::: "memory")
; #define PG8_WAIT_L(n) asm volatile("s_waitcnt lgkmcnt(" #n ")" ::: "memory")
; #define PG8_BAR __builtin_amdgcn_s_barrier()
; #define PG8_SCHED __builtin_amdgcn_sched_barrier(0)
;     ...
;             PG8_WAIT_V(6); PG8_BAR; PG8_MMA(1, 1, At, B1); PG8_BAR;
;             PG8_LDB(B0, 1, 0); PG8_SCHED; PG8_LDA(At, 1, 0); PG8_STAGE(PG8_SA(0, 1), a2 + hstepA, voffA);
;             PG8_WAIT_L(8); PG8_BAR; PG8_WAIT_L(0); PG8_MMA(0, 0, At, B0); PG8_BAR; PG8_SCHED;
;             PG8_LDB(B1, 1, 1); PG8_STAGE(PG8_SB(1, 0), b3, voffB);
;             PG8_BAR; PG8_WAIT_L(0); PG8_MMA(0, 1, At, B1); PG8_BAR;
	ds_read_b128 v[128:131], v230
	ds_read_b128 v[132:135], v230 offset:1024
	ds_read_b128 v[136:139], v230 offset:2048
	ds_read_b128 v[140:143], v230 offset:3072
	s_add_u32 s8, s24, s38
	s_addc_u32 s23, s18, s39
	s_and_b32 s9, s23, 0xffff
	s_mov_b32 m0, s76
	s_nop 0
	buffer_load_dwordx4 v223, s[8:11], 0 offen lds
	s_mov_b32 m0, s77
	s_nop 0
	buffer_load_dwordx4 v225, s[8:11], 0 offen lds
	s_waitcnt vmcnt(6)
	s_barrier
	s_setprio 1
	v_mfma_f32_16x16x32_bf16 v[52:55], v[176:179], v[144:147], v[52:55]
	v_mfma_f32_16x16x32_bf16 v[48:51], v[192:195], v[144:147], v[48:51]
	v_mfma_f32_16x16x32_bf16 v[36:39], v[176:179], v[152:155], v[36:39]
	v_mfma_f32_16x16x32_bf16 v[32:35], v[192:195], v[152:155], v[32:35]
	v_mfma_f32_16x16x32_bf16 v[20:23], v[176:179], v[160:163], v[20:23]
	v_mfma_f32_16x16x32_bf16 v[16:19], v[192:195], v[160:163], v[16:19]
	v_mfma_f32_16x16x32_bf16 v[4:7], v[176:179], v[168:171], v[4:7]
	v_mfma_f32_16x16x32_bf16 v[0:3], v[192:195], v[168:171], v[0:3]
	v_mfma_f32_16x16x32_bf16 v[52:55], v[180:183], v[148:151], v[52:55]
	v_mfma_f32_16x16x32_bf16 v[48:51], v[196:199], v[148:151], v[48:51]
	v_mfma_f32_16x16x32_bf16 v[36:39], v[180:183], v[156:159], v[36:39]
	v_mfma_f32_16x16x32_bf16 v[32:35], v[196:199], v[156:159], v[32:35]
	v_mfma_f32_16x16x32_bf16 v[20:23], v[180:183], v[164:167], v[20:23]
	v_mfma_f32_16x16x32_bf16 v[16:19], v[196:199], v[164:167], v[16:19]
	v_mfma_f32_16x16x32_bf16 v[4:7], v[180:183], v[172:175], v[4:7]
	v_mfma_f32_16x16x32_bf16 v[0:3], v[196:199], v[172:175], v[0:3]
	s_setprio 0
	s_barrier
	s_add_u32 s28, s28, s36
	s_addc_u32 s9, s19, s37
	s_and_b32 s29, s9, 0xffff
	s_mov_b32 m0, s78
	ds_read_b128 v[144:147], v228 offset:32768
	ds_read_b128 v[148:151], v228 offset:33792
	ds_read_b128 v[152:155], v228 offset:34816
	ds_read_b128 v[156:159], v228 offset:35840
	ds_read_b128 v[160:163], v228 offset:36864
	ds_read_b128 v[164:167], v228 offset:37888
	ds_read_b128 v[168:171], v228 offset:38912
	ds_read_b128 v[172:175], v228 offset:39936
	buffer_load_dwordx4 v222, s[28:31], 0 offen lds
	s_mov_b32 m0, s79
	s_nop 0
	buffer_load_dwordx4 v224, s[28:31], 0 offen lds
	s_waitcnt lgkmcnt(8)
	s_barrier
	s_waitcnt lgkmcnt(0)
	s_setprio 1
	s_waitcnt lgkmcnt(7)
	v_mfma_f32_16x16x32_bf16 v[120:123], v[128:131], v[144:147], v[120:123]
	v_mfma_f32_16x16x32_bf16 v[124:127], v[136:139], v[144:147], v[124:127]
	s_waitcnt lgkmcnt(5)
	v_mfma_f32_16x16x32_bf16 v[108:111], v[128:131], v[152:155], v[108:111]
	v_mfma_f32_16x16x32_bf16 v[104:107], v[136:139], v[152:155], v[104:107]
	s_waitcnt lgkmcnt(3)
	v_mfma_f32_16x16x32_bf16 v[92:95], v[128:131], v[160:163], v[92:95]
	v_mfma_f32_16x16x32_bf16 v[88:91], v[136:139], v[160:163], v[88:91]
	s_waitcnt lgkmcnt(1)
	v_mfma_f32_16x16x32_bf16 v[76:79], v[128:131], v[168:171], v[76:79]
	v_mfma_f32_16x16x32_bf16 v[72:75], v[136:139], v[168:171], v[72:75]
	v_mfma_f32_16x16x32_bf16 v[120:123], v[132:135], v[148:151], v[120:123]
	v_mfma_f32_16x16x32_bf16 v[124:127], v[140:143], v[148:151], v[124:127]
	v_mfma_f32_16x16x32_bf16 v[108:111], v[132:135], v[156:159], v[108:111]
	v_mfma_f32_16x16x32_bf16 v[104:107], v[140:143], v[156:159], v[104:107]
	v_mfma_f32_16x16x32_bf16 v[92:95], v[132:135], v[164:167], v[92:95]
	v_mfma_f32_16x16x32_bf16 v[88:91], v[140:143], v[164:167], v[88:91]
	s_waitcnt lgkmcnt(0)
	v_mfma_f32_16x16x32_bf16 v[76:79], v[132:135], v[172:175], v[76:79]
	v_mfma_f32_16x16x32_bf16 v[72:75], v[140:143], v[172:175], v[72:75]
	s_setprio 0
	s_barrier
	s_add_u32 s24, s24, 0x80
	s_addc_u32 s9, s18, 0
	s_and_b32 s25, s9, 0xffff
	s_mov_b32 m0, s81
	ds_read_b128 v[176:179], v231
	ds_read_b128 v[180:183], v231 offset:1024
	ds_read_b128 v[192:195], v231 offset:2048
	ds_read_b128 v[196:199], v231 offset:3072
	buffer_load_dwordx4 v223, s[24:27], 0 offen lds
	s_mov_b32 m0, s82
	s_nop 0
	buffer_load_dwordx4 v225, s[24:27], 0 offen lds
	s_barrier
; #define PG8_STAGE(bufoff, gbase, voff) do { const __amdgpu_buffer_rsrc_t _r = __builtin_amdgcn_make_buffer_rsrc((void*)(gbase), (short)0, 0x7fffffff, 0x00020000); _Pragma("unroll") for (int _i = 0; _i < 2; ++_i) \
;         __builtin_amdgcn_raw_ptr_buffer_load_lds(_r, (LAS unsigned*)(lds + (bufoff) + ldsw + _i * 8192), 16, (int)(voff)[_i], 0, 0, 0); } while (0)
; #define PG8_LDA(dst, b, h) do { _Pragma("unroll") for (int m = 0; m < 4; ++m) _Pragma("unroll") for (int k = 0; k < 2; ++k) dst[m][k] = *(const LAS bf16x8*)(lds + PG8_SA(b, h) + aoff + m * 2048 + k * 1024); } while (0)
; #define PG8_MMA(ai, bj, At, Bt) do { __builtin_amdgcn_s_setprio(1); _Pragma("unroll") for (int k = 0; k < 2; ++k) _Pragma("unroll") for (int m = 0; m < 4; ++m) _Pragma("unroll") for (int n = 0; n < ((bj) == 1 ? NB1 : 2); ++n) \
;         acc[ai][bj][m][n] = __builtin_amdgcn_mfma_f32_16x16x32_bf16(Bt[n][k], At[m][k], acc[ai][bj][m][n], 0, 0, 0); __builtin_amdgcn_s_setprio(0); } while (0)
; #define PG8_WAIT_V(n) asm volatile("s_waitcnt vmcnt(" #n ")" ::: "memory")
; #define PG8_WAIT_L(n) asm volatile("s_waitcnt lgkmcnt(" #n ")" ::: "memory")
; #define PG8_BAR __builtin_amdgcn_s_barrier()
; #define PG8_SCHED __builtin_amdgcn_sched_barrier(0)
;     ...
;             PG8_BAR; PG8_WAIT_L(0); PG8_MMA(0, 1, At, B1); PG8_BAR;
;             PG8_LDA(At, 1, 1); PG8_STAGE(PG8_SA(1, 0), a3, voffA);
;             PG8_BAR; PG8_WAIT_L(0); PG8_MMA(1, 0, At, B0); PG8_BAR; PG8_SCHED;
;             PG8_STAGE(PG8_SB(1, 1), b3 + hstepB, voffB);
;             PG8_WAIT_V(6); PG8_BAR; PG8_MMA(1, 1, At, B1); PG8_BAR;
;         }
	s_waitcnt lgkmcnt(0)
	s_setprio 1
	s_waitcnt lgkmcnt(3)
	v_mfma_f32_16x16x32_bf16 v[116:119], v[176:179], v[144:147], v[116:119]
	s_waitcnt lgkmcnt(1)
	v_mfma_f32_16x16x32_bf16 v[112:115], v[192:195], v[144:147], v[112:115]
	v_mfma_f32_16x16x32_bf16 v[100:103], v[176:179], v[152:155], v[100:103]
	v_mfma_f32_16x16x32_bf16 v[96:99], v[192:195], v[152:155], v[96:99]
	v_mfma_f32_16x16x32_bf16 v[84:87], v[176:179], v[160:163], v[84:87]
	v_mfma_f32_16x16x32_bf16 v[80:83], v[192:195], v[160:163], v[80:83]
	v_mfma_f32_16x16x32_bf16 v[68:71], v[176:179], v[168:171], v[68:71]
	v_mfma_f32_16x16x32_bf16 v[64:67], v[192:195], v[168:171], v[64:67]
	v_mfma_f32_16x16x32_bf16 v[116:119], v[180:183], v[148:151], v[116:119]
	s_waitcnt lgkmcnt(0)
	v_mfma_f32_16x16x32_bf16 v[112:115], v[196:199], v[148:151], v[112:115]
	v_mfma_f32_16x16x32_bf16 v[100:103], v[180:183], v[156:159], v[100:103]
	v_mfma_f32_16x16x32_bf16 v[96:99], v[196:199], v[156:159], v[96:99]
	v_mfma_f32_16x16x32_bf16 v[84:87], v[180:183], v[164:167], v[84:87]
	v_mfma_f32_16x16x32_bf16 v[80:83], v[196:199], v[164:167], v[80:83]
	v_mfma_f32_16x16x32_bf16 v[68:71], v[180:183], v[172:175], v[68:71]
	v_mfma_f32_16x16x32_bf16 v[64:67], v[196:199], v[172:175], v[64:67]
	s_setprio 0
	s_and_b32 s17, s17, 0xffff
	s_mov_b32 s18, s10
	s_mov_b32 s19, s11
	s_mov_b32 m0, s83
	s_barrier
	ds_read_b128 v[144:147], v228 offset:49152
	ds_read_b128 v[148:151], v228 offset:50176
	ds_read_b128 v[152:155], v228 offset:51200
	ds_read_b128 v[156:159], v228 offset:52224
	ds_read_b128 v[160:163], v228 offset:53248
	ds_read_b128 v[164:167], v228 offset:54272
	ds_read_b128 v[168:171], v228 offset:55296
	ds_read_b128 v[172:175], v228 offset:56320
	buffer_load_dwordx4 v222, s[16:19], 0 offen lds
	s_mov_b32 m0, s84
	s_nop 0
	buffer_load_dwordx4 v224, s[16:19], 0 offen lds
	s_waitcnt vmcnt(8)
	s_barrier
	s_waitcnt lgkmcnt(0)
	s_setprio 1
	s_waitcnt lgkmcnt(7)
	v_mfma_f32_16x16x32_bf16 v[60:63], v[128:131], v[144:147], v[60:63]
	v_mfma_f32_16x16x32_bf16 v[56:59], v[136:139], v[144:147], v[56:59]
	s_waitcnt lgkmcnt(5)
	v_mfma_f32_16x16x32_bf16 v[44:47], v[128:131], v[152:155], v[44:47]
	v_mfma_f32_16x16x32_bf16 v[40:43], v[136:139], v[152:155], v[40:43]
	s_waitcnt lgkmcnt(3)
	v_mfma_f32_16x16x32_bf16 v[28:31], v[128:131], v[160:163], v[28:31]
	v_mfma_f32_16x16x32_bf16 v[24:27], v[136:139], v[160:163], v[24:27]
	s_waitcnt lgkmcnt(1)
	v_mfma_f32_16x16x32_bf16 v[12:15], v[128:131], v[168:171], v[12:15]
	v_mfma_f32_16x16x32_bf16 v[8:11], v[136:139], v[168:171], v[8:11]
	v_mfma_f32_16x16x32_bf16 v[60:63], v[132:135], v[148:151], v[60:63]
	v_mfma_f32_16x16x32_bf16 v[56:59], v[140:143], v[148:151], v[56:59]
	v_mfma_f32_16x16x32_bf16 v[44:47], v[132:135], v[156:159], v[44:47]
	v_mfma_f32_16x16x32_bf16 v[40:43], v[140:143], v[156:159], v[40:43]
	v_mfma_f32_16x16x32_bf16 v[28:31], v[132:135], v[164:167], v[28:31]
	v_mfma_f32_16x16x32_bf16 v[24:27], v[140:143], v[164:167], v[24:27]
	s_waitcnt lgkmcnt(0)
	v_mfma_f32_16x16x32_bf16 v[12:15], v[132:135], v[172:175], v[12:15]
	v_mfma_f32_16x16x32_bf16 v[8:11], v[140:143], v[172:175], v[8:11]
	s_setprio 0
	s_barrier
	ds_read_b128 v[128:131], v227
	ds_read_b128 v[132:135], v227 offset:1024
	ds_read_b128 v[136:139], v227 offset:2048
	ds_read_b128 v[140:143], v227 offset:3072
	s_add_u32 s8, s8, 0x80
	s_addc_u32 s9, s23, 0
	s_and_b32 s9, s9, 0xffff
	s_mov_b32 m0, s85
	s_nop 0
	buffer_load_dwordx4 v223, s[8:11], 0 offen lds
	s_mov_b32 m0, s86
	s_nop 0
	buffer_load_dwordx4 v225, s[8:11], 0 offen lds
	s_waitcnt vmcnt(6)
	s_barrier
	s_setprio 1
	v_mfma_f32_16x16x32_bf16 v[52:55], v[176:179], v[144:147], v[52:55]
	v_mfma_f32_16x16x32_bf16 v[48:51], v[192:195], v[144:147], v[48:51]
	v_mfma_f32_16x16x32_bf16 v[36:39], v[176:179], v[152:155], v[36:39]
	v_mfma_f32_16x16x32_bf16 v[32:35], v[192:195], v[152:155], v[32:35]
	v_mfma_f32_16x16x32_bf16 v[20:23], v[176:179], v[160:163], v[20:23]
	v_mfma_f32_16x16x32_bf16 v[16:19], v[192:195], v[160:163], v[16:19]
	v_mfma_f32_16x16x32_bf16 v[4:7], v[176:179], v[168:171], v[4:7]
	v_mfma_f32_16x16x32_bf16 v[0:3], v[192:195], v[168:171], v[0:3]
	v_mfma_f32_16x16x32_bf16 v[52:55], v[180:183], v[148:151], v[52:55]
	v_mfma_f32_16x16x32_bf16 v[48:51], v[196:199], v[148:151], v[48:51]
	v_mfma_f32_16x16x32_bf16 v[36:39], v[180:183], v[156:159], v[36:39]
	v_mfma_f32_16x16x32_bf16 v[32:35], v[196:199], v[156:159], v[32:35]
	v_mfma_f32_16x16x32_bf16 v[20:23], v[180:183], v[164:167], v[20:23]
	v_mfma_f32_16x16x32_bf16 v[16:19], v[196:199], v[164:167], v[16:19]
	v_mfma_f32_16x16x32_bf16 v[4:7], v[180:183], v[172:175], v[4:7]
	v_mfma_f32_16x16x32_bf16 v[0:3], v[196:199], v[172:175], v[0:3]
	s_setprio 0
	s_add_u32 s91, s91, 0x100
	s_addc_u32 s92, s92, 0
	s_add_u32 s93, s93, 0x100
	s_addc_u32 s94, s94, 0
	s_cmp_ge_i32 s22, s80
	s_mov_b32 s8, s22
	s_barrier
	s_cbranch_scc0 .Lkrot_922
	s_waitcnt lgkmcnt(0)

; #define PG8_STAGE(bufoff, gbase, voff) do { const __amdgpu_buffer_rsrc_t _r = __builtin_amdgcn_make_buffer_rsrc((void*)(gbase), (short)0, 0x7fffffff, 0x00020000); _Pragma("unroll") for (int _i = 0; _i < 2; ++_i) \
;         __builtin_amdgcn_raw_ptr_buffer_load_lds(_r, (LAS unsigned*)(lds + (bufoff) + ldsw + _i * 8192), 16, (int)(voff)[_i], 0, 0, 0); } while (0)
; #define PG8_LDA(dst, b, h) do { _Pragma("unroll") for (int m = 0; m < 4; ++m) _Pragma("unroll") for (int k = 0; k < 2; ++k) dst[m][k] = *(const LAS bf16x8*)(lds + PG8_SA(b, h) + aoff + m * 2048 + k * 1024); } while (0)
; #define PG8_LDB(dst, b, h) do { _Pragma("unroll") for (int n = 0; n < 2; ++n) _Pragma("unroll") for (int k = 0; k < 2; ++k) dst[n][k] = *(const LAS bf16x8*)(lds + PG8_SB(b, h) + boff + n * 2048 + k * 1024); } while (0)
; #define PG8_MMA(ai, bj, At, Bt) do { __builtin_amdgcn_s_setprio(1); _Pragma("unroll") for (int k = 0; k < 2; ++k) _Pragma("unroll") for (int m = 0; m < 4; ++m) _Pragma("unroll") for (int n = 0; n < ((bj) == 1 ? NB1 : 2); ++n) \
;         acc[ai][bj][m][n] = __builtin_amdgcn_mfma_f32_16x16x32_bf16(Bt[n][k], At[m][k], acc[ai][bj][m][n], 0, 0, 0); __builtin_amdgcn_s_setprio(0); } while (0)
; #define PG8_WAIT_V(n) asm volatile("s_waitcnt vmcnt(" #n ")" ::: "memory")
; #define PG8_WAIT_L(n) asm volatile("s_waitcnt lgkmcnt(" #n ")" ::: "memory")
; #define PG8_BAR __builtin_amdgcn_s_barrier()
;     ...
;         for (int t = 0; t < nt; t += 2) {
;             const bool last = (t == nt - 2);
;             const char* a1 = cA + (size_t)(t + 1) * kstep;
;             const char* a2 = last ? nA : cA + (size_t)(t + 2) * kstep; const char* b2 = last ? nB : cB + (size_t)(t + 2) * kstep;
;             const char* a3 = a2 + kstep; const char* b3 = b2 + kstep;
;             PG8_LDB(B0, 0, 0); PG8_SCHED; PG8_LDA(At, 0, 0); PG8_STAGE(PG8_SA(1, 1), a1 + hstepA, voffA);
;             PG8_WAIT_L(8); PG8_BAR; PG8_WAIT_L(0); PG8_MMA(0, 0, At, B0); PG8_BAR; PG8_SCHED;
;             PG8_LDB(B1, 0, 1); PG8_STAGE(PG8_SB(0, 0), b2, voffB);
;             PG8_BAR; PG8_WAIT_L(0); PG8_MMA(0, 1, At, B1); PG8_BAR;
;             PG8_LDA(At, 0, 1); PG8_STAGE(PG8_SA(0, 0), a2, voffA);
;             PG8_BAR; PG8_WAIT_L(0); PG8_MMA(1, 0, At, B0); PG8_BAR; PG8_SCHED;
;             PG8_STAGE(PG8_SB(0, 1), b2 + hstepB, voffB);
;             PG8_WAIT_V(6); PG8_BAR; PG8_MMA(1, 1, At, B1); PG8_BAR;
.Lkrot_984:
	s_add_i32 s22, s16, 2
	s_cmp_eq_u32 s90, s16
	s_cselect_b32 s36, s57, s96
	s_cselect_b32 s26, s53, s97
	s_cselect_b32 s25, s94, vcc_hi
	s_cselect_b32 s28, s95, vcc_lo
	s_add_u32 s24, s36, 0x80
	s_addc_u32 s23, s26, 0
	s_add_u32 s16, s96, s44
	s_addc_u32 s17, s97, s45
	s_add_u32 s16, s16, 0xffffff80
	s_addc_u32 s17, s17, -1
	s_and_b32 s17, s17, 0xffff
	s_mov_b32 m0, s91
	ds_read_b128 v[132:135], v194
	ds_read_b128 v[136:139], v194 offset:1024
	ds_read_b128 v[140:143], v194 offset:2048
	ds_read_b128 v[174:177], v194 offset:3072
	ds_read_b128 v[178:181], v194 offset:4096
	ds_read_b128 v[182:185], v194 offset:5120
	ds_read_b128 v[202:205], v194 offset:6144
	ds_read_b128 v[206:209], v194 offset:7168
	buffer_load_dwordx4 v186, s[16:19], 0 offen lds
	s_mov_b32 m0, s92
	s_nop 0
	buffer_load_dwordx4 v188, s[16:19], 0 offen lds
	s_waitcnt lgkmcnt(8)
	s_barrier
	s_waitcnt lgkmcnt(0)
	s_setprio 1
	s_waitcnt lgkmcnt(7)
	v_mfma_f32_16x16x32_bf16 v[152:155], v[76:79], v[132:135], v[152:155]
	v_mfma_f32_16x16x32_bf16 v[144:147], v[92:95], v[132:135], v[144:147]
	s_waitcnt lgkmcnt(5)
	v_mfma_f32_16x16x32_bf16 v[124:127], v[76:79], v[140:143], v[124:127]
	v_mfma_f32_16x16x32_bf16 v[120:123], v[92:95], v[140:143], v[120:123]
	s_waitcnt lgkmcnt(3)
	v_mfma_f32_16x16x32_bf16 v[108:111], v[76:79], v[178:181], v[108:111]
	v_mfma_f32_16x16x32_bf16 v[104:107], v[92:95], v[178:181], v[104:107]
	s_waitcnt lgkmcnt(1)
	v_mfma_f32_16x16x32_bf16 v[84:87], v[76:79], v[202:205], v[84:87]
	v_mfma_f32_16x16x32_bf16 v[80:83], v[92:95], v[202:205], v[80:83]
	v_mfma_f32_16x16x32_bf16 v[152:155], v[88:91], v[136:139], v[152:155]
	v_mfma_f32_16x16x32_bf16 v[144:147], v[128:131], v[136:139], v[144:147]
	v_mfma_f32_16x16x32_bf16 v[124:127], v[88:91], v[174:177], v[124:127]
	v_mfma_f32_16x16x32_bf16 v[120:123], v[128:131], v[174:177], v[120:123]
	v_mfma_f32_16x16x32_bf16 v[108:111], v[88:91], v[182:185], v[108:111]
	v_mfma_f32_16x16x32_bf16 v[104:107], v[128:131], v[182:185], v[104:107]
	s_waitcnt lgkmcnt(0)
	v_mfma_f32_16x16x32_bf16 v[84:87], v[88:91], v[206:209], v[84:87]
	v_mfma_f32_16x16x32_bf16 v[80:83], v[128:131], v[206:209], v[80:83]
	s_setprio 0
	s_barrier
	s_and_b32 s29, s25, 0xffff
	s_mov_b32 s30, s18
	s_mov_b32 s31, s19
	s_mov_b32 m0, s71
	ds_read_b128 v[210:213], v195
	ds_read_b128 v[214:217], v195 offset:1024
	ds_read_b128 v[218:221], v195 offset:2048
	ds_read_b128 v[222:225], v195 offset:3072
	buffer_load_dwordx4 v187, s[28:31], 0 offen lds
	s_mov_b32 m0, s77
	s_nop 0
	buffer_load_dwordx4 v189, s[28:31], 0 offen lds
	s_barrier
	s_waitcnt lgkmcnt(0)
	s_setprio 1
	s_waitcnt lgkmcnt(3)
	v_mfma_f32_16x16x32_bf16 v[116:119], v[210:213], v[140:143], v[116:119]
	s_waitcnt lgkmcnt(1)
	v_mfma_f32_16x16x32_bf16 v[112:115], v[218:221], v[140:143], v[112:115]
	v_mfma_f32_16x16x32_bf16 v[100:103], v[210:213], v[178:181], v[100:103]
	v_mfma_f32_16x16x32_bf16 v[96:99], v[218:221], v[178:181], v[96:99]
	v_mfma_f32_16x16x32_bf16 v[68:71], v[210:213], v[202:205], v[68:71]
	v_mfma_f32_16x16x32_bf16 v[64:67], v[218:221], v[202:205], v[64:67]
	v_mfma_f32_16x16x32_bf16 v[156:159], v[210:213], v[132:135], v[156:159]
	v_mfma_f32_16x16x32_bf16 v[132:135], v[218:221], v[132:135], v[148:151]
	v_mfma_f32_16x16x32_bf16 v[116:119], v[214:217], v[174:177], v[116:119]
	s_waitcnt lgkmcnt(0)
	v_mfma_f32_16x16x32_bf16 v[112:115], v[222:225], v[174:177], v[112:115]
	v_mfma_f32_16x16x32_bf16 v[100:103], v[214:217], v[182:185], v[100:103]
	v_mfma_f32_16x16x32_bf16 v[96:99], v[222:225], v[182:185], v[96:99]
	v_mfma_f32_16x16x32_bf16 v[68:71], v[214:217], v[206:209], v[68:71]
	v_mfma_f32_16x16x32_bf16 v[64:67], v[222:225], v[206:209], v[64:67]
	v_mfma_f32_16x16x32_bf16 v[140:143], v[214:217], v[136:139], v[156:159]
	v_mfma_f32_16x16x32_bf16 v[132:135], v[222:225], v[136:139], v[132:135]
	s_setprio 0
	s_and_b32 s37, s26, 0xffff
	s_mov_b32 s38, s18
	s_mov_b32 s39, s19
	s_mov_b32 m0, s67
	s_barrier
	ds_read_b128 v[136:139], v194 offset:16384
	ds_read_b128 v[148:151], v194 offset:17408
	ds_read_b128 v[156:159], v194 offset:18432
	ds_read_b128 v[174:177], v194 offset:19456
	ds_read_b128 v[178:181], v194 offset:20480
	ds_read_b128 v[182:185], v194 offset:21504
	ds_read_b128 v[202:205], v194 offset:22528
	ds_read_b128 v[206:209], v194 offset:23552
	buffer_load_dwordx4 v186, s[36:39], 0 offen lds
	s_mov_b32 m0, s78
	s_nop 0
	buffer_load_dwordx4 v188, s[36:39], 0 offen lds
	s_waitcnt vmcnt(8)
	s_barrier
	s_waitcnt lgkmcnt(0)
	s_setprio 1
	s_waitcnt lgkmcnt(7)
	v_mfma_f32_16x16x32_bf16 v[60:63], v[76:79], v[136:139], v[60:63]
	v_mfma_f32_16x16x32_bf16 v[52:55], v[92:95], v[136:139], v[52:55]
	s_waitcnt lgkmcnt(5)
	v_mfma_f32_16x16x32_bf16 v[44:47], v[76:79], v[156:159], v[44:47]
	v_mfma_f32_16x16x32_bf16 v[40:43], v[92:95], v[156:159], v[40:43]
	s_waitcnt lgkmcnt(3)
	v_mfma_f32_16x16x32_bf16 v[28:31], v[76:79], v[178:181], v[28:31]
	v_mfma_f32_16x16x32_bf16 v[24:27], v[92:95], v[178:181], v[24:27]
	s_waitcnt lgkmcnt(1)
	v_mfma_f32_16x16x32_bf16 v[12:15], v[76:79], v[202:205], v[12:15]
	v_mfma_f32_16x16x32_bf16 v[8:11], v[92:95], v[202:205], v[8:11]
	v_mfma_f32_16x16x32_bf16 v[60:63], v[88:91], v[148:151], v[60:63]
	v_mfma_f32_16x16x32_bf16 v[52:55], v[128:131], v[148:151], v[52:55]
	v_mfma_f32_16x16x32_bf16 v[44:47], v[88:91], v[174:177], v[44:47]
	v_mfma_f32_16x16x32_bf16 v[40:43], v[128:131], v[174:177], v[40:43]
	v_mfma_f32_16x16x32_bf16 v[28:31], v[88:91], v[182:185], v[28:31]
	v_mfma_f32_16x16x32_bf16 v[24:27], v[128:131], v[182:185], v[24:27]
	s_waitcnt lgkmcnt(0)
	v_mfma_f32_16x16x32_bf16 v[12:15], v[88:91], v[206:209], v[12:15]
	v_mfma_f32_16x16x32_bf16 v[8:11], v[128:131], v[206:209], v[8:11]
	s_setprio 0
	s_barrier
; #define PG8_STAGE(bufoff, gbase, voff) do { const __amdgpu_buffer_rsrc_t _r = __builtin_amdgcn_make_buffer_rsrc((void*)(gbase), (short)0, 0x7fffffff, 0x00020000); _Pragma("unroll") for (int _i = 0; _i < 2; ++_i) \
;         __builtin_amdgcn_raw_ptr_buffer_load_lds(_r, (LAS unsigned*)(lds + (bufoff) + ldsw + _i * 8192), 16, (int)(voff)[_i], 0, 0, 0); } while (0)
; #define PG8_LDA(dst, b, h) do { _Pragma("unroll") for (int m = 0; m < 4; ++m) _Pragma("unroll") for (int k = 0; k < 2; ++k) dst[m][k] = *(const LAS bf16x8*)(lds + PG8_SA(b, h) + aoff + m * 2048 + k * 1024); } while (0)
; #define PG8_LDB(dst, b, h) do { _Pragma("unroll") for (int n = 0; n < 2; ++n) _Pragma("unroll") for (int k = 0; k < 2; ++k) dst[n][k] = *(const LAS bf16x8*)(lds + PG8_SB(b, h) + boff + n * 2048 + k * 1024); } while (0)
; #define PG8_MMA(ai, bj, At, Bt) do { __builtin_amdgcn_s_setprio(1); _Pragma("unroll") for (int k = 0; k < 2; ++k) _Pragma("unroll") for (int m = 0; m < 4; ++m) _Pragma("unroll") for (int n = 0; n < ((bj) == 1 ? NB1 : 2); ++n) \
;         acc[ai][bj][m][n] = __builtin_amdgcn_mfma_f32_16x16x32_bf16(Bt[n][k], At[m][k], acc[ai][bj][m][n], 0, 0, 0); __builtin_amdgcn_s_setprio(0); } while (0)
; #define PG8_WAIT_V(n) asm volatile("s_waitcnt vmcnt(" #n ")" ::: "memory")
; #define PG8_WAIT_L(n) asm volatile("s_waitcnt lgkmcnt(" #n ")" ::: "memory")
; #define PG8_BAR __builtin_amdgcn_s_barrier()
; #define PG8_SCHED __builtin_amdgcn_sched_barrier(0)
;     ...
;             PG8_WAIT_V(6); PG8_BAR; PG8_MMA(1, 1, At, B1); PG8_BAR;
;             PG8_LDB(B0, 1, 0); PG8_SCHED; PG8_LDA(At, 1, 0); PG8_STAGE(PG8_SA(0, 1), a2 + hstepA, voffA);
;             PG8_WAIT_L(8); PG8_BAR; PG8_WAIT_L(0); PG8_MMA(0, 0, At, B0); PG8_BAR; PG8_SCHED;
;             PG8_LDB(B1, 1, 1); PG8_STAGE(PG8_SB(1, 0), b3, voffB);
;             PG8_BAR; PG8_WAIT_L(0); PG8_MMA(0, 1, At, B1); PG8_BAR;
	ds_read_b128 v[76:79], v196
	ds_read_b128 v[88:91], v196 offset:1024
	ds_read_b128 v[92:95], v196 offset:2048
	ds_read_b128 v[128:131], v196 offset:3072
	s_add_u32 s16, s28, s46
	s_addc_u32 s14, s25, s47
	s_and_b32 s17, s14, 0xffff
	s_mov_b32 m0, s79
	s_nop 0
	buffer_load_dwordx4 v187, s[16:19], 0 offen lds
	s_mov_b32 m0, s80
	s_nop 0
	buffer_load_dwordx4 v189, s[16:19], 0 offen lds
	s_waitcnt vmcnt(6)
	s_barrier
	s_setprio 1
	v_mfma_f32_16x16x32_bf16 v[56:59], v[210:213], v[136:139], v[56:59]
	v_mfma_f32_16x16x32_bf16 v[48:51], v[218:221], v[136:139], v[48:51]
	v_mfma_f32_16x16x32_bf16 v[36:39], v[210:213], v[156:159], v[36:39]
	v_mfma_f32_16x16x32_bf16 v[32:35], v[218:221], v[156:159], v[32:35]
	v_mfma_f32_16x16x32_bf16 v[20:23], v[210:213], v[178:181], v[20:23]
	v_mfma_f32_16x16x32_bf16 v[16:19], v[218:221], v[178:181], v[16:19]
	v_mfma_f32_16x16x32_bf16 v[4:7], v[210:213], v[202:205], v[4:7]
	v_mfma_f32_16x16x32_bf16 v[0:3], v[218:221], v[202:205], v[0:3]
	v_mfma_f32_16x16x32_bf16 v[56:59], v[214:217], v[148:151], v[56:59]
	v_mfma_f32_16x16x32_bf16 v[48:51], v[222:225], v[148:151], v[48:51]
	v_mfma_f32_16x16x32_bf16 v[36:39], v[214:217], v[174:177], v[36:39]
	v_mfma_f32_16x16x32_bf16 v[32:35], v[222:225], v[174:177], v[32:35]
	v_mfma_f32_16x16x32_bf16 v[20:23], v[214:217], v[182:185], v[20:23]
	v_mfma_f32_16x16x32_bf16 v[16:19], v[222:225], v[182:185], v[16:19]
	v_mfma_f32_16x16x32_bf16 v[4:7], v[214:217], v[206:209], v[4:7]
	v_mfma_f32_16x16x32_bf16 v[0:3], v[222:225], v[206:209], v[0:3]
	s_setprio 0
	s_barrier
	s_add_u32 s36, s36, s44
	s_addc_u32 s17, s26, s45
	s_and_b32 s37, s17, 0xffff
	s_mov_b32 m0, s81
	ds_read_b128 v[136:139], v194 offset:32768
	ds_read_b128 v[148:151], v194 offset:33792
	ds_read_b128 v[156:159], v194 offset:34816
	ds_read_b128 v[174:177], v194 offset:35840
	ds_read_b128 v[178:181], v194 offset:36864
	ds_read_b128 v[182:185], v194 offset:37888
	ds_read_b128 v[202:205], v194 offset:38912
	ds_read_b128 v[206:209], v194 offset:39936
	buffer_load_dwordx4 v186, s[36:39], 0 offen lds
	s_mov_b32 m0, s82
	s_nop 0
	buffer_load_dwordx4 v188, s[36:39], 0 offen lds
	s_waitcnt lgkmcnt(8)
	s_barrier
	s_waitcnt lgkmcnt(0)
	s_setprio 1
	s_waitcnt lgkmcnt(7)
	v_mfma_f32_16x16x32_bf16 v[152:155], v[76:79], v[136:139], v[152:155]
	v_mfma_f32_16x16x32_bf16 v[144:147], v[92:95], v[136:139], v[144:147]
	s_waitcnt lgkmcnt(5)
	v_mfma_f32_16x16x32_bf16 v[124:127], v[76:79], v[156:159], v[124:127]
	v_mfma_f32_16x16x32_bf16 v[120:123], v[92:95], v[156:159], v[120:123]
	s_waitcnt lgkmcnt(3)
	v_mfma_f32_16x16x32_bf16 v[108:111], v[76:79], v[178:181], v[108:111]
	v_mfma_f32_16x16x32_bf16 v[104:107], v[92:95], v[178:181], v[104:107]
	s_waitcnt lgkmcnt(1)
	v_mfma_f32_16x16x32_bf16 v[84:87], v[76:79], v[202:205], v[84:87]
	v_mfma_f32_16x16x32_bf16 v[80:83], v[92:95], v[202:205], v[80:83]
	v_mfma_f32_16x16x32_bf16 v[152:155], v[88:91], v[148:151], v[152:155]
	v_mfma_f32_16x16x32_bf16 v[144:147], v[128:131], v[148:151], v[144:147]
	v_mfma_f32_16x16x32_bf16 v[124:127], v[88:91], v[174:177], v[124:127]
	v_mfma_f32_16x16x32_bf16 v[120:123], v[128:131], v[174:177], v[120:123]
	v_mfma_f32_16x16x32_bf16 v[108:111], v[88:91], v[182:185], v[108:111]
	v_mfma_f32_16x16x32_bf16 v[104:107], v[128:131], v[182:185], v[104:107]
	s_waitcnt lgkmcnt(0)
	v_mfma_f32_16x16x32_bf16 v[84:87], v[88:91], v[206:209], v[84:87]
	v_mfma_f32_16x16x32_bf16 v[80:83], v[128:131], v[206:209], v[80:83]
	s_setprio 0
	s_barrier
	s_add_u32 s28, s28, 0x80
	s_addc_u32 s17, s25, 0
	s_and_b32 s29, s17, 0xffff
	s_mov_b32 m0, s84
	ds_read_b128 v[210:213], v197
	ds_read_b128 v[214:217], v197 offset:1024
	ds_read_b128 v[218:221], v197 offset:2048
	ds_read_b128 v[222:225], v197 offset:3072
	buffer_load_dwordx4 v187, s[28:31], 0 offen lds
	s_mov_b32 m0, s85
	s_nop 0
	buffer_load_dwordx4 v189, s[28:31], 0 offen lds
	s_barrier
; #define PG8_STAGE(bufoff, gbase, voff) do { const __amdgpu_buffer_rsrc_t _r = __builtin_amdgcn_make_buffer_rsrc((void*)(gbase), (short)0, 0x7fffffff, 0x00020000); _Pragma("unroll") for (int _i = 0; _i < 2; ++_i) \
;         __builtin_amdgcn_raw_ptr_buffer_load_lds(_r, (LAS unsigned*)(lds + (bufoff) + ldsw + _i * 8192), 16, (int)(voff)[_i], 0, 0, 0); } while (0)
; #define PG8_LDA(dst, b, h) do { _Pragma("unroll") for (int m = 0; m < 4; ++m) _Pragma("unroll") for (int k = 0; k < 2; ++k) dst[m][k] = *(const LAS bf16x8*)(lds + PG8_SA(b, h) + aoff + m * 2048 + k * 1024); } while (0)
; #define PG8_MMA(ai, bj, At, Bt) do { __builtin_amdgcn_s_setprio(1); _Pragma("unroll") for (int k = 0; k < 2; ++k) _Pragma("unroll") for (int m = 0; m < 4; ++m) _Pragma("unroll") for (int n = 0; n < ((bj) == 1 ? NB1 : 2); ++n) \
;         acc[ai][bj][m][n] = __builtin_amdgcn_mfma_f32_16x16x32_bf16(Bt[n][k], At[m][k], acc[ai][bj][m][n], 0, 0, 0); __builtin_amdgcn_s_setprio(0); } while (0)
; #define PG8_WAIT_V(n) asm volatile("s_waitcnt vmcnt(" #n ")" ::: "memory")
; #define PG8_WAIT_L(n) asm volatile("s_waitcnt lgkmcnt(" #n ")" ::: "memory")
; #define PG8_BAR __builtin_amdgcn_s_barrier()
; #define PG8_SCHED __builtin_amdgcn_sched_barrier(0)
;     ...
;             PG8_BAR; PG8_WAIT_L(0); PG8_MMA(0, 1, At, B1); PG8_BAR;
;             PG8_LDA(At, 1, 1); PG8_STAGE(PG8_SA(1, 0), a3, voffA);
;             PG8_BAR; PG8_WAIT_L(0); PG8_MMA(1, 0, At, B0); PG8_BAR; PG8_SCHED;
;             PG8_STAGE(PG8_SB(1, 1), b3 + hstepB, voffB);
;             PG8_WAIT_V(6); PG8_BAR; PG8_MMA(1, 1, At, B1); PG8_BAR;
;         }
	s_waitcnt lgkmcnt(0)
	s_setprio 1
	s_waitcnt lgkmcnt(3)
	v_mfma_f32_16x16x32_bf16 v[140:143], v[210:213], v[136:139], v[140:143]
	s_waitcnt lgkmcnt(1)
	v_mfma_f32_16x16x32_bf16 v[132:135], v[218:221], v[136:139], v[132:135]
	v_mfma_f32_16x16x32_bf16 v[116:119], v[210:213], v[156:159], v[116:119]
	v_mfma_f32_16x16x32_bf16 v[112:115], v[218:221], v[156:159], v[112:115]
	v_mfma_f32_16x16x32_bf16 v[100:103], v[210:213], v[178:181], v[100:103]
	v_mfma_f32_16x16x32_bf16 v[96:99], v[218:221], v[178:181], v[96:99]
	v_mfma_f32_16x16x32_bf16 v[68:71], v[210:213], v[202:205], v[68:71]
	v_mfma_f32_16x16x32_bf16 v[64:67], v[218:221], v[202:205], v[64:67]
	v_mfma_f32_16x16x32_bf16 v[156:159], v[214:217], v[148:151], v[140:143]
	s_waitcnt lgkmcnt(0)
	v_mfma_f32_16x16x32_bf16 v[148:151], v[222:225], v[148:151], v[132:135]
	v_mfma_f32_16x16x32_bf16 v[116:119], v[214:217], v[174:177], v[116:119]
	v_mfma_f32_16x16x32_bf16 v[112:115], v[222:225], v[174:177], v[112:115]
	v_mfma_f32_16x16x32_bf16 v[100:103], v[214:217], v[182:185], v[100:103]
	v_mfma_f32_16x16x32_bf16 v[96:99], v[222:225], v[182:185], v[96:99]
	v_mfma_f32_16x16x32_bf16 v[68:71], v[214:217], v[206:209], v[68:71]
	v_mfma_f32_16x16x32_bf16 v[64:67], v[222:225], v[206:209], v[64:67]
	s_setprio 0
	s_and_b32 s25, s23, 0xffff
	s_mov_b32 s26, s18
	s_mov_b32 s27, s19
	s_mov_b32 m0, s86
	s_barrier
	ds_read_b128 v[132:135], v194 offset:49152
	ds_read_b128 v[136:139], v194 offset:50176
	ds_read_b128 v[140:143], v194 offset:51200
	ds_read_b128 v[174:177], v194 offset:52224
	ds_read_b128 v[178:181], v194 offset:53248
	ds_read_b128 v[182:185], v194 offset:54272
	ds_read_b128 v[202:205], v194 offset:55296
	ds_read_b128 v[206:209], v194 offset:56320
	buffer_load_dwordx4 v186, s[24:27], 0 offen lds
	s_mov_b32 m0, s87
	s_nop 0
	buffer_load_dwordx4 v188, s[24:27], 0 offen lds
	s_waitcnt vmcnt(8)
	s_barrier
	s_waitcnt lgkmcnt(0)
	s_setprio 1
	s_waitcnt lgkmcnt(7)
	v_mfma_f32_16x16x32_bf16 v[60:63], v[76:79], v[132:135], v[60:63]
	v_mfma_f32_16x16x32_bf16 v[52:55], v[92:95], v[132:135], v[52:55]
	s_waitcnt lgkmcnt(5)
	v_mfma_f32_16x16x32_bf16 v[44:47], v[76:79], v[140:143], v[44:47]
	v_mfma_f32_16x16x32_bf16 v[40:43], v[92:95], v[140:143], v[40:43]
	s_waitcnt lgkmcnt(3)
	v_mfma_f32_16x16x32_bf16 v[28:31], v[76:79], v[178:181], v[28:31]
	v_mfma_f32_16x16x32_bf16 v[24:27], v[92:95], v[178:181], v[24:27]
	s_waitcnt lgkmcnt(1)
	v_mfma_f32_16x16x32_bf16 v[12:15], v[76:79], v[202:205], v[12:15]
	v_mfma_f32_16x16x32_bf16 v[8:11], v[92:95], v[202:205], v[8:11]
	v_mfma_f32_16x16x32_bf16 v[60:63], v[88:91], v[136:139], v[60:63]
	v_mfma_f32_16x16x32_bf16 v[52:55], v[128:131], v[136:139], v[52:55]
	v_mfma_f32_16x16x32_bf16 v[44:47], v[88:91], v[174:177], v[44:47]
	v_mfma_f32_16x16x32_bf16 v[40:43], v[128:131], v[174:177], v[40:43]
	v_mfma_f32_16x16x32_bf16 v[28:31], v[88:91], v[182:185], v[28:31]
	v_mfma_f32_16x16x32_bf16 v[24:27], v[128:131], v[182:185], v[24:27]
	s_waitcnt lgkmcnt(0)
	v_mfma_f32_16x16x32_bf16 v[12:15], v[88:91], v[206:209], v[12:15]
	v_mfma_f32_16x16x32_bf16 v[8:11], v[128:131], v[206:209], v[8:11]
	s_setprio 0
	s_barrier
	ds_read_b128 v[76:79], v193
	ds_read_b128 v[88:91], v193 offset:1024
	ds_read_b128 v[92:95], v193 offset:2048
	ds_read_b128 v[128:131], v193 offset:3072
	s_add_u32 s16, s16, 0x80
	s_addc_u32 s14, s14, 0
	s_and_b32 s17, s14, 0xffff
	s_mov_b32 m0, s88
	s_nop 0
	buffer_load_dwordx4 v187, s[16:19], 0 offen lds
	s_mov_b32 m0, s89
	s_nop 0
	buffer_load_dwordx4 v189, s[16:19], 0 offen lds
	s_waitcnt vmcnt(6)
	s_barrier
	s_setprio 1
	v_mfma_f32_16x16x32_bf16 v[56:59], v[210:213], v[132:135], v[56:59]
	v_mfma_f32_16x16x32_bf16 v[48:51], v[218:221], v[132:135], v[48:51]
	v_mfma_f32_16x16x32_bf16 v[36:39], v[210:213], v[140:143], v[36:39]
	v_mfma_f32_16x16x32_bf16 v[32:35], v[218:221], v[140:143], v[32:35]
	v_mfma_f32_16x16x32_bf16 v[20:23], v[210:213], v[178:181], v[20:23]
	v_mfma_f32_16x16x32_bf16 v[16:19], v[218:221], v[178:181], v[16:19]
	v_mfma_f32_16x16x32_bf16 v[4:7], v[210:213], v[202:205], v[4:7]
	v_mfma_f32_16x16x32_bf16 v[0:3], v[218:221], v[202:205], v[0:3]
	v_mfma_f32_16x16x32_bf16 v[56:59], v[214:217], v[136:139], v[56:59]
	v_mfma_f32_16x16x32_bf16 v[48:51], v[222:225], v[136:139], v[48:51]
	v_mfma_f32_16x16x32_bf16 v[36:39], v[214:217], v[174:177], v[36:39]
	v_mfma_f32_16x16x32_bf16 v[32:35], v[222:225], v[174:177], v[32:35]
	v_mfma_f32_16x16x32_bf16 v[20:23], v[214:217], v[182:185], v[20:23]
	v_mfma_f32_16x16x32_bf16 v[16:19], v[222:225], v[182:185], v[16:19]
	v_mfma_f32_16x16x32_bf16 v[4:7], v[214:217], v[206:209], v[4:7]
	v_mfma_f32_16x16x32_bf16 v[0:3], v[222:225], v[206:209], v[0:3]
	s_setprio 0
	s_add_u32 s96, s96, 0x100
	s_addc_u32 s97, s97, 0
	s_add_u32 vcc_lo, vcc_lo, 0x100
	s_addc_u32 vcc_hi, vcc_hi, 0
	s_cmp_ge_i32 s22, s83
	s_mov_b32 s16, s22
	s_barrier
	s_cbranch_scc0 .Lkrot_984
	s_waitcnt lgkmcnt(0)
	v_readlane_b32 s96, v252, 38
	v_readlane_b32 s97, v252, 39

; #define PG8_STAGE(bufoff, gbase, voff) do { const __amdgpu_buffer_rsrc_t _r = __builtin_amdgcn_make_buffer_rsrc((void*)(gbase), (short)0, 0x7fffffff, 0x00020000); _Pragma("unroll") for (int _i = 0; _i < 2; ++_i) \
;         __builtin_amdgcn_raw_ptr_buffer_load_lds(_r, (LAS unsigned*)(lds + (bufoff) + ldsw + _i * 8192), 16, (int)(voff)[_i], 0, 0, 0); } while (0)
; #define PG8_LDA(dst, b, h) do { _Pragma("unroll") for (int m = 0; m < 4; ++m) _Pragma("unroll") for (int k = 0; k < 2; ++k) dst[m][k] = *(const LAS bf16x8*)(lds + PG8_SA(b, h) + aoff + m * 2048 + k * 1024); } while (0)
; #define PG8_LDB(dst, b, h) do { _Pragma("unroll") for (int n = 0; n < 2; ++n) _Pragma("unroll") for (int k = 0; k < 2; ++k) dst[n][k] = *(const LAS bf16x8*)(lds + PG8_SB(b, h) + boff + n * 2048 + k * 1024); } while (0)
; #define PG8_MMA(ai, bj, At, Bt) do { __builtin_amdgcn_s_setprio(1); _Pragma("unroll") for (int k = 0; k < 2; ++k) _Pragma("unroll") for (int m = 0; m < 4; ++m) _Pragma("unroll") for (int n = 0; n < ((bj) == 1 ? NB1 : 2); ++n) \
;         acc[ai][bj][m][n] = __builtin_amdgcn_mfma_f32_16x16x32_bf16(Bt[n][k], At[m][k], acc[ai][bj][m][n], 0, 0, 0); __builtin_amdgcn_s_setprio(0); } while (0)
; #define PG8_WAIT_V(n) asm volatile("s_waitcnt vmcnt(" #n ")" ::: "memory")
; #define PG8_WAIT_L(n) asm volatile("s_waitcnt lgkmcnt(" #n ")" ::: "memory")
; #define PG8_BAR __builtin_amdgcn_s_barrier()
;     ...
;         for (int t = 0; t < nt; t += 2) {
;             const bool last = (t == nt - 2);
;             const char* a1 = cA + (size_t)(t + 1) * kstep;
;             const char* a2 = last ? nA : cA + (size_t)(t + 2) * kstep; const char* b2 = last ? nB : cB + (size_t)(t + 2) * kstep;
;             const char* a3 = a2 + kstep; const char* b3 = b2 + kstep;
;             PG8_LDB(B0, 0, 0); PG8_SCHED; PG8_LDA(At, 0, 0); PG8_STAGE(PG8_SA(1, 1), a1 + hstepA, voffA);
;             PG8_WAIT_L(8); PG8_BAR; PG8_WAIT_L(0); PG8_MMA(0, 0, At, B0); PG8_BAR; PG8_SCHED;
;             PG8_LDB(B1, 0, 1); PG8_STAGE(PG8_SB(0, 0), b2, voffB);
;             PG8_BAR; PG8_WAIT_L(0); PG8_MMA(0, 1, At, B1); PG8_BAR;
;             PG8_LDA(At, 0, 1); PG8_STAGE(PG8_SA(0, 0), a2, voffA);
;             PG8_BAR; PG8_WAIT_L(0); PG8_MMA(1, 0, At, B0); PG8_BAR; PG8_SCHED;
;             PG8_STAGE(PG8_SB(0, 1), b2 + hstepB, voffB);
;             PG8_WAIT_V(6); PG8_BAR; PG8_MMA(1, 1, At, B1); PG8_BAR;
.Lkrot_1066:
	s_add_i32 s22, s8, 2
	s_cmp_eq_u32 s71, s8
	s_cselect_b32 s28, s0, s79
	s_cselect_b32 s19, s1, s80
	s_cselect_b32 s18, s45, s82
	s_cselect_b32 s24, s44, s81
	s_add_u32 s16, s28, 0x80
	s_addc_u32 s17, s19, 0
	s_add_u32 s8, s79, s36
	s_addc_u32 s9, s80, s37
	s_add_u32 s8, s8, 0xffffff80
	s_addc_u32 s9, s9, -1
	s_and_b32 s9, s9, 0xffff
	s_mov_b32 m0, s72
	ds_read_b128 v[144:147], v228
	ds_read_b128 v[148:151], v228 offset:1024
	ds_read_b128 v[152:155], v228 offset:2048
	ds_read_b128 v[156:159], v228 offset:3072
	ds_read_b128 v[160:163], v228 offset:4096
	ds_read_b128 v[164:167], v228 offset:5120
	ds_read_b128 v[168:171], v228 offset:6144
	ds_read_b128 v[172:175], v228 offset:7168
	buffer_load_dwordx4 v222, s[8:11], 0 offen lds
	s_mov_b32 m0, s73
	s_nop 0
	buffer_load_dwordx4 v224, s[8:11], 0 offen lds
	s_waitcnt lgkmcnt(8)
	s_barrier
	s_waitcnt lgkmcnt(0)
	s_setprio 1
	s_waitcnt lgkmcnt(7)
	v_mfma_f32_16x16x32_bf16 v[120:123], v[128:131], v[144:147], v[120:123]
	v_mfma_f32_16x16x32_bf16 v[124:127], v[136:139], v[144:147], v[124:127]
	s_waitcnt lgkmcnt(5)
	v_mfma_f32_16x16x32_bf16 v[108:111], v[128:131], v[152:155], v[108:111]
	v_mfma_f32_16x16x32_bf16 v[104:107], v[136:139], v[152:155], v[104:107]
	s_waitcnt lgkmcnt(3)
	v_mfma_f32_16x16x32_bf16 v[92:95], v[128:131], v[160:163], v[92:95]
	v_mfma_f32_16x16x32_bf16 v[88:91], v[136:139], v[160:163], v[88:91]
	s_waitcnt lgkmcnt(1)
	v_mfma_f32_16x16x32_bf16 v[76:79], v[128:131], v[168:171], v[76:79]
	v_mfma_f32_16x16x32_bf16 v[72:75], v[136:139], v[168:171], v[72:75]
	v_mfma_f32_16x16x32_bf16 v[120:123], v[132:135], v[148:151], v[120:123]
	v_mfma_f32_16x16x32_bf16 v[124:127], v[140:143], v[148:151], v[124:127]
	v_mfma_f32_16x16x32_bf16 v[108:111], v[132:135], v[156:159], v[108:111]
	v_mfma_f32_16x16x32_bf16 v[104:107], v[140:143], v[156:159], v[104:107]
	v_mfma_f32_16x16x32_bf16 v[92:95], v[132:135], v[164:167], v[92:95]
	v_mfma_f32_16x16x32_bf16 v[88:91], v[140:143], v[164:167], v[88:91]
	s_waitcnt lgkmcnt(0)
	v_mfma_f32_16x16x32_bf16 v[76:79], v[132:135], v[172:175], v[76:79]
	v_mfma_f32_16x16x32_bf16 v[72:75], v[140:143], v[172:175], v[72:75]
	s_setprio 0
	s_barrier
	s_and_b32 s25, s18, 0xffff
	s_mov_b32 s26, s10
	s_mov_b32 s27, s11
	s_mov_b32 m0, s50
	ds_read_b128 v[176:179], v229
	ds_read_b128 v[180:183], v229 offset:1024
	ds_read_b128 v[192:195], v229 offset:2048
	ds_read_b128 v[196:199], v229 offset:3072
	buffer_load_dwordx4 v223, s[24:27], 0 offen lds
	s_mov_b32 m0, s51
	s_nop 0
	buffer_load_dwordx4 v225, s[24:27], 0 offen lds
	s_barrier
	s_waitcnt lgkmcnt(0)
	s_setprio 1
	s_waitcnt lgkmcnt(3)
	v_mfma_f32_16x16x32_bf16 v[116:119], v[176:179], v[144:147], v[116:119]
	s_waitcnt lgkmcnt(1)
	v_mfma_f32_16x16x32_bf16 v[112:115], v[192:195], v[144:147], v[112:115]
	v_mfma_f32_16x16x32_bf16 v[100:103], v[176:179], v[152:155], v[100:103]
	v_mfma_f32_16x16x32_bf16 v[96:99], v[192:195], v[152:155], v[96:99]
	v_mfma_f32_16x16x32_bf16 v[84:87], v[176:179], v[160:163], v[84:87]
	v_mfma_f32_16x16x32_bf16 v[80:83], v[192:195], v[160:163], v[80:83]
	v_mfma_f32_16x16x32_bf16 v[68:71], v[176:179], v[168:171], v[68:71]
	v_mfma_f32_16x16x32_bf16 v[64:67], v[192:195], v[168:171], v[64:67]
	v_mfma_f32_16x16x32_bf16 v[116:119], v[180:183], v[148:151], v[116:119]
	s_waitcnt lgkmcnt(0)
	v_mfma_f32_16x16x32_bf16 v[112:115], v[196:199], v[148:151], v[112:115]
	v_mfma_f32_16x16x32_bf16 v[100:103], v[180:183], v[156:159], v[100:103]
	v_mfma_f32_16x16x32_bf16 v[96:99], v[196:199], v[156:159], v[96:99]
	v_mfma_f32_16x16x32_bf16 v[84:87], v[180:183], v[164:167], v[84:87]
	v_mfma_f32_16x16x32_bf16 v[80:83], v[196:199], v[164:167], v[80:83]
	v_mfma_f32_16x16x32_bf16 v[68:71], v[180:183], v[172:175], v[68:71]
	v_mfma_f32_16x16x32_bf16 v[64:67], v[196:199], v[172:175], v[64:67]
	s_setprio 0
	s_and_b32 s29, s19, 0xffff
	s_mov_b32 s30, s10
	s_mov_b32 s31, s11
	s_mov_b32 m0, s49
	s_barrier
	ds_read_b128 v[144:147], v228 offset:16384
	ds_read_b128 v[148:151], v228 offset:17408
	ds_read_b128 v[152:155], v228 offset:18432
	ds_read_b128 v[156:159], v228 offset:19456
	ds_read_b128 v[160:163], v228 offset:20480
	ds_read_b128 v[164:167], v228 offset:21504
	ds_read_b128 v[168:171], v228 offset:22528
	ds_read_b128 v[172:175], v228 offset:23552
	buffer_load_dwordx4 v222, s[28:31], 0 offen lds
	s_mov_b32 m0, s52
	s_nop 0
	buffer_load_dwordx4 v224, s[28:31], 0 offen lds
	s_waitcnt vmcnt(8)
	s_barrier
	s_waitcnt lgkmcnt(0)
	s_setprio 1
	s_waitcnt lgkmcnt(7)
	v_mfma_f32_16x16x32_bf16 v[60:63], v[128:131], v[144:147], v[60:63]
	v_mfma_f32_16x16x32_bf16 v[56:59], v[136:139], v[144:147], v[56:59]
	s_waitcnt lgkmcnt(5)
	v_mfma_f32_16x16x32_bf16 v[44:47], v[128:131], v[152:155], v[44:47]
	v_mfma_f32_16x16x32_bf16 v[40:43], v[136:139], v[152:155], v[40:43]
	s_waitcnt lgkmcnt(3)
	v_mfma_f32_16x16x32_bf16 v[28:31], v[128:131], v[160:163], v[28:31]
	v_mfma_f32_16x16x32_bf16 v[24:27], v[136:139], v[160:163], v[24:27]
	s_waitcnt lgkmcnt(1)
	v_mfma_f32_16x16x32_bf16 v[12:15], v[128:131], v[168:171], v[12:15]
	v_mfma_f32_16x16x32_bf16 v[8:11], v[136:139], v[168:171], v[8:11]
	v_mfma_f32_16x16x32_bf16 v[60:63], v[132:135], v[148:151], v[60:63]
	v_mfma_f32_16x16x32_bf16 v[56:59], v[140:143], v[148:151], v[56:59]
	v_mfma_f32_16x16x32_bf16 v[44:47], v[132:135], v[156:159], v[44:47]
	v_mfma_f32_16x16x32_bf16 v[40:43], v[140:143], v[156:159], v[40:43]
	v_mfma_f32_16x16x32_bf16 v[28:31], v[132:135], v[164:167], v[28:31]
	v_mfma_f32_16x16x32_bf16 v[24:27], v[140:143], v[164:167], v[24:27]
	s_waitcnt lgkmcnt(0)
	v_mfma_f32_16x16x32_bf16 v[12:15], v[132:135], v[172:175], v[12:15]
	v_mfma_f32_16x16x32_bf16 v[8:11], v[140:143], v[172:175], v[8:11]
	s_setprio 0
	s_barrier
; #define PG8_STAGE(bufoff, gbase, voff) do { const __amdgpu_buffer_rsrc_t _r = __builtin_amdgcn_make_buffer_rsrc((void*)(gbase), (short)0, 0x7fffffff, 0x00020000); _Pragma("unroll") for (int _i = 0; _i < 2; ++_i) \
;         __builtin_amdgcn_raw_ptr_buffer_load_lds(_r, (LAS unsigned*)(lds + (bufoff) + ldsw + _i * 8192), 16, (int)(voff)[_i], 0, 0, 0); } while (0)
; #define PG8_LDA(dst, b, h) do { _Pragma("unroll") for (int m = 0; m < 4; ++m) _Pragma("unroll") for (int k = 0; k < 2; ++k) dst[m][k] = *(const LAS bf16x8*)(lds + PG8_SA(b, h) + aoff + m * 2048 + k * 1024); } while (0)
; #define PG8_LDB(dst, b, h) do { _Pragma("unroll") for (int n = 0; n < 2; ++n) _Pragma("unroll") for (int k = 0; k < 2; ++k) dst[n][k] = *(const LAS bf16x8*)(lds + PG8_SB(b, h) + boff + n * 2048 + k * 1024); } while (0)
; #define PG8_MMA(ai, bj, At, Bt) do { __builtin_amdgcn_s_setprio(1); _Pragma("unroll") for (int k = 0; k < 2; ++k) _Pragma("unroll") for (int m = 0; m < 4; ++m) _Pragma("unroll") for (int n = 0; n < ((bj) == 1 ? NB1 : 2); ++n) \
;         acc[ai][bj][m][n] = __builtin_amdgcn_mfma_f32_16x16x32_bf16(Bt[n][k], At[m][k], acc[ai][bj][m][n], 0, 0, 0); __builtin_amdgcn_s_setprio(0); } while (0)
; #define PG8_WAIT_V(n) asm volatile("s_waitcnt vmcnt(" #n ")" ::: "memory")
; #define PG8_WAIT_L(n) asm volatile("s_waitcnt lgkmcnt(" #n ")" ::: "memory")
; #define PG8_BAR __builtin_amdgcn_s_barrier()
; #define PG8_SCHED __builtin_amdgcn_sched_barrier(0)
;     ...
;             PG8_WAIT_V(6); PG8_BAR; PG8_MMA(1, 1, At, B1); PG8_BAR;
;             PG8_LDB(B0, 1, 0); PG8_SCHED; PG8_LDA(At, 1, 0); PG8_STAGE(PG8_SA(0, 1), a2 + hstepA, voffA);
;             PG8_WAIT_L(8); PG8_BAR; PG8_WAIT_L(0); PG8_MMA(0, 0, At, B0); PG8_BAR; PG8_SCHED;
;             PG8_LDB(B1, 1, 1); PG8_STAGE(PG8_SB(1, 0), b3, voffB);
;             PG8_BAR; PG8_WAIT_L(0); PG8_MMA(0, 1, At, B1); PG8_BAR;
	ds_read_b128 v[128:131], v230
	ds_read_b128 v[132:135], v230 offset:1024
	ds_read_b128 v[136:139], v230 offset:2048
	ds_read_b128 v[140:143], v230 offset:3072
	s_add_u32 s8, s24, s38
	s_addc_u32 s23, s18, s39
	s_and_b32 s9, s23, 0xffff
	s_mov_b32 m0, s53
	s_nop 0
	buffer_load_dwordx4 v223, s[8:11], 0 offen lds
	s_mov_b32 m0, s54
	s_nop 0
	buffer_load_dwordx4 v225, s[8:11], 0 offen lds
	s_waitcnt vmcnt(6)
	s_barrier
	s_setprio 1
	v_mfma_f32_16x16x32_bf16 v[52:55], v[176:179], v[144:147], v[52:55]
	v_mfma_f32_16x16x32_bf16 v[48:51], v[192:195], v[144:147], v[48:51]
	v_mfma_f32_16x16x32_bf16 v[36:39], v[176:179], v[152:155], v[36:39]
	v_mfma_f32_16x16x32_bf16 v[32:35], v[192:195], v[152:155], v[32:35]
	v_mfma_f32_16x16x32_bf16 v[20:23], v[176:179], v[160:163], v[20:23]
	v_mfma_f32_16x16x32_bf16 v[16:19], v[192:195], v[160:163], v[16:19]
	v_mfma_f32_16x16x32_bf16 v[4:7], v[176:179], v[168:171], v[4:7]
	v_mfma_f32_16x16x32_bf16 v[0:3], v[192:195], v[168:171], v[0:3]
	v_mfma_f32_16x16x32_bf16 v[52:55], v[180:183], v[148:151], v[52:55]
	v_mfma_f32_16x16x32_bf16 v[48:51], v[196:199], v[148:151], v[48:51]
	v_mfma_f32_16x16x32_bf16 v[36:39], v[180:183], v[156:159], v[36:39]
	v_mfma_f32_16x16x32_bf16 v[32:35], v[196:199], v[156:159], v[32:35]
	v_mfma_f32_16x16x32_bf16 v[20:23], v[180:183], v[164:167], v[20:23]
	v_mfma_f32_16x16x32_bf16 v[16:19], v[196:199], v[164:167], v[16:19]
	v_mfma_f32_16x16x32_bf16 v[4:7], v[180:183], v[172:175], v[4:7]
	v_mfma_f32_16x16x32_bf16 v[0:3], v[196:199], v[172:175], v[0:3]
	s_setprio 0
	s_barrier
	s_add_u32 s28, s28, s36
	s_addc_u32 s9, s19, s37
	s_and_b32 s29, s9, 0xffff
	s_mov_b32 m0, s55
	ds_read_b128 v[144:147], v228 offset:32768
	ds_read_b128 v[148:151], v228 offset:33792
	ds_read_b128 v[152:155], v228 offset:34816
	ds_read_b128 v[156:159], v228 offset:35840
	ds_read_b128 v[160:163], v228 offset:36864
	ds_read_b128 v[164:167], v228 offset:37888
	ds_read_b128 v[168:171], v228 offset:38912
	ds_read_b128 v[172:175], v228 offset:39936
	buffer_load_dwordx4 v222, s[28:31], 0 offen lds
	s_mov_b32 m0, s56
	s_nop 0
	buffer_load_dwordx4 v224, s[28:31], 0 offen lds
	s_waitcnt lgkmcnt(8)
	s_barrier
	s_waitcnt lgkmcnt(0)
	s_setprio 1
	s_waitcnt lgkmcnt(7)
	v_mfma_f32_16x16x32_bf16 v[120:123], v[128:131], v[144:147], v[120:123]
	v_mfma_f32_16x16x32_bf16 v[124:127], v[136:139], v[144:147], v[124:127]
	s_waitcnt lgkmcnt(5)
	v_mfma_f32_16x16x32_bf16 v[108:111], v[128:131], v[152:155], v[108:111]
	v_mfma_f32_16x16x32_bf16 v[104:107], v[136:139], v[152:155], v[104:107]
	s_waitcnt lgkmcnt(3)
	v_mfma_f32_16x16x32_bf16 v[92:95], v[128:131], v[160:163], v[92:95]
	v_mfma_f32_16x16x32_bf16 v[88:91], v[136:139], v[160:163], v[88:91]
	s_waitcnt lgkmcnt(1)
	v_mfma_f32_16x16x32_bf16 v[76:79], v[128:131], v[168:171], v[76:79]
	v_mfma_f32_16x16x32_bf16 v[72:75], v[136:139], v[168:171], v[72:75]
	v_mfma_f32_16x16x32_bf16 v[120:123], v[132:135], v[148:151], v[120:123]
	v_mfma_f32_16x16x32_bf16 v[124:127], v[140:143], v[148:151], v[124:127]
	v_mfma_f32_16x16x32_bf16 v[108:111], v[132:135], v[156:159], v[108:111]
	v_mfma_f32_16x16x32_bf16 v[104:107], v[140:143], v[156:159], v[104:107]
	v_mfma_f32_16x16x32_bf16 v[92:95], v[132:135], v[164:167], v[92:95]
	v_mfma_f32_16x16x32_bf16 v[88:91], v[140:143], v[164:167], v[88:91]
	s_waitcnt lgkmcnt(0)
	v_mfma_f32_16x16x32_bf16 v[76:79], v[132:135], v[172:175], v[76:79]
	v_mfma_f32_16x16x32_bf16 v[72:75], v[140:143], v[172:175], v[72:75]
	s_setprio 0
	s_barrier
	s_add_u32 s24, s24, 0x80
	s_addc_u32 s9, s18, 0
	s_and_b32 s25, s9, 0xffff
	s_mov_b32 m0, s59
	ds_read_b128 v[176:179], v231
	ds_read_b128 v[180:183], v231 offset:1024
	ds_read_b128 v[192:195], v231 offset:2048
	ds_read_b128 v[196:199], v231 offset:3072
	buffer_load_dwordx4 v223, s[24:27], 0 offen lds
	s_mov_b32 m0, s64
	s_nop 0
	buffer_load_dwordx4 v225, s[24:27], 0 offen lds
	s_barrier
; #define PG8_STAGE(bufoff, gbase, voff) do { const __amdgpu_buffer_rsrc_t _r = __builtin_amdgcn_make_buffer_rsrc((void*)(gbase), (short)0, 0x7fffffff, 0x00020000); _Pragma("unroll") for (int _i = 0; _i < 2; ++_i) \
;         __builtin_amdgcn_raw_ptr_buffer_load_lds(_r, (LAS unsigned*)(lds + (bufoff) + ldsw + _i * 8192), 16, (int)(voff)[_i], 0, 0, 0); } while (0)
; #define PG8_LDA(dst, b, h) do { _Pragma("unroll") for (int m = 0; m < 4; ++m) _Pragma("unroll") for (int k = 0; k < 2; ++k) dst[m][k] = *(const LAS bf16x8*)(lds + PG8_SA(b, h) + aoff + m * 2048 + k * 1024); } while (0)
; #define PG8_MMA(ai, bj, At, Bt) do { __builtin_amdgcn_s_setprio(1); _Pragma("unroll") for (int k = 0; k < 2; ++k) _Pragma("unroll") for (int m = 0; m < 4; ++m) _Pragma("unroll") for (int n = 0; n < ((bj) == 1 ? NB1 : 2); ++n) \
;         acc[ai][bj][m][n] = __builtin_amdgcn_mfma_f32_16x16x32_bf16(Bt[n][k], At[m][k], acc[ai][bj][m][n], 0, 0, 0); __builtin_amdgcn_s_setprio(0); } while (0)
; #define PG8_WAIT_V(n) asm volatile("s_waitcnt vmcnt(" #n ")" ::: "memory")
; #define PG8_WAIT_L(n) asm volatile("s_waitcnt lgkmcnt(" #n ")" ::: "memory")
; #define PG8_BAR __builtin_amdgcn_s_barrier()
; #define PG8_SCHED __builtin_amdgcn_sched_barrier(0)
;     ...
;             PG8_BAR; PG8_WAIT_L(0); PG8_MMA(0, 1, At, B1); PG8_BAR;
;             PG8_LDA(At, 1, 1); PG8_STAGE(PG8_SA(1, 0), a3, voffA);
;             PG8_BAR; PG8_WAIT_L(0); PG8_MMA(1, 0, At, B0); PG8_BAR; PG8_SCHED;
;             PG8_STAGE(PG8_SB(1, 1), b3 + hstepB, voffB);
;             PG8_WAIT_V(6); PG8_BAR; PG8_MMA(1, 1, At, B1); PG8_BAR;
;         }
	s_waitcnt lgkmcnt(0)
	s_setprio 1
	s_waitcnt lgkmcnt(3)
	v_mfma_f32_16x16x32_bf16 v[116:119], v[176:179], v[144:147], v[116:119]
	s_waitcnt lgkmcnt(1)
	v_mfma_f32_16x16x32_bf16 v[112:115], v[192:195], v[144:147], v[112:115]
	v_mfma_f32_16x16x32_bf16 v[100:103], v[176:179], v[152:155], v[100:103]
	v_mfma_f32_16x16x32_bf16 v[96:99], v[192:195], v[152:155], v[96:99]
	v_mfma_f32_16x16x32_bf16 v[84:87], v[176:179], v[160:163], v[84:87]
	v_mfma_f32_16x16x32_bf16 v[80:83], v[192:195], v[160:163], v[80:83]
	v_mfma_f32_16x16x32_bf16 v[68:71], v[176:179], v[168:171], v[68:71]
	v_mfma_f32_16x16x32_bf16 v[64:67], v[192:195], v[168:171], v[64:67]
	v_mfma_f32_16x16x32_bf16 v[116:119], v[180:183], v[148:151], v[116:119]
	s_waitcnt lgkmcnt(0)
	v_mfma_f32_16x16x32_bf16 v[112:115], v[196:199], v[148:151], v[112:115]
	v_mfma_f32_16x16x32_bf16 v[100:103], v[180:183], v[156:159], v[100:103]
	v_mfma_f32_16x16x32_bf16 v[96:99], v[196:199], v[156:159], v[96:99]
	v_mfma_f32_16x16x32_bf16 v[84:87], v[180:183], v[164:167], v[84:87]
	v_mfma_f32_16x16x32_bf16 v[80:83], v[196:199], v[164:167], v[80:83]
	v_mfma_f32_16x16x32_bf16 v[68:71], v[180:183], v[172:175], v[68:71]
	v_mfma_f32_16x16x32_bf16 v[64:67], v[196:199], v[172:175], v[64:67]
	s_setprio 0
	s_and_b32 s17, s17, 0xffff
	s_mov_b32 s18, s10
	s_mov_b32 s19, s11
	s_mov_b32 m0, s65
	s_barrier
	ds_read_b128 v[144:147], v228 offset:49152
	ds_read_b128 v[148:151], v228 offset:50176
	ds_read_b128 v[152:155], v228 offset:51200
	ds_read_b128 v[156:159], v228 offset:52224
	ds_read_b128 v[160:163], v228 offset:53248
	ds_read_b128 v[164:167], v228 offset:54272
	ds_read_b128 v[168:171], v228 offset:55296
	ds_read_b128 v[172:175], v228 offset:56320
	buffer_load_dwordx4 v222, s[16:19], 0 offen lds
	s_mov_b32 m0, s66
	s_nop 0
	buffer_load_dwordx4 v224, s[16:19], 0 offen lds
	s_waitcnt vmcnt(8)
	s_barrier
	s_waitcnt lgkmcnt(0)
	s_setprio 1
	s_waitcnt lgkmcnt(7)
	v_mfma_f32_16x16x32_bf16 v[60:63], v[128:131], v[144:147], v[60:63]
	v_mfma_f32_16x16x32_bf16 v[56:59], v[136:139], v[144:147], v[56:59]
	s_waitcnt lgkmcnt(5)
	v_mfma_f32_16x16x32_bf16 v[44:47], v[128:131], v[152:155], v[44:47]
	v_mfma_f32_16x16x32_bf16 v[40:43], v[136:139], v[152:155], v[40:43]
	s_waitcnt lgkmcnt(3)
	v_mfma_f32_16x16x32_bf16 v[28:31], v[128:131], v[160:163], v[28:31]
	v_mfma_f32_16x16x32_bf16 v[24:27], v[136:139], v[160:163], v[24:27]
	s_waitcnt lgkmcnt(1)
	v_mfma_f32_16x16x32_bf16 v[12:15], v[128:131], v[168:171], v[12:15]
	v_mfma_f32_16x16x32_bf16 v[8:11], v[136:139], v[168:171], v[8:11]
	v_mfma_f32_16x16x32_bf16 v[60:63], v[132:135], v[148:151], v[60:63]
	v_mfma_f32_16x16x32_bf16 v[56:59], v[140:143], v[148:151], v[56:59]
	v_mfma_f32_16x16x32_bf16 v[44:47], v[132:135], v[156:159], v[44:47]
	v_mfma_f32_16x16x32_bf16 v[40:43], v[140:143], v[156:159], v[40:43]
	v_mfma_f32_16x16x32_bf16 v[28:31], v[132:135], v[164:167], v[28:31]
	v_mfma_f32_16x16x32_bf16 v[24:27], v[140:143], v[164:167], v[24:27]
	s_waitcnt lgkmcnt(0)
	v_mfma_f32_16x16x32_bf16 v[12:15], v[132:135], v[172:175], v[12:15]
	v_mfma_f32_16x16x32_bf16 v[8:11], v[140:143], v[172:175], v[8:11]
	s_setprio 0
	s_barrier
	ds_read_b128 v[128:131], v227
	ds_read_b128 v[132:135], v227 offset:1024
	ds_read_b128 v[136:139], v227 offset:2048
	ds_read_b128 v[140:143], v227 offset:3072
	s_add_u32 s8, s8, 0x80
	s_addc_u32 s9, s23, 0
	s_and_b32 s9, s9, 0xffff
	s_mov_b32 m0, s67
	s_nop 0
	buffer_load_dwordx4 v223, s[8:11], 0 offen lds
	s_mov_b32 m0, s70
	s_nop 0
	buffer_load_dwordx4 v225, s[8:11], 0 offen lds
	s_waitcnt vmcnt(6)
	s_barrier
	s_setprio 1
	v_mfma_f32_16x16x32_bf16 v[52:55], v[176:179], v[144:147], v[52:55]
	v_mfma_f32_16x16x32_bf16 v[48:51], v[192:195], v[144:147], v[48:51]
	v_mfma_f32_16x16x32_bf16 v[36:39], v[176:179], v[152:155], v[36:39]
	v_mfma_f32_16x16x32_bf16 v[32:35], v[192:195], v[152:155], v[32:35]
	v_mfma_f32_16x16x32_bf16 v[20:23], v[176:179], v[160:163], v[20:23]
	v_mfma_f32_16x16x32_bf16 v[16:19], v[192:195], v[160:163], v[16:19]
	v_mfma_f32_16x16x32_bf16 v[4:7], v[176:179], v[168:171], v[4:7]
	v_mfma_f32_16x16x32_bf16 v[0:3], v[192:195], v[168:171], v[0:3]
	v_mfma_f32_16x16x32_bf16 v[52:55], v[180:183], v[148:151], v[52:55]
	v_mfma_f32_16x16x32_bf16 v[48:51], v[196:199], v[148:151], v[48:51]
	v_mfma_f32_16x16x32_bf16 v[36:39], v[180:183], v[156:159], v[36:39]
	v_mfma_f32_16x16x32_bf16 v[32:35], v[196:199], v[156:159], v[32:35]
	v_mfma_f32_16x16x32_bf16 v[20:23], v[180:183], v[164:167], v[20:23]
	v_mfma_f32_16x16x32_bf16 v[16:19], v[196:199], v[164:167], v[16:19]
	v_mfma_f32_16x16x32_bf16 v[4:7], v[180:183], v[172:175], v[4:7]
	v_mfma_f32_16x16x32_bf16 v[0:3], v[196:199], v[172:175], v[0:3]
	s_setprio 0
	s_add_u32 s79, s79, 0x100
	s_addc_u32 s80, s80, 0
	s_add_u32 s81, s81, 0x100
	s_addc_u32 s82, s82, 0
	s_cmp_ge_i32 s22, s57
	s_mov_b32 s8, s22
	s_barrier
	s_cbranch_scc0 .Lkrot_1066
	s_waitcnt lgkmcnt(0)
